# static s_setprio 1 for waves 4-7 at kernel entry, per-cluster priority flips removed from the 13 GEMM mainloops (on top of vt_pair2)
# baseline (speedup 1.0000x reference)
; #define LAS __attribute__((address_space(3)))
; __device__ __forceinline__ unsigned xb_add(unsigned* p, unsigned v) { return __hip_atomic_fetch_add(p, v, __ATOMIC_RELAXED, __HIP_MEMORY_SCOPE_AGENT); }
; __device__ __forceinline__ unsigned xb_xcc_id() { return (unsigned)__builtin_amdgcn_s_getreg((3 << 11) | 20) & 0xFu; }
; __device__ __forceinline__ unsigned char* wsl_(KP p) { unsigned char* w = p->ws; asm volatile("" : "+s"(w)); return w; }
; __global__ void __launch_bounds__(512, 2) fwd_kernel(Params parg) {
;     KP p = (KP)__builtin_amdgcn_kernarg_segment_ptr();
;     extern __shared__ __attribute__((aligned(16))) unsigned char lds_raw[];
;     const int wid_s = __builtin_amdgcn_readfirstlane((int)threadIdx.x >> 6);
;     LAS unsigned char* lds3 = (LAS unsigned char*)lds_raw;
;     unsigned char* lds = lds_raw; float* ldsf = (float*)lds_raw;
;     unsigned char* ws = p->ws;
;     const int bid = blockIdx.x;
;     unsigned* ctl = (unsigned*)(wsl_(p) + WS_CTL);
;     bf16* xb = (bf16*)(wsl_(p) + WS_XB); float* part = (float*)(wsl_(p) + WS_PART); float* pq = (float*)(wsl_(p) + WS_PQ); float* pkv = (float*)(wsl_(p) + WS_PKV);
;     bf16* Y = (bf16*)(wsl_(p) + WS_Y);
;     float* xcur = p->out;
;     volatile unsigned* bst = (volatile unsigned*)(lds + QIDX_OFF + 16);
;     if (threadIdx.x == 0) { bst[0] = 0u; bst[1] = 0u; (void)xb_add(&ctl[1024 + XB_XCNT(xb_xcc_id())], 1u); }
;     __syncthreads();
_Z10fwd_kernel6Params:
	s_mov_b32 s50, s2
	v_writelane_b32 v254, s0, 0
	s_load_dwordx4 s[12:15], s[0:1], 0x158
	s_mov_b32 s43, 0
	v_writelane_b32 v254, s1, 1
	v_readfirstlane_b32 s0, v0
	v_cmp_eq_u32_e32 vcc, 0, v0
	s_nop 3
	s_cmp_lt_u32 s0, 0x100
	s_cbranch_scc1 .Lmy_prio_done
	s_setprio 1
.Lmy_prio_done:
	s_waitcnt lgkmcnt(0)
	s_mov_b64 s[16:17], s[14:15]
	s_mov_b64 s[10:11], s[14:15]
	s_mov_b64 s[8:9], s[14:15]
	s_mov_b64 s[6:7], s[14:15]
	s_mov_b64 s[4:5], s[14:15]
	v_writelane_b32 v254, s12, 2
	s_mov_b64 s[2:3], s[14:15]
	s_nop 0
	v_writelane_b32 v254, s13, 3
	v_writelane_b32 v254, s14, 4
	v_writelane_b32 v254, s15, 5
	s_and_saveexec_b64 s[12:13], vcc
	s_cbranch_execz .LBB0_2
	s_add_i32 s1, 0, 0x222f0
	s_cmp_lg_u32 s1, -1
	s_mov_b64 s[14:15], src_shared_base
	s_cselect_b32 s1, s1, 0
	s_cselect_b32 s14, s15, 0
	v_mov_b32_e32 v0, s1
	s_add_i32 s1, 0, 0x222f4
	s_cmp_lg_u32 s1, -1
	v_mov_b32_e32 v1, s14
	v_mov_b32_e32 v2, 0
	s_cselect_b32 s1, s1, 0
	s_cselect_b32 s14, s15, 0
	flat_store_dword v[0:1], v2 sc0 sc1
	s_waitcnt vmcnt(0)
	v_mov_b32_e32 v0, s1
	v_mov_b32_e32 v1, s14
	flat_store_dword v[0:1], v2 sc0 sc1
	s_waitcnt vmcnt(0)
	s_getreg_b32 s1, hwreg(HW_REG_XCC_ID, 0, 4)
	s_lshl_b32 s1, s1, 8
	s_and_b32 s1, s1, 0xf00
	s_add_u32 s1, s16, s1
	s_addc_u32 s14, s17, 0
	v_mov_b32_e32 v0, s1
	v_add_co_u32_e32 v0, vcc, 0x1000, v0
	v_mov_b32_e32 v1, s14
	s_nop 0
	v_addc_co_u32_e32 v1, vcc, 0, v1, vcc
	v_mov_b32_e32 v2, 1
	flat_atomic_add v[0:1], v2 offset:1024

; #define PG8_STAGE(bufoff, gbase, voff) do { _Pragma("unroll") for (int _i = 0; _i < 2; ++_i) \
;         __builtin_amdgcn_global_load_lds((const unsigned*)((const char*)(gbase) + (voff)[_i]), (PG8_LAS unsigned*)(lds + (bufoff) + ldsw + _i * 8192), 16, 0, 0); } while (0)
; #define PG8_LDA(dst, b, h) do { _Pragma("unroll") for (int m = 0; m < 4; ++m) _Pragma("unroll") for (int k = 0; k < 2; ++k) dst[m][k] = *(const PG8_LAS bf16x8*)(lds + PG8_SA(b, h) + aoff + m * 2048 + k * 1024); } while (0)
; #define PG8_LDB(dst, b, h) do { _Pragma("unroll") for (int n = 0; n < 2; ++n) _Pragma("unroll") for (int k = 0; k < 2; ++k) dst[n][k] = *(const PG8_LAS bf16x8*)(lds + PG8_SB(b, h) + boff + n * 2048 + k * 1024); } while (0)
; #define PG8_MMA(ai, bj, At, Bt) do { __builtin_amdgcn_s_setprio(1); _Pragma("unroll") for (int m = 0; m < 4; ++m) _Pragma("unroll") for (int n = 0; n < 2; ++n) _Pragma("unroll") for (int k = 0; k < 2; ++k) \
;         acc[ai][bj][m][n] = __builtin_amdgcn_mfma_f32_16x16x32_bf16(Bt[n][k], At[m][k], acc[ai][bj][m][n], 0, 0, 0); __builtin_amdgcn_s_setprio(0); } while (0)
; #define PG8_WAIT_V(n) asm volatile("s_waitcnt vmcnt(" #n ")" ::: "memory")
; #define PG8_WAIT_L(n) asm volatile("s_waitcnt lgkmcnt(" #n ")" ::: "memory")
; #define PG8_BAR __builtin_amdgcn_s_barrier()
; #define PG8_SCHED __builtin_amdgcn_sched_barrier(0)
; template <class Epi, class Sched>
; __device__ __forceinline__ void gemm_phase(int wid_s, PG8_LAS unsigned char* lds, const Gemm g, const Sched& S, const Epi& E) {
;     ...
;         for (int t = 0; t < nt; t += 2) {
;             const bool last = (t == nt - 2);
;             const char* a1 = cA + (size_t)(t + 1) * kstep;
;             const char* a2 = last ? nA : cA + (size_t)(t + 2) * kstep; const char* b2 = last ? nB : cB + (size_t)(t + 2) * kstep;
;             const char* a3 = a2 + kstep; const char* b3 = b2 + kstep;
;             PG8_LDB(B0, 0, 0); PG8_LDB(B1, 0, 1); PG8_SCHED; PG8_LDA(At, 0, 0); PG8_STAGE(PG8_SA(1, 1), a1 + hstepA, voffA);
;             PG8_WAIT_V(8); PG8_WAIT_L(0); PG8_BAR; PG8_MMA(0, 0, At, B0); PG8_MMA(0, 1, At, B1); PG8_BAR; PG8_SCHED;
;             PG8_LDA(At, 0, 1); PG8_STAGE(PG8_SB(0, 0), b2, voffB); PG8_STAGE(PG8_SB(0, 1), b2 + hstepB, voffB); PG8_STAGE(PG8_SA(0, 0), a2, voffA);
;             PG8_WAIT_V(8); PG8_WAIT_L(0); PG8_BAR; PG8_MMA(1, 0, At, B0); PG8_MMA(1, 1, At, B1); PG8_BAR; PG8_SCHED;
.LBB0_491:
	s_add_i32 s34, s8, 2
	s_add_u32 s35, s6, 0x80
	s_addc_u32 s9, s7, 0
	s_add_i32 s50, 0, 0x10000
	s_cmp_eq_u32 s92, s8
	s_cselect_b32 s9, s29, s9
	s_cselect_b32 s8, s28, s35
	v_add_u32_e32 v142, s50, v158
	s_cselect_b32 s49, s31, s47
	s_cselect_b32 s48, s30, s33
	s_add_i32 s35, 0, 0x14000
	ds_read_b128 v[138:141], v142
	ds_read_b128 v[154:157], v142 offset:1024
	ds_read_b128 v[164:167], v142 offset:2048
	ds_read_b128 v[186:189], v142 offset:3072
	v_add_u32_e32 v142, s35, v158
	ds_read_b128 v[190:193], v142
	ds_read_b128 v[194:197], v142 offset:1024
	ds_read_b128 v[198:201], v142 offset:2048
	ds_read_b128 v[202:205], v142 offset:3072
	v_lshl_add_u64 v[238:239], s[6:7], 0, v[136:137]
	s_add_i32 m0, s18, 0xc000
	ds_read_b128 v[206:209], v162
	ds_read_b128 v[210:213], v162 offset:1024
	ds_read_b128 v[214:217], v162 offset:2048
	ds_read_b128 v[218:221], v162 offset:3072
	ds_read_b128 v[222:225], v162 offset:4096
	ds_read_b128 v[226:229], v162 offset:5120
	ds_read_b128 v[230:233], v162 offset:6144
	ds_read_b128 v[234:237], v162 offset:7168
	global_load_lds_dwordx4 v[238:239], off
	v_lshl_add_u64 v[238:239], s[6:7], 0, v[134:135]
	s_add_i32 m0, s18, 0xe000
	s_nop 0
	global_load_lds_dwordx4 v[238:239], off
	s_waitcnt vmcnt(8)
	s_waitcnt lgkmcnt(0)
	s_barrier
	s_waitcnt lgkmcnt(0)
	v_mfma_f32_16x16x32_bf16 v[120:123], v[138:141], v[206:209], v[120:123]
	v_mfma_f32_16x16x32_bf16 v[124:127], v[164:167], v[206:209], v[124:127]
	v_mfma_f32_16x16x32_bf16 v[108:111], v[138:141], v[214:217], v[108:111]
	v_mfma_f32_16x16x32_bf16 v[104:107], v[164:167], v[214:217], v[104:107]
	v_mfma_f32_16x16x32_bf16 v[92:95], v[138:141], v[222:225], v[92:95]
	v_mfma_f32_16x16x32_bf16 v[88:91], v[164:167], v[222:225], v[88:91]
	v_mfma_f32_16x16x32_bf16 v[76:79], v[138:141], v[230:233], v[76:79]
	v_mfma_f32_16x16x32_bf16 v[72:75], v[164:167], v[230:233], v[72:75]
	v_mfma_f32_16x16x32_bf16 v[120:123], v[154:157], v[210:213], v[120:123]
	v_mfma_f32_16x16x32_bf16 v[124:127], v[186:189], v[210:213], v[124:127]
	v_mfma_f32_16x16x32_bf16 v[108:111], v[154:157], v[218:221], v[108:111]
	v_mfma_f32_16x16x32_bf16 v[104:107], v[186:189], v[218:221], v[104:107]
	v_mfma_f32_16x16x32_bf16 v[92:95], v[154:157], v[226:229], v[92:95]
	v_mfma_f32_16x16x32_bf16 v[88:91], v[186:189], v[226:229], v[88:91]
	v_mfma_f32_16x16x32_bf16 v[76:79], v[154:157], v[234:237], v[76:79]
	v_mfma_f32_16x16x32_bf16 v[72:75], v[186:189], v[234:237], v[72:75]
	v_mfma_f32_16x16x32_bf16 v[116:119], v[190:193], v[206:209], v[116:119]
	v_mfma_f32_16x16x32_bf16 v[112:115], v[198:201], v[206:209], v[112:115]
	v_mfma_f32_16x16x32_bf16 v[100:103], v[190:193], v[214:217], v[100:103]
	v_mfma_f32_16x16x32_bf16 v[96:99], v[198:201], v[214:217], v[96:99]
	v_mfma_f32_16x16x32_bf16 v[84:87], v[190:193], v[222:225], v[84:87]
	v_mfma_f32_16x16x32_bf16 v[80:83], v[198:201], v[222:225], v[80:83]
	v_mfma_f32_16x16x32_bf16 v[68:71], v[190:193], v[230:233], v[68:71]
	v_mfma_f32_16x16x32_bf16 v[64:67], v[198:201], v[230:233], v[64:67]
	v_mfma_f32_16x16x32_bf16 v[116:119], v[194:197], v[210:213], v[116:119]
	v_mfma_f32_16x16x32_bf16 v[112:115], v[202:205], v[210:213], v[112:115]
	v_mfma_f32_16x16x32_bf16 v[100:103], v[194:197], v[218:221], v[100:103]
	v_mfma_f32_16x16x32_bf16 v[96:99], v[202:205], v[218:221], v[96:99]
	v_mfma_f32_16x16x32_bf16 v[84:87], v[194:197], v[226:229], v[84:87]
	v_mfma_f32_16x16x32_bf16 v[80:83], v[202:205], v[226:229], v[80:83]
	v_mfma_f32_16x16x32_bf16 v[68:71], v[194:197], v[234:237], v[68:71]
	v_mfma_f32_16x16x32_bf16 v[64:67], v[202:205], v[234:237], v[64:67]
	s_barrier
	s_add_i32 s50, s50, s53
	v_lshl_add_u64 v[238:239], s[48:49], 0, v[144:145]
	s_mov_b32 m0, s50
	ds_read_b128 v[206:209], v162 offset:16384
	ds_read_b128 v[210:213], v162 offset:17408
	ds_read_b128 v[214:217], v162 offset:18432
	ds_read_b128 v[218:221], v162 offset:19456
	ds_read_b128 v[222:225], v162 offset:20480
	ds_read_b128 v[226:229], v162 offset:21504
	ds_read_b128 v[230:233], v162 offset:22528
	ds_read_b128 v[234:237], v162 offset:23552
	global_load_lds_dwordx4 v[238:239], off
	s_add_i32 m0, s50, 0x2000
	v_lshl_add_u64 v[240:241], s[48:49], 0, v[132:133]
	s_add_u32 s48, s48, s12
	s_addc_u32 s49, s49, s13
	s_add_i32 s35, s35, s53
	global_load_lds_dwordx4 v[240:241], off
	v_lshl_add_u64 v[242:243], s[48:49], 0, v[144:145]
	s_mov_b32 m0, s35
	v_lshl_add_u64 v[244:245], s[48:49], 0, v[132:133]
	global_load_lds_dwordx4 v[242:243], off
	s_add_i32 m0, s35, 0x2000
	v_lshl_add_u64 v[246:247], s[8:9], 0, v[128:129]
	global_load_lds_dwordx4 v[244:245], off
	s_mov_b32 m0, s18
	v_lshl_add_u64 v[248:249], s[8:9], 0, v[130:131]
	global_load_lds_dwordx4 v[246:247], off
	s_mov_b32 m0, s19
	s_nop 0
	global_load_lds_dwordx4 v[248:249], off
	s_waitcnt vmcnt(8)
	s_waitcnt lgkmcnt(0)
	s_barrier
; #define PG8_STAGE(bufoff, gbase, voff) do { _Pragma("unroll") for (int _i = 0; _i < 2; ++_i) \
;         __builtin_amdgcn_global_load_lds((const unsigned*)((const char*)(gbase) + (voff)[_i]), (PG8_LAS unsigned*)(lds + (bufoff) + ldsw + _i * 8192), 16, 0, 0); } while (0)
; #define PG8_LDA(dst, b, h) do { _Pragma("unroll") for (int m = 0; m < 4; ++m) _Pragma("unroll") for (int k = 0; k < 2; ++k) dst[m][k] = *(const PG8_LAS bf16x8*)(lds + PG8_SA(b, h) + aoff + m * 2048 + k * 1024); } while (0)
; #define PG8_LDB(dst, b, h) do { _Pragma("unroll") for (int n = 0; n < 2; ++n) _Pragma("unroll") for (int k = 0; k < 2; ++k) dst[n][k] = *(const PG8_LAS bf16x8*)(lds + PG8_SB(b, h) + boff + n * 2048 + k * 1024); } while (0)
; #define PG8_MMA(ai, bj, At, Bt) do { __builtin_amdgcn_s_setprio(1); _Pragma("unroll") for (int m = 0; m < 4; ++m) _Pragma("unroll") for (int n = 0; n < 2; ++n) _Pragma("unroll") for (int k = 0; k < 2; ++k) \
;         acc[ai][bj][m][n] = __builtin_amdgcn_mfma_f32_16x16x32_bf16(Bt[n][k], At[m][k], acc[ai][bj][m][n], 0, 0, 0); __builtin_amdgcn_s_setprio(0); } while (0)
; #define PG8_WAIT_V(n) asm volatile("s_waitcnt vmcnt(" #n ")" ::: "memory")
; #define PG8_WAIT_L(n) asm volatile("s_waitcnt lgkmcnt(" #n ")" ::: "memory")
; #define PG8_BAR __builtin_amdgcn_s_barrier()
; #define PG8_SCHED __builtin_amdgcn_sched_barrier(0)
; template <class Epi, class Sched>
; __device__ __forceinline__ void gemm_phase(int wid_s, PG8_LAS unsigned char* lds, const Gemm g, const Sched& S, const Epi& E) {
;     ...
;             PG8_WAIT_V(8); PG8_WAIT_L(0); PG8_BAR; PG8_MMA(1, 0, At, B0); PG8_MMA(1, 1, At, B1); PG8_BAR; PG8_SCHED;
;             PG8_LDB(B0, 1, 0); PG8_LDB(B1, 1, 1); PG8_SCHED; PG8_LDA(At, 1, 0); PG8_STAGE(PG8_SA(0, 1), a2 + hstepA, voffA);
;             PG8_WAIT_V(8); PG8_WAIT_L(0); PG8_BAR; PG8_MMA(0, 0, At, B0); PG8_MMA(0, 1, At, B1); PG8_BAR; PG8_SCHED;
	s_waitcnt lgkmcnt(0)
	v_mfma_f32_16x16x32_bf16 v[60:63], v[138:141], v[206:209], v[60:63]
	v_mfma_f32_16x16x32_bf16 v[56:59], v[164:167], v[206:209], v[56:59]
	v_mfma_f32_16x16x32_bf16 v[44:47], v[138:141], v[214:217], v[44:47]
	v_mfma_f32_16x16x32_bf16 v[40:43], v[164:167], v[214:217], v[40:43]
	v_mfma_f32_16x16x32_bf16 v[28:31], v[138:141], v[222:225], v[28:31]
	v_mfma_f32_16x16x32_bf16 v[24:27], v[164:167], v[222:225], v[24:27]
	v_mfma_f32_16x16x32_bf16 v[12:15], v[138:141], v[230:233], v[12:15]
	v_mfma_f32_16x16x32_bf16 v[8:11], v[164:167], v[230:233], v[8:11]
	v_mfma_f32_16x16x32_bf16 v[60:63], v[154:157], v[210:213], v[60:63]
	v_mfma_f32_16x16x32_bf16 v[56:59], v[186:189], v[210:213], v[56:59]
	v_mfma_f32_16x16x32_bf16 v[44:47], v[154:157], v[218:221], v[44:47]
	v_mfma_f32_16x16x32_bf16 v[40:43], v[186:189], v[218:221], v[40:43]
	v_mfma_f32_16x16x32_bf16 v[28:31], v[154:157], v[226:229], v[28:31]
	v_mfma_f32_16x16x32_bf16 v[24:27], v[186:189], v[226:229], v[24:27]
	v_mfma_f32_16x16x32_bf16 v[12:15], v[154:157], v[234:237], v[12:15]
	v_mfma_f32_16x16x32_bf16 v[8:11], v[186:189], v[234:237], v[8:11]
	v_mfma_f32_16x16x32_bf16 v[52:55], v[190:193], v[206:209], v[52:55]
	v_mfma_f32_16x16x32_bf16 v[48:51], v[198:201], v[206:209], v[48:51]
	v_mfma_f32_16x16x32_bf16 v[36:39], v[190:193], v[214:217], v[36:39]
	v_mfma_f32_16x16x32_bf16 v[32:35], v[198:201], v[214:217], v[32:35]
	v_mfma_f32_16x16x32_bf16 v[20:23], v[190:193], v[222:225], v[20:23]
	v_mfma_f32_16x16x32_bf16 v[16:19], v[198:201], v[222:225], v[16:19]
	v_mfma_f32_16x16x32_bf16 v[4:7], v[190:193], v[230:233], v[4:7]
	v_mfma_f32_16x16x32_bf16 v[0:3], v[198:201], v[230:233], v[0:3]
	v_mfma_f32_16x16x32_bf16 v[52:55], v[194:197], v[210:213], v[52:55]
	v_mfma_f32_16x16x32_bf16 v[48:51], v[202:205], v[210:213], v[48:51]
	v_mfma_f32_16x16x32_bf16 v[36:39], v[194:197], v[218:221], v[36:39]
	v_mfma_f32_16x16x32_bf16 v[32:35], v[202:205], v[218:221], v[32:35]
	v_mfma_f32_16x16x32_bf16 v[20:23], v[194:197], v[226:229], v[20:23]
	v_mfma_f32_16x16x32_bf16 v[16:19], v[202:205], v[226:229], v[16:19]
	v_mfma_f32_16x16x32_bf16 v[4:7], v[194:197], v[234:237], v[4:7]
	v_mfma_f32_16x16x32_bf16 v[0:3], v[202:205], v[234:237], v[0:3]
	s_barrier
	s_add_i32 s35, 0, 0x18000
	v_add_u32_e32 v142, s35, v158
	s_add_i32 s48, 0, 0x1c000
	ds_read_b128 v[138:141], v142
	ds_read_b128 v[154:157], v142 offset:1024
	ds_read_b128 v[164:167], v142 offset:2048
	ds_read_b128 v[186:189], v142 offset:3072
	v_add_u32_e32 v142, s48, v158
	ds_read_b128 v[190:193], v142
	ds_read_b128 v[194:197], v142 offset:1024
	ds_read_b128 v[198:201], v142 offset:2048
	ds_read_b128 v[202:205], v142 offset:3072
	s_add_u32 s8, s8, s10
	s_addc_u32 s9, s9, s11
	s_mov_b32 m0, s94
	v_lshl_add_u64 v[250:251], s[8:9], 0, v[128:129]
	ds_read_b128 v[206:209], v162 offset:32768
	ds_read_b128 v[210:213], v162 offset:33792
	ds_read_b128 v[214:217], v162 offset:34816
	ds_read_b128 v[218:221], v162 offset:35840
	ds_read_b128 v[222:225], v162 offset:36864
	ds_read_b128 v[226:229], v162 offset:37888
	ds_read_b128 v[230:233], v162 offset:38912
	ds_read_b128 v[234:237], v162 offset:39936
	global_load_lds_dwordx4 v[250:251], off
	v_lshl_add_u64 v[250:251], s[8:9], 0, v[130:131]
	s_mov_b32 m0, s95
	s_nop 0
	global_load_lds_dwordx4 v[250:251], off
	s_waitcnt vmcnt(8)
	s_waitcnt lgkmcnt(0)
	s_barrier
	s_waitcnt lgkmcnt(0)
	v_mfma_f32_16x16x32_bf16 v[120:123], v[138:141], v[206:209], v[120:123]
	v_mfma_f32_16x16x32_bf16 v[124:127], v[164:167], v[206:209], v[124:127]
	v_mfma_f32_16x16x32_bf16 v[108:111], v[138:141], v[214:217], v[108:111]
	v_mfma_f32_16x16x32_bf16 v[104:107], v[164:167], v[214:217], v[104:107]
	v_mfma_f32_16x16x32_bf16 v[92:95], v[138:141], v[222:225], v[92:95]
	v_mfma_f32_16x16x32_bf16 v[88:91], v[164:167], v[222:225], v[88:91]
	v_mfma_f32_16x16x32_bf16 v[76:79], v[138:141], v[230:233], v[76:79]
	v_mfma_f32_16x16x32_bf16 v[72:75], v[164:167], v[230:233], v[72:75]
	v_mfma_f32_16x16x32_bf16 v[120:123], v[154:157], v[210:213], v[120:123]
	v_mfma_f32_16x16x32_bf16 v[124:127], v[186:189], v[210:213], v[124:127]
	v_mfma_f32_16x16x32_bf16 v[108:111], v[154:157], v[218:221], v[108:111]
	v_mfma_f32_16x16x32_bf16 v[104:107], v[186:189], v[218:221], v[104:107]
	v_mfma_f32_16x16x32_bf16 v[92:95], v[154:157], v[226:229], v[92:95]
	v_mfma_f32_16x16x32_bf16 v[88:91], v[186:189], v[226:229], v[88:91]
	v_mfma_f32_16x16x32_bf16 v[76:79], v[154:157], v[234:237], v[76:79]
	v_mfma_f32_16x16x32_bf16 v[72:75], v[186:189], v[234:237], v[72:75]
	v_mfma_f32_16x16x32_bf16 v[116:119], v[190:193], v[206:209], v[116:119]
	v_mfma_f32_16x16x32_bf16 v[112:115], v[198:201], v[206:209], v[112:115]
	v_mfma_f32_16x16x32_bf16 v[100:103], v[190:193], v[214:217], v[100:103]
	v_mfma_f32_16x16x32_bf16 v[96:99], v[198:201], v[214:217], v[96:99]
	v_mfma_f32_16x16x32_bf16 v[84:87], v[190:193], v[222:225], v[84:87]
	v_mfma_f32_16x16x32_bf16 v[80:83], v[198:201], v[222:225], v[80:83]
	v_mfma_f32_16x16x32_bf16 v[68:71], v[190:193], v[230:233], v[68:71]
	v_mfma_f32_16x16x32_bf16 v[64:67], v[198:201], v[230:233], v[64:67]
	v_mfma_f32_16x16x32_bf16 v[116:119], v[194:197], v[210:213], v[116:119]
	v_mfma_f32_16x16x32_bf16 v[112:115], v[202:205], v[210:213], v[112:115]
	v_mfma_f32_16x16x32_bf16 v[100:103], v[194:197], v[218:221], v[100:103]
	v_mfma_f32_16x16x32_bf16 v[96:99], v[202:205], v[218:221], v[96:99]
	v_mfma_f32_16x16x32_bf16 v[84:87], v[194:197], v[226:229], v[84:87]
	v_mfma_f32_16x16x32_bf16 v[80:83], v[202:205], v[226:229], v[80:83]
	v_mfma_f32_16x16x32_bf16 v[68:71], v[194:197], v[234:237], v[68:71]
	v_mfma_f32_16x16x32_bf16 v[64:67], v[202:205], v[234:237], v[64:67]
	s_barrier
; #define PG8_STAGE(bufoff, gbase, voff) do { _Pragma("unroll") for (int _i = 0; _i < 2; ++_i) \
;         __builtin_amdgcn_global_load_lds((const unsigned*)((const char*)(gbase) + (voff)[_i]), (PG8_LAS unsigned*)(lds + (bufoff) + ldsw + _i * 8192), 16, 0, 0); } while (0)
; #define PG8_LDA(dst, b, h) do { _Pragma("unroll") for (int m = 0; m < 4; ++m) _Pragma("unroll") for (int k = 0; k < 2; ++k) dst[m][k] = *(const PG8_LAS bf16x8*)(lds + PG8_SA(b, h) + aoff + m * 2048 + k * 1024); } while (0)
; #define PG8_MMA(ai, bj, At, Bt) do { __builtin_amdgcn_s_setprio(1); _Pragma("unroll") for (int m = 0; m < 4; ++m) _Pragma("unroll") for (int n = 0; n < 2; ++n) _Pragma("unroll") for (int k = 0; k < 2; ++k) \
;         acc[ai][bj][m][n] = __builtin_amdgcn_mfma_f32_16x16x32_bf16(Bt[n][k], At[m][k], acc[ai][bj][m][n], 0, 0, 0); __builtin_amdgcn_s_setprio(0); } while (0)
; #define PG8_WAIT_V(n) asm volatile("s_waitcnt vmcnt(" #n ")" ::: "memory")
; #define PG8_WAIT_L(n) asm volatile("s_waitcnt lgkmcnt(" #n ")" ::: "memory")
; #define PG8_BAR __builtin_amdgcn_s_barrier()
; #define PG8_SCHED __builtin_amdgcn_sched_barrier(0)
; template <class Epi, class Sched>
; __device__ __forceinline__ void gemm_phase(int wid_s, PG8_LAS unsigned char* lds, const Gemm g, const Sched& S, const Epi& E) {
;     ...
;         for (int t = 0; t < nt; t += 2) {
;     ...
;             PG8_LDA(At, 1, 1); PG8_STAGE(PG8_SB(1, 0), b3, voffB); PG8_STAGE(PG8_SB(1, 1), b3 + hstepB, voffB); PG8_STAGE(PG8_SA(1, 0), a3, voffA);
;             PG8_WAIT_V(8); PG8_WAIT_L(0); PG8_BAR; PG8_MMA(1, 0, At, B0); PG8_MMA(1, 1, At, B1); PG8_BAR; PG8_SCHED;
	s_add_i32 s8, s35, s53
	v_lshl_add_u64 v[238:239], v[238:239], 0, s[96:97]
	s_mov_b32 m0, s8
	ds_read_b128 v[206:209], v162 offset:49152
	ds_read_b128 v[210:213], v162 offset:50176
	ds_read_b128 v[214:217], v162 offset:51200
	ds_read_b128 v[218:221], v162 offset:52224
	ds_read_b128 v[222:225], v162 offset:53248
	ds_read_b128 v[226:229], v162 offset:54272
	ds_read_b128 v[230:233], v162 offset:55296
	ds_read_b128 v[234:237], v162 offset:56320
	global_load_lds_dwordx4 v[238:239], off
	v_lshl_add_u64 v[238:239], v[240:241], 0, s[96:97]
	s_add_i32 m0, s8, 0x2000
	s_add_i32 s8, s48, s53
	global_load_lds_dwordx4 v[238:239], off
	v_lshl_add_u64 v[238:239], v[242:243], 0, s[96:97]
	s_mov_b32 m0, s8
	s_nop 0
	global_load_lds_dwordx4 v[238:239], off
	v_lshl_add_u64 v[238:239], v[244:245], 0, s[96:97]
	s_add_i32 m0, s8, 0x2000
	s_nop 0
	global_load_lds_dwordx4 v[238:239], off
	v_lshl_add_u64 v[238:239], v[246:247], 0, s[96:97]
	s_mov_b32 m0, s40
	s_nop 0
	global_load_lds_dwordx4 v[238:239], off
	v_lshl_add_u64 v[238:239], v[248:249], 0, s[96:97]
	s_mov_b32 m0, s41
	s_nop 0
	global_load_lds_dwordx4 v[238:239], off
	s_waitcnt vmcnt(8)
	s_waitcnt lgkmcnt(0)
	s_barrier
	s_waitcnt lgkmcnt(0)
	v_mfma_f32_16x16x32_bf16 v[60:63], v[138:141], v[206:209], v[60:63]
	v_mfma_f32_16x16x32_bf16 v[56:59], v[164:167], v[206:209], v[56:59]
	v_mfma_f32_16x16x32_bf16 v[44:47], v[138:141], v[214:217], v[44:47]
	v_mfma_f32_16x16x32_bf16 v[40:43], v[164:167], v[214:217], v[40:43]
	v_mfma_f32_16x16x32_bf16 v[28:31], v[138:141], v[222:225], v[28:31]
	v_mfma_f32_16x16x32_bf16 v[24:27], v[164:167], v[222:225], v[24:27]
	v_mfma_f32_16x16x32_bf16 v[12:15], v[138:141], v[230:233], v[12:15]
	v_mfma_f32_16x16x32_bf16 v[8:11], v[164:167], v[230:233], v[8:11]
	v_mfma_f32_16x16x32_bf16 v[60:63], v[154:157], v[210:213], v[60:63]
	v_mfma_f32_16x16x32_bf16 v[56:59], v[186:189], v[210:213], v[56:59]
	v_mfma_f32_16x16x32_bf16 v[44:47], v[154:157], v[218:221], v[44:47]
	v_mfma_f32_16x16x32_bf16 v[40:43], v[186:189], v[218:221], v[40:43]
	v_mfma_f32_16x16x32_bf16 v[28:31], v[154:157], v[226:229], v[28:31]
	v_mfma_f32_16x16x32_bf16 v[24:27], v[186:189], v[226:229], v[24:27]
	v_mfma_f32_16x16x32_bf16 v[12:15], v[154:157], v[234:237], v[12:15]
	v_mfma_f32_16x16x32_bf16 v[8:11], v[186:189], v[234:237], v[8:11]
	v_mfma_f32_16x16x32_bf16 v[52:55], v[190:193], v[206:209], v[52:55]
	v_mfma_f32_16x16x32_bf16 v[48:51], v[198:201], v[206:209], v[48:51]
	v_mfma_f32_16x16x32_bf16 v[36:39], v[190:193], v[214:217], v[36:39]
	v_mfma_f32_16x16x32_bf16 v[32:35], v[198:201], v[214:217], v[32:35]
	v_mfma_f32_16x16x32_bf16 v[20:23], v[190:193], v[222:225], v[20:23]
	v_mfma_f32_16x16x32_bf16 v[16:19], v[198:201], v[222:225], v[16:19]
	v_mfma_f32_16x16x32_bf16 v[4:7], v[190:193], v[230:233], v[4:7]
	v_mfma_f32_16x16x32_bf16 v[0:3], v[198:201], v[230:233], v[0:3]
	v_mfma_f32_16x16x32_bf16 v[52:55], v[194:197], v[210:213], v[52:55]
	v_mfma_f32_16x16x32_bf16 v[48:51], v[202:205], v[210:213], v[48:51]
	v_mfma_f32_16x16x32_bf16 v[36:39], v[194:197], v[218:221], v[36:39]
	v_mfma_f32_16x16x32_bf16 v[32:35], v[202:205], v[218:221], v[32:35]
	v_mfma_f32_16x16x32_bf16 v[20:23], v[194:197], v[226:229], v[20:23]
	v_mfma_f32_16x16x32_bf16 v[16:19], v[202:205], v[226:229], v[16:19]
	v_mfma_f32_16x16x32_bf16 v[4:7], v[194:197], v[234:237], v[4:7]
	v_mfma_f32_16x16x32_bf16 v[0:3], v[202:205], v[234:237], v[0:3]
	s_barrier
	s_add_u32 s33, s33, 0x100
	s_addc_u32 s47, s47, 0
	s_add_u32 s6, s6, 0x100
	s_addc_u32 s7, s7, 0
	s_cmp_ge_i32 s34, s37
	s_mov_b32 s8, s34
	s_cbranch_scc0 .LBB0_491
	s_movk_i32 s33, 0x300

; #define PG8_STAGE(bufoff, gbase, voff) do { _Pragma("unroll") for (int _i = 0; _i < 2; ++_i) \
;         __builtin_amdgcn_global_load_lds((const unsigned*)((const char*)(gbase) + (voff)[_i]), (PG8_LAS unsigned*)(lds + (bufoff) + ldsw + _i * 8192), 16, 0, 0); } while (0)
; #define PG8_LDA(dst, b, h) do { _Pragma("unroll") for (int m = 0; m < 4; ++m) _Pragma("unroll") for (int k = 0; k < 2; ++k) dst[m][k] = *(const PG8_LAS bf16x8*)(lds + PG8_SA(b, h) + aoff + m * 2048 + k * 1024); } while (0)
; #define PG8_LDB(dst, b, h) do { _Pragma("unroll") for (int n = 0; n < 2; ++n) _Pragma("unroll") for (int k = 0; k < 2; ++k) dst[n][k] = *(const PG8_LAS bf16x8*)(lds + PG8_SB(b, h) + boff + n * 2048 + k * 1024); } while (0)
; #define PG8_MMA(ai, bj, At, Bt) do { __builtin_amdgcn_s_setprio(1); _Pragma("unroll") for (int m = 0; m < 4; ++m) _Pragma("unroll") for (int n = 0; n < 2; ++n) _Pragma("unroll") for (int k = 0; k < 2; ++k) \
;         acc[ai][bj][m][n] = __builtin_amdgcn_mfma_f32_16x16x32_bf16(Bt[n][k], At[m][k], acc[ai][bj][m][n], 0, 0, 0); __builtin_amdgcn_s_setprio(0); } while (0)
; #define PG8_WAIT_V(n) asm volatile("s_waitcnt vmcnt(" #n ")" ::: "memory")
; #define PG8_WAIT_L(n) asm volatile("s_waitcnt lgkmcnt(" #n ")" ::: "memory")
; #define PG8_BAR __builtin_amdgcn_s_barrier()
; #define PG8_SCHED __builtin_amdgcn_sched_barrier(0)
; template <class Epi, class Sched>
; __device__ __forceinline__ void gemm_phase(int wid_s, PG8_LAS unsigned char* lds, const Gemm g, const Sched& S, const Epi& E) {
;     ...
;         for (int t = 0; t < nt; t += 2) {
;             const bool last = (t == nt - 2);
;             const char* a1 = cA + (size_t)(t + 1) * kstep;
;             const char* a2 = last ? nA : cA + (size_t)(t + 2) * kstep; const char* b2 = last ? nB : cB + (size_t)(t + 2) * kstep;
;             const char* a3 = a2 + kstep; const char* b3 = b2 + kstep;
;             PG8_LDB(B0, 0, 0); PG8_LDB(B1, 0, 1); PG8_SCHED; PG8_LDA(At, 0, 0); PG8_STAGE(PG8_SA(1, 1), a1 + hstepA, voffA);
;             PG8_WAIT_V(8); PG8_WAIT_L(0); PG8_BAR; PG8_MMA(0, 0, At, B0); PG8_MMA(0, 1, At, B1); PG8_BAR; PG8_SCHED;
;             PG8_LDA(At, 0, 1); PG8_STAGE(PG8_SB(0, 0), b2, voffB); PG8_STAGE(PG8_SB(0, 1), b2 + hstepB, voffB); PG8_STAGE(PG8_SA(0, 0), a2, voffA);
;             PG8_WAIT_V(8); PG8_WAIT_L(0); PG8_BAR; PG8_MMA(1, 0, At, B0); PG8_MMA(1, 1, At, B1); PG8_BAR; PG8_SCHED;
.LBB0_1061:
	s_add_i32 s55, s28, 2
	s_add_u32 s56, s26, 0x80
	s_addc_u32 s29, s27, 0
	s_add_i32 s92, 0, 0x10000
	s_cmp_eq_u32 s46, s28
	s_cselect_b32 s29, s5, s29
	s_cselect_b32 s28, s4, s56
	v_add_u32_e32 v138, s92, v141
	s_cselect_b32 s57, s25, s54
	s_cselect_b32 s56, s24, s33
	s_add_i32 s94, 0, 0x14000
	ds_read_b128 v[154:157], v138
	ds_read_b128 v[158:161], v138 offset:1024
	ds_read_b128 v[162:165], v138 offset:2048
	ds_read_b128 v[186:189], v138 offset:3072
	v_add_u32_e32 v138, s94, v141
	ds_read_b128 v[190:193], v138
	ds_read_b128 v[194:197], v138 offset:1024
	ds_read_b128 v[198:201], v138 offset:2048
	ds_read_b128 v[202:205], v138 offset:3072
	v_lshl_add_u64 v[138:139], s[26:27], 0, v[136:137]
	s_add_i32 m0, s37, 0xc000
	ds_read_b128 v[206:209], v143
	ds_read_b128 v[210:213], v143 offset:1024
	ds_read_b128 v[214:217], v143 offset:2048
	ds_read_b128 v[218:221], v143 offset:3072
	ds_read_b128 v[222:225], v143 offset:4096
	ds_read_b128 v[226:229], v143 offset:5120
	ds_read_b128 v[230:233], v143 offset:6144
	ds_read_b128 v[234:237], v143 offset:7168
	global_load_lds_dwordx4 v[138:139], off
	v_lshl_add_u64 v[138:139], s[26:27], 0, v[134:135]
	s_add_i32 m0, s37, 0xe000
	s_nop 0
	global_load_lds_dwordx4 v[138:139], off
	s_waitcnt vmcnt(8)
	s_waitcnt lgkmcnt(0)
	s_barrier
	s_waitcnt lgkmcnt(0)
	v_mfma_f32_16x16x32_bf16 v[120:123], v[154:157], v[206:209], v[120:123]
	v_mfma_f32_16x16x32_bf16 v[124:127], v[162:165], v[206:209], v[124:127]
	v_mfma_f32_16x16x32_bf16 v[108:111], v[154:157], v[214:217], v[108:111]
	v_mfma_f32_16x16x32_bf16 v[104:107], v[162:165], v[214:217], v[104:107]
	v_mfma_f32_16x16x32_bf16 v[92:95], v[154:157], v[222:225], v[92:95]
	v_mfma_f32_16x16x32_bf16 v[88:91], v[162:165], v[222:225], v[88:91]
	v_mfma_f32_16x16x32_bf16 v[76:79], v[154:157], v[230:233], v[76:79]
	v_mfma_f32_16x16x32_bf16 v[72:75], v[162:165], v[230:233], v[72:75]
	v_mfma_f32_16x16x32_bf16 v[120:123], v[158:161], v[210:213], v[120:123]
	v_mfma_f32_16x16x32_bf16 v[124:127], v[186:189], v[210:213], v[124:127]
	v_mfma_f32_16x16x32_bf16 v[108:111], v[158:161], v[218:221], v[108:111]
	v_mfma_f32_16x16x32_bf16 v[104:107], v[186:189], v[218:221], v[104:107]
	v_mfma_f32_16x16x32_bf16 v[92:95], v[158:161], v[226:229], v[92:95]
	v_mfma_f32_16x16x32_bf16 v[88:91], v[186:189], v[226:229], v[88:91]
	v_mfma_f32_16x16x32_bf16 v[76:79], v[158:161], v[234:237], v[76:79]
	v_mfma_f32_16x16x32_bf16 v[72:75], v[186:189], v[234:237], v[72:75]
	v_mfma_f32_16x16x32_bf16 v[116:119], v[190:193], v[206:209], v[116:119]
	v_mfma_f32_16x16x32_bf16 v[112:115], v[198:201], v[206:209], v[112:115]
	v_mfma_f32_16x16x32_bf16 v[100:103], v[190:193], v[214:217], v[100:103]
	v_mfma_f32_16x16x32_bf16 v[96:99], v[198:201], v[214:217], v[96:99]
	v_mfma_f32_16x16x32_bf16 v[84:87], v[190:193], v[222:225], v[84:87]
	v_mfma_f32_16x16x32_bf16 v[80:83], v[198:201], v[222:225], v[80:83]
	v_mfma_f32_16x16x32_bf16 v[68:71], v[190:193], v[230:233], v[68:71]
	v_mfma_f32_16x16x32_bf16 v[64:67], v[198:201], v[230:233], v[64:67]
	v_mfma_f32_16x16x32_bf16 v[116:119], v[194:197], v[210:213], v[116:119]
	v_mfma_f32_16x16x32_bf16 v[112:115], v[202:205], v[210:213], v[112:115]
	v_mfma_f32_16x16x32_bf16 v[100:103], v[194:197], v[218:221], v[100:103]
	v_mfma_f32_16x16x32_bf16 v[96:99], v[202:205], v[218:221], v[96:99]
	v_mfma_f32_16x16x32_bf16 v[84:87], v[194:197], v[226:229], v[84:87]
	v_mfma_f32_16x16x32_bf16 v[80:83], v[202:205], v[226:229], v[80:83]
	v_mfma_f32_16x16x32_bf16 v[68:71], v[194:197], v[234:237], v[68:71]
	v_mfma_f32_16x16x32_bf16 v[64:67], v[202:205], v[234:237], v[64:67]
	s_barrier
	s_add_i32 s92, s92, s35
	v_lshl_add_u64 v[138:139], s[56:57], 0, v[144:145]
	s_mov_b32 m0, s92
	ds_read_b128 v[206:209], v143 offset:16384
	ds_read_b128 v[210:213], v143 offset:17408
	ds_read_b128 v[214:217], v143 offset:18432
	ds_read_b128 v[218:221], v143 offset:19456
	ds_read_b128 v[222:225], v143 offset:20480
	ds_read_b128 v[226:229], v143 offset:21504
	ds_read_b128 v[230:233], v143 offset:22528
	ds_read_b128 v[234:237], v143 offset:23552
	global_load_lds_dwordx4 v[138:139], off
	s_add_i32 m0, s92, 0x2000
	v_lshl_add_u64 v[166:167], s[56:57], 0, v[128:129]
	s_add_u32 s56, s56, s8
	s_addc_u32 s57, s57, s9
	s_add_i32 s92, s94, s35
	global_load_lds_dwordx4 v[166:167], off
	v_lshl_add_u64 v[238:239], s[56:57], 0, v[144:145]
	s_mov_b32 m0, s92
	v_lshl_add_u64 v[240:241], s[56:57], 0, v[128:129]
	global_load_lds_dwordx4 v[238:239], off
	s_add_i32 m0, s92, 0x2000
	v_lshl_add_u64 v[242:243], s[28:29], 0, v[132:133]
	global_load_lds_dwordx4 v[240:241], off
	s_mov_b32 m0, s37
	v_lshl_add_u64 v[244:245], s[28:29], 0, v[130:131]
	global_load_lds_dwordx4 v[242:243], off
	s_mov_b32 m0, s39
	s_nop 0
	global_load_lds_dwordx4 v[244:245], off
	s_waitcnt vmcnt(8)
	s_waitcnt lgkmcnt(0)
	s_barrier
; #define PG8_STAGE(bufoff, gbase, voff) do { _Pragma("unroll") for (int _i = 0; _i < 2; ++_i) \
;         __builtin_amdgcn_global_load_lds((const unsigned*)((const char*)(gbase) + (voff)[_i]), (PG8_LAS unsigned*)(lds + (bufoff) + ldsw + _i * 8192), 16, 0, 0); } while (0)
; #define PG8_LDA(dst, b, h) do { _Pragma("unroll") for (int m = 0; m < 4; ++m) _Pragma("unroll") for (int k = 0; k < 2; ++k) dst[m][k] = *(const PG8_LAS bf16x8*)(lds + PG8_SA(b, h) + aoff + m * 2048 + k * 1024); } while (0)
; #define PG8_LDB(dst, b, h) do { _Pragma("unroll") for (int n = 0; n < 2; ++n) _Pragma("unroll") for (int k = 0; k < 2; ++k) dst[n][k] = *(const PG8_LAS bf16x8*)(lds + PG8_SB(b, h) + boff + n * 2048 + k * 1024); } while (0)
; #define PG8_MMA(ai, bj, At, Bt) do { __builtin_amdgcn_s_setprio(1); _Pragma("unroll") for (int m = 0; m < 4; ++m) _Pragma("unroll") for (int n = 0; n < 2; ++n) _Pragma("unroll") for (int k = 0; k < 2; ++k) \
;         acc[ai][bj][m][n] = __builtin_amdgcn_mfma_f32_16x16x32_bf16(Bt[n][k], At[m][k], acc[ai][bj][m][n], 0, 0, 0); __builtin_amdgcn_s_setprio(0); } while (0)
; #define PG8_WAIT_V(n) asm volatile("s_waitcnt vmcnt(" #n ")" ::: "memory")
; #define PG8_WAIT_L(n) asm volatile("s_waitcnt lgkmcnt(" #n ")" ::: "memory")
; #define PG8_BAR __builtin_amdgcn_s_barrier()
; #define PG8_SCHED __builtin_amdgcn_sched_barrier(0)
; template <class Epi, class Sched>
; __device__ __forceinline__ void gemm_phase(int wid_s, PG8_LAS unsigned char* lds, const Gemm g, const Sched& S, const Epi& E) {
;     ...
;             PG8_WAIT_V(8); PG8_WAIT_L(0); PG8_BAR; PG8_MMA(1, 0, At, B0); PG8_MMA(1, 1, At, B1); PG8_BAR; PG8_SCHED;
;             PG8_LDB(B0, 1, 0); PG8_LDB(B1, 1, 1); PG8_SCHED; PG8_LDA(At, 1, 0); PG8_STAGE(PG8_SA(0, 1), a2 + hstepA, voffA);
;             PG8_WAIT_V(8); PG8_WAIT_L(0); PG8_BAR; PG8_MMA(0, 0, At, B0); PG8_MMA(0, 1, At, B1); PG8_BAR; PG8_SCHED;
	s_waitcnt lgkmcnt(0)
	v_mfma_f32_16x16x32_bf16 v[60:63], v[154:157], v[206:209], v[60:63]
	v_mfma_f32_16x16x32_bf16 v[56:59], v[162:165], v[206:209], v[56:59]
	v_mfma_f32_16x16x32_bf16 v[44:47], v[154:157], v[214:217], v[44:47]
	v_mfma_f32_16x16x32_bf16 v[40:43], v[162:165], v[214:217], v[40:43]
	v_mfma_f32_16x16x32_bf16 v[28:31], v[154:157], v[222:225], v[28:31]
	v_mfma_f32_16x16x32_bf16 v[24:27], v[162:165], v[222:225], v[24:27]
	v_mfma_f32_16x16x32_bf16 v[12:15], v[154:157], v[230:233], v[12:15]
	v_mfma_f32_16x16x32_bf16 v[8:11], v[162:165], v[230:233], v[8:11]
	v_mfma_f32_16x16x32_bf16 v[60:63], v[158:161], v[210:213], v[60:63]
	v_mfma_f32_16x16x32_bf16 v[56:59], v[186:189], v[210:213], v[56:59]
	v_mfma_f32_16x16x32_bf16 v[44:47], v[158:161], v[218:221], v[44:47]
	v_mfma_f32_16x16x32_bf16 v[40:43], v[186:189], v[218:221], v[40:43]
	v_mfma_f32_16x16x32_bf16 v[28:31], v[158:161], v[226:229], v[28:31]
	v_mfma_f32_16x16x32_bf16 v[24:27], v[186:189], v[226:229], v[24:27]
	v_mfma_f32_16x16x32_bf16 v[12:15], v[158:161], v[234:237], v[12:15]
	v_mfma_f32_16x16x32_bf16 v[8:11], v[186:189], v[234:237], v[8:11]
	v_mfma_f32_16x16x32_bf16 v[52:55], v[190:193], v[206:209], v[52:55]
	v_mfma_f32_16x16x32_bf16 v[48:51], v[198:201], v[206:209], v[48:51]
	v_mfma_f32_16x16x32_bf16 v[36:39], v[190:193], v[214:217], v[36:39]
	v_mfma_f32_16x16x32_bf16 v[32:35], v[198:201], v[214:217], v[32:35]
	v_mfma_f32_16x16x32_bf16 v[20:23], v[190:193], v[222:225], v[20:23]
	v_mfma_f32_16x16x32_bf16 v[16:19], v[198:201], v[222:225], v[16:19]
	v_mfma_f32_16x16x32_bf16 v[4:7], v[190:193], v[230:233], v[4:7]
	v_mfma_f32_16x16x32_bf16 v[0:3], v[198:201], v[230:233], v[0:3]
	v_mfma_f32_16x16x32_bf16 v[52:55], v[194:197], v[210:213], v[52:55]
	v_mfma_f32_16x16x32_bf16 v[48:51], v[202:205], v[210:213], v[48:51]
	v_mfma_f32_16x16x32_bf16 v[36:39], v[194:197], v[218:221], v[36:39]
	v_mfma_f32_16x16x32_bf16 v[32:35], v[202:205], v[218:221], v[32:35]
	v_mfma_f32_16x16x32_bf16 v[20:23], v[194:197], v[226:229], v[20:23]
	v_mfma_f32_16x16x32_bf16 v[16:19], v[202:205], v[226:229], v[16:19]
	v_mfma_f32_16x16x32_bf16 v[4:7], v[194:197], v[234:237], v[4:7]
	v_mfma_f32_16x16x32_bf16 v[0:3], v[202:205], v[234:237], v[0:3]
	s_barrier
	s_add_i32 s56, 0, 0x18000
	v_add_u32_e32 v185, s56, v141
	s_add_i32 s57, 0, 0x1c000
	ds_read_b128 v[154:157], v185
	ds_read_b128 v[158:161], v185 offset:1024
	ds_read_b128 v[162:165], v185 offset:2048
	ds_read_b128 v[186:189], v185 offset:3072
	v_add_u32_e32 v185, s57, v141
	ds_read_b128 v[190:193], v185
	ds_read_b128 v[194:197], v185 offset:1024
	ds_read_b128 v[198:201], v185 offset:2048
	ds_read_b128 v[202:205], v185 offset:3072
	s_add_u32 s28, s28, s6
	s_addc_u32 s29, s29, s7
	s_mov_b32 m0, s40
	v_lshl_add_u64 v[246:247], s[28:29], 0, v[132:133]
	ds_read_b128 v[206:209], v143 offset:32768
	ds_read_b128 v[210:213], v143 offset:33792
	ds_read_b128 v[214:217], v143 offset:34816
	ds_read_b128 v[218:221], v143 offset:35840
	ds_read_b128 v[222:225], v143 offset:36864
	ds_read_b128 v[226:229], v143 offset:37888
	ds_read_b128 v[230:233], v143 offset:38912
	ds_read_b128 v[234:237], v143 offset:39936
	global_load_lds_dwordx4 v[246:247], off
	v_lshl_add_u64 v[246:247], s[28:29], 0, v[130:131]
	s_mov_b32 m0, s41
	s_nop 0
	global_load_lds_dwordx4 v[246:247], off
	s_waitcnt vmcnt(8)
	s_waitcnt lgkmcnt(0)
	s_barrier
	s_waitcnt lgkmcnt(0)
	v_mfma_f32_16x16x32_bf16 v[120:123], v[154:157], v[206:209], v[120:123]
	v_mfma_f32_16x16x32_bf16 v[124:127], v[162:165], v[206:209], v[124:127]
	v_mfma_f32_16x16x32_bf16 v[108:111], v[154:157], v[214:217], v[108:111]
	v_mfma_f32_16x16x32_bf16 v[104:107], v[162:165], v[214:217], v[104:107]
	v_mfma_f32_16x16x32_bf16 v[92:95], v[154:157], v[222:225], v[92:95]
	v_mfma_f32_16x16x32_bf16 v[88:91], v[162:165], v[222:225], v[88:91]
	v_mfma_f32_16x16x32_bf16 v[76:79], v[154:157], v[230:233], v[76:79]
	v_mfma_f32_16x16x32_bf16 v[72:75], v[162:165], v[230:233], v[72:75]
	v_mfma_f32_16x16x32_bf16 v[120:123], v[158:161], v[210:213], v[120:123]
	v_mfma_f32_16x16x32_bf16 v[124:127], v[186:189], v[210:213], v[124:127]
	v_mfma_f32_16x16x32_bf16 v[108:111], v[158:161], v[218:221], v[108:111]
	v_mfma_f32_16x16x32_bf16 v[104:107], v[186:189], v[218:221], v[104:107]
	v_mfma_f32_16x16x32_bf16 v[92:95], v[158:161], v[226:229], v[92:95]
	v_mfma_f32_16x16x32_bf16 v[88:91], v[186:189], v[226:229], v[88:91]
	v_mfma_f32_16x16x32_bf16 v[76:79], v[158:161], v[234:237], v[76:79]
	v_mfma_f32_16x16x32_bf16 v[72:75], v[186:189], v[234:237], v[72:75]
	v_mfma_f32_16x16x32_bf16 v[116:119], v[190:193], v[206:209], v[116:119]
	v_mfma_f32_16x16x32_bf16 v[112:115], v[198:201], v[206:209], v[112:115]
	v_mfma_f32_16x16x32_bf16 v[100:103], v[190:193], v[214:217], v[100:103]
	v_mfma_f32_16x16x32_bf16 v[96:99], v[198:201], v[214:217], v[96:99]
	v_mfma_f32_16x16x32_bf16 v[84:87], v[190:193], v[222:225], v[84:87]
	v_mfma_f32_16x16x32_bf16 v[80:83], v[198:201], v[222:225], v[80:83]
	v_mfma_f32_16x16x32_bf16 v[68:71], v[190:193], v[230:233], v[68:71]
	v_mfma_f32_16x16x32_bf16 v[64:67], v[198:201], v[230:233], v[64:67]
	v_mfma_f32_16x16x32_bf16 v[116:119], v[194:197], v[210:213], v[116:119]
	v_mfma_f32_16x16x32_bf16 v[112:115], v[202:205], v[210:213], v[112:115]
	v_mfma_f32_16x16x32_bf16 v[100:103], v[194:197], v[218:221], v[100:103]
	v_mfma_f32_16x16x32_bf16 v[96:99], v[202:205], v[218:221], v[96:99]
	v_mfma_f32_16x16x32_bf16 v[84:87], v[194:197], v[226:229], v[84:87]
	v_mfma_f32_16x16x32_bf16 v[80:83], v[202:205], v[226:229], v[80:83]
	v_mfma_f32_16x16x32_bf16 v[68:71], v[194:197], v[234:237], v[68:71]
	v_mfma_f32_16x16x32_bf16 v[64:67], v[202:205], v[234:237], v[64:67]
	s_barrier
; #define PG8_STAGE(bufoff, gbase, voff) do { _Pragma("unroll") for (int _i = 0; _i < 2; ++_i) \
;         __builtin_amdgcn_global_load_lds((const unsigned*)((const char*)(gbase) + (voff)[_i]), (PG8_LAS unsigned*)(lds + (bufoff) + ldsw + _i * 8192), 16, 0, 0); } while (0)
; #define PG8_LDA(dst, b, h) do { _Pragma("unroll") for (int m = 0; m < 4; ++m) _Pragma("unroll") for (int k = 0; k < 2; ++k) dst[m][k] = *(const PG8_LAS bf16x8*)(lds + PG8_SA(b, h) + aoff + m * 2048 + k * 1024); } while (0)
; #define PG8_MMA(ai, bj, At, Bt) do { __builtin_amdgcn_s_setprio(1); _Pragma("unroll") for (int m = 0; m < 4; ++m) _Pragma("unroll") for (int n = 0; n < 2; ++n) _Pragma("unroll") for (int k = 0; k < 2; ++k) \
;         acc[ai][bj][m][n] = __builtin_amdgcn_mfma_f32_16x16x32_bf16(Bt[n][k], At[m][k], acc[ai][bj][m][n], 0, 0, 0); __builtin_amdgcn_s_setprio(0); } while (0)
; #define PG8_WAIT_V(n) asm volatile("s_waitcnt vmcnt(" #n ")" ::: "memory")
; #define PG8_WAIT_L(n) asm volatile("s_waitcnt lgkmcnt(" #n ")" ::: "memory")
; #define PG8_BAR __builtin_amdgcn_s_barrier()
; #define PG8_SCHED __builtin_amdgcn_sched_barrier(0)
; template <class Epi, class Sched>
; __device__ __forceinline__ void gemm_phase(int wid_s, PG8_LAS unsigned char* lds, const Gemm g, const Sched& S, const Epi& E) {
;     ...
;         for (int t = 0; t < nt; t += 2) {
;     ...
;             PG8_LDA(At, 1, 1); PG8_STAGE(PG8_SB(1, 0), b3, voffB); PG8_STAGE(PG8_SB(1, 1), b3 + hstepB, voffB); PG8_STAGE(PG8_SA(1, 0), a3, voffA);
;             PG8_WAIT_V(8); PG8_WAIT_L(0); PG8_BAR; PG8_MMA(1, 0, At, B0); PG8_MMA(1, 1, At, B1); PG8_BAR; PG8_SCHED;
	s_add_i32 s28, s56, s35
	v_lshl_add_u64 v[138:139], v[138:139], 0, s[96:97]
	s_mov_b32 m0, s28
	ds_read_b128 v[206:209], v143 offset:49152
	ds_read_b128 v[210:213], v143 offset:50176
	ds_read_b128 v[214:217], v143 offset:51200
	ds_read_b128 v[218:221], v143 offset:52224
	ds_read_b128 v[222:225], v143 offset:53248
	ds_read_b128 v[226:229], v143 offset:54272
	ds_read_b128 v[230:233], v143 offset:55296
	ds_read_b128 v[234:237], v143 offset:56320
	global_load_lds_dwordx4 v[138:139], off
	v_lshl_add_u64 v[138:139], v[166:167], 0, s[96:97]
	s_add_i32 m0, s28, 0x2000
	s_add_i32 s28, s57, s35
	global_load_lds_dwordx4 v[138:139], off
	v_lshl_add_u64 v[138:139], v[238:239], 0, s[96:97]
	s_mov_b32 m0, s28
	s_nop 0
	global_load_lds_dwordx4 v[138:139], off
	v_lshl_add_u64 v[138:139], v[240:241], 0, s[96:97]
	s_add_i32 m0, s28, 0x2000
	s_nop 0
	global_load_lds_dwordx4 v[138:139], off
	v_lshl_add_u64 v[138:139], v[242:243], 0, s[96:97]
	s_mov_b32 m0, s44
	s_nop 0
	global_load_lds_dwordx4 v[138:139], off
	v_lshl_add_u64 v[138:139], v[244:245], 0, s[96:97]
	s_mov_b32 m0, s45
	s_nop 0
	global_load_lds_dwordx4 v[138:139], off
	s_waitcnt vmcnt(8)
	s_waitcnt lgkmcnt(0)
	s_barrier
	s_waitcnt lgkmcnt(0)
	v_mfma_f32_16x16x32_bf16 v[60:63], v[154:157], v[206:209], v[60:63]
	v_mfma_f32_16x16x32_bf16 v[56:59], v[162:165], v[206:209], v[56:59]
	v_mfma_f32_16x16x32_bf16 v[44:47], v[154:157], v[214:217], v[44:47]
	v_mfma_f32_16x16x32_bf16 v[40:43], v[162:165], v[214:217], v[40:43]
	v_mfma_f32_16x16x32_bf16 v[28:31], v[154:157], v[222:225], v[28:31]
	v_mfma_f32_16x16x32_bf16 v[24:27], v[162:165], v[222:225], v[24:27]
	v_mfma_f32_16x16x32_bf16 v[12:15], v[154:157], v[230:233], v[12:15]
	v_mfma_f32_16x16x32_bf16 v[8:11], v[162:165], v[230:233], v[8:11]
	v_mfma_f32_16x16x32_bf16 v[60:63], v[158:161], v[210:213], v[60:63]
	v_mfma_f32_16x16x32_bf16 v[56:59], v[186:189], v[210:213], v[56:59]
	v_mfma_f32_16x16x32_bf16 v[44:47], v[158:161], v[218:221], v[44:47]
	v_mfma_f32_16x16x32_bf16 v[40:43], v[186:189], v[218:221], v[40:43]
	v_mfma_f32_16x16x32_bf16 v[28:31], v[158:161], v[226:229], v[28:31]
	v_mfma_f32_16x16x32_bf16 v[24:27], v[186:189], v[226:229], v[24:27]
	v_mfma_f32_16x16x32_bf16 v[12:15], v[158:161], v[234:237], v[12:15]
	v_mfma_f32_16x16x32_bf16 v[8:11], v[186:189], v[234:237], v[8:11]
	v_mfma_f32_16x16x32_bf16 v[52:55], v[190:193], v[206:209], v[52:55]
	v_mfma_f32_16x16x32_bf16 v[48:51], v[198:201], v[206:209], v[48:51]
	v_mfma_f32_16x16x32_bf16 v[36:39], v[190:193], v[214:217], v[36:39]
	v_mfma_f32_16x16x32_bf16 v[32:35], v[198:201], v[214:217], v[32:35]
	v_mfma_f32_16x16x32_bf16 v[20:23], v[190:193], v[222:225], v[20:23]
	v_mfma_f32_16x16x32_bf16 v[16:19], v[198:201], v[222:225], v[16:19]
	v_mfma_f32_16x16x32_bf16 v[4:7], v[190:193], v[230:233], v[4:7]
	v_mfma_f32_16x16x32_bf16 v[0:3], v[198:201], v[230:233], v[0:3]
	v_mfma_f32_16x16x32_bf16 v[52:55], v[194:197], v[210:213], v[52:55]
	v_mfma_f32_16x16x32_bf16 v[48:51], v[202:205], v[210:213], v[48:51]
	v_mfma_f32_16x16x32_bf16 v[36:39], v[194:197], v[218:221], v[36:39]
	v_mfma_f32_16x16x32_bf16 v[32:35], v[202:205], v[218:221], v[32:35]
	v_mfma_f32_16x16x32_bf16 v[20:23], v[194:197], v[226:229], v[20:23]
	v_mfma_f32_16x16x32_bf16 v[16:19], v[202:205], v[226:229], v[16:19]
	v_mfma_f32_16x16x32_bf16 v[4:7], v[194:197], v[234:237], v[4:7]
	v_mfma_f32_16x16x32_bf16 v[0:3], v[202:205], v[234:237], v[0:3]
	s_barrier
	s_add_u32 s33, s33, 0x100
	s_addc_u32 s54, s54, 0
	s_add_u32 s26, s26, 0x100
	s_addc_u32 s27, s27, 0
	s_cmp_ge_i32 s55, s42
	s_mov_b32 s28, s55
	s_cbranch_scc0 .LBB0_1061
	v_readlane_b32 s54, v254, 52
	v_readlane_b32 s55, v254, 53
	v_readlane_b32 s92, v254, 54
	v_readlane_b32 s94, v254, 55
	s_movk_i32 s33, 0x300

; #define PG8_STAGE(bufoff, gbase, voff) do { _Pragma("unroll") for (int _i = 0; _i < 2; ++_i) \
;         __builtin_amdgcn_global_load_lds((const unsigned*)((const char*)(gbase) + (voff)[_i]), (PG8_LAS unsigned*)(lds + (bufoff) + ldsw + _i * 8192), 16, 0, 0); } while (0)
; #define PG8_LDA(dst, b, h) do { _Pragma("unroll") for (int m = 0; m < 4; ++m) _Pragma("unroll") for (int k = 0; k < 2; ++k) dst[m][k] = *(const PG8_LAS bf16x8*)(lds + PG8_SA(b, h) + aoff + m * 2048 + k * 1024); } while (0)
; #define PG8_LDB(dst, b, h) do { _Pragma("unroll") for (int n = 0; n < 2; ++n) _Pragma("unroll") for (int k = 0; k < 2; ++k) dst[n][k] = *(const PG8_LAS bf16x8*)(lds + PG8_SB(b, h) + boff + n * 2048 + k * 1024); } while (0)
; #define PG8_MMA(ai, bj, At, Bt) do { __builtin_amdgcn_s_setprio(1); _Pragma("unroll") for (int m = 0; m < 4; ++m) _Pragma("unroll") for (int n = 0; n < 2; ++n) _Pragma("unroll") for (int k = 0; k < 2; ++k) \
;         acc[ai][bj][m][n] = __builtin_amdgcn_mfma_f32_16x16x32_bf16(Bt[n][k], At[m][k], acc[ai][bj][m][n], 0, 0, 0); __builtin_amdgcn_s_setprio(0); } while (0)
; #define PG8_WAIT_V(n) asm volatile("s_waitcnt vmcnt(" #n ")" ::: "memory")
; #define PG8_WAIT_L(n) asm volatile("s_waitcnt lgkmcnt(" #n ")" ::: "memory")
; #define PG8_BAR __builtin_amdgcn_s_barrier()
; #define PG8_SCHED __builtin_amdgcn_sched_barrier(0)
; template <class Epi, class Sched>
; __device__ __forceinline__ void gemm_phase(int wid_s, PG8_LAS unsigned char* lds, const Gemm g, const Sched& S, const Epi& E) {
;     ...
;         for (int t = 0; t < nt; t += 2) {
;             const bool last = (t == nt - 2);
;             const char* a1 = cA + (size_t)(t + 1) * kstep;
;             const char* a2 = last ? nA : cA + (size_t)(t + 2) * kstep; const char* b2 = last ? nB : cB + (size_t)(t + 2) * kstep;
;             const char* a3 = a2 + kstep; const char* b3 = b2 + kstep;
;             PG8_LDB(B0, 0, 0); PG8_LDB(B1, 0, 1); PG8_SCHED; PG8_LDA(At, 0, 0); PG8_STAGE(PG8_SA(1, 1), a1 + hstepA, voffA);
;             PG8_WAIT_V(8); PG8_WAIT_L(0); PG8_BAR; PG8_MMA(0, 0, At, B0); PG8_MMA(0, 1, At, B1); PG8_BAR; PG8_SCHED;
;             PG8_LDA(At, 0, 1); PG8_STAGE(PG8_SB(0, 0), b2, voffB); PG8_STAGE(PG8_SB(0, 1), b2 + hstepB, voffB); PG8_STAGE(PG8_SA(0, 0), a2, voffA);
;             PG8_WAIT_V(8); PG8_WAIT_L(0); PG8_BAR; PG8_MMA(1, 0, At, B0); PG8_MMA(1, 1, At, B1); PG8_BAR; PG8_SCHED;
.LBB0_1093:
	s_add_i32 s33, s30, 2
	s_add_u32 s34, s4, 0x80
	s_addc_u32 s31, s5, 0
	s_add_i32 s50, 0, 0x10000
	s_cmp_eq_u32 s94, s30
	s_cselect_b32 s31, s27, s31
	s_cselect_b32 s30, s26, s34
	v_add_u32_e32 v144, s50, v162
	s_cselect_b32 s35, s29, s15
	s_cselect_b32 s34, s28, s14
	s_add_i32 s51, 0, 0x14000
	ds_read_b128 v[154:157], v144
	ds_read_b128 v[158:161], v144 offset:1024
	ds_read_b128 v[164:167], v144 offset:2048
	ds_read_b128 v[186:189], v144 offset:3072
	v_add_u32_e32 v144, s51, v162
	ds_read_b128 v[190:193], v144
	ds_read_b128 v[194:197], v144 offset:1024
	ds_read_b128 v[198:201], v144 offset:2048
	ds_read_b128 v[202:205], v144 offset:3072
	v_lshl_add_u64 v[238:239], s[4:5], 0, v[142:143]
	s_add_i32 m0, s46, 0xc000
	ds_read_b128 v[206:209], v163
	ds_read_b128 v[210:213], v163 offset:1024
	ds_read_b128 v[214:217], v163 offset:2048
	ds_read_b128 v[218:221], v163 offset:3072
	ds_read_b128 v[222:225], v163 offset:4096
	ds_read_b128 v[226:229], v163 offset:5120
	ds_read_b128 v[230:233], v163 offset:6144
	ds_read_b128 v[234:237], v163 offset:7168
	global_load_lds_dwordx4 v[238:239], off
	v_lshl_add_u64 v[238:239], s[4:5], 0, v[140:141]
	s_add_i32 m0, s46, 0xe000
	s_nop 0
	global_load_lds_dwordx4 v[238:239], off
	s_waitcnt vmcnt(8)
	s_waitcnt lgkmcnt(0)
	s_barrier
	s_waitcnt lgkmcnt(0)
	v_mfma_f32_16x16x32_bf16 v[120:123], v[154:157], v[206:209], v[120:123]
	v_mfma_f32_16x16x32_bf16 v[124:127], v[164:167], v[206:209], v[124:127]
	v_mfma_f32_16x16x32_bf16 v[108:111], v[154:157], v[214:217], v[108:111]
	v_mfma_f32_16x16x32_bf16 v[104:107], v[164:167], v[214:217], v[104:107]
	v_mfma_f32_16x16x32_bf16 v[92:95], v[154:157], v[222:225], v[92:95]
	v_mfma_f32_16x16x32_bf16 v[88:91], v[164:167], v[222:225], v[88:91]
	v_mfma_f32_16x16x32_bf16 v[76:79], v[154:157], v[230:233], v[76:79]
	v_mfma_f32_16x16x32_bf16 v[72:75], v[164:167], v[230:233], v[72:75]
	v_mfma_f32_16x16x32_bf16 v[120:123], v[158:161], v[210:213], v[120:123]
	v_mfma_f32_16x16x32_bf16 v[124:127], v[186:189], v[210:213], v[124:127]
	v_mfma_f32_16x16x32_bf16 v[108:111], v[158:161], v[218:221], v[108:111]
	v_mfma_f32_16x16x32_bf16 v[104:107], v[186:189], v[218:221], v[104:107]
	v_mfma_f32_16x16x32_bf16 v[92:95], v[158:161], v[226:229], v[92:95]
	v_mfma_f32_16x16x32_bf16 v[88:91], v[186:189], v[226:229], v[88:91]
	v_mfma_f32_16x16x32_bf16 v[76:79], v[158:161], v[234:237], v[76:79]
	v_mfma_f32_16x16x32_bf16 v[72:75], v[186:189], v[234:237], v[72:75]
	v_mfma_f32_16x16x32_bf16 v[116:119], v[190:193], v[206:209], v[116:119]
	v_mfma_f32_16x16x32_bf16 v[112:115], v[198:201], v[206:209], v[112:115]
	v_mfma_f32_16x16x32_bf16 v[100:103], v[190:193], v[214:217], v[100:103]
	v_mfma_f32_16x16x32_bf16 v[96:99], v[198:201], v[214:217], v[96:99]
	v_mfma_f32_16x16x32_bf16 v[84:87], v[190:193], v[222:225], v[84:87]
	v_mfma_f32_16x16x32_bf16 v[80:83], v[198:201], v[222:225], v[80:83]
	v_mfma_f32_16x16x32_bf16 v[68:71], v[190:193], v[230:233], v[68:71]
	v_mfma_f32_16x16x32_bf16 v[64:67], v[198:201], v[230:233], v[64:67]
	v_mfma_f32_16x16x32_bf16 v[116:119], v[194:197], v[210:213], v[116:119]
	v_mfma_f32_16x16x32_bf16 v[112:115], v[202:205], v[210:213], v[112:115]
	v_mfma_f32_16x16x32_bf16 v[100:103], v[194:197], v[218:221], v[100:103]
	v_mfma_f32_16x16x32_bf16 v[96:99], v[202:205], v[218:221], v[96:99]
	v_mfma_f32_16x16x32_bf16 v[84:87], v[194:197], v[226:229], v[84:87]
	v_mfma_f32_16x16x32_bf16 v[80:83], v[202:205], v[226:229], v[80:83]
	v_mfma_f32_16x16x32_bf16 v[68:71], v[194:197], v[234:237], v[68:71]
	v_mfma_f32_16x16x32_bf16 v[64:67], v[202:205], v[234:237], v[64:67]
	s_barrier
	s_add_i32 s50, s50, s41
	v_lshl_add_u64 v[238:239], s[34:35], 0, v[130:131]
	s_mov_b32 m0, s50
	ds_read_b128 v[206:209], v163 offset:16384
	ds_read_b128 v[210:213], v163 offset:17408
	ds_read_b128 v[214:217], v163 offset:18432
	ds_read_b128 v[218:221], v163 offset:19456
	ds_read_b128 v[222:225], v163 offset:20480
	ds_read_b128 v[226:229], v163 offset:21504
	ds_read_b128 v[230:233], v163 offset:22528
	ds_read_b128 v[234:237], v163 offset:23552
	global_load_lds_dwordx4 v[238:239], off
	s_add_i32 m0, s50, 0x2000
	v_lshl_add_u64 v[240:241], s[34:35], 0, v[134:135]
	s_add_u32 s34, s34, s8
	s_addc_u32 s35, s35, s9
	s_add_i32 s50, s51, s41
	global_load_lds_dwordx4 v[240:241], off
	v_lshl_add_u64 v[242:243], s[34:35], 0, v[130:131]
	s_mov_b32 m0, s50
	v_lshl_add_u64 v[244:245], s[34:35], 0, v[134:135]
	global_load_lds_dwordx4 v[242:243], off
	s_add_i32 m0, s50, 0x2000
	v_lshl_add_u64 v[246:247], s[30:31], 0, v[128:129]
	global_load_lds_dwordx4 v[244:245], off
	s_mov_b32 m0, s46
	v_lshl_add_u64 v[248:249], s[30:31], 0, v[132:133]
	global_load_lds_dwordx4 v[246:247], off
	s_mov_b32 m0, s47
	s_nop 0
	global_load_lds_dwordx4 v[248:249], off
	s_waitcnt vmcnt(8)
	s_waitcnt lgkmcnt(0)
	s_barrier
; #define PG8_STAGE(bufoff, gbase, voff) do { _Pragma("unroll") for (int _i = 0; _i < 2; ++_i) \
;         __builtin_amdgcn_global_load_lds((const unsigned*)((const char*)(gbase) + (voff)[_i]), (PG8_LAS unsigned*)(lds + (bufoff) + ldsw + _i * 8192), 16, 0, 0); } while (0)
; #define PG8_LDA(dst, b, h) do { _Pragma("unroll") for (int m = 0; m < 4; ++m) _Pragma("unroll") for (int k = 0; k < 2; ++k) dst[m][k] = *(const PG8_LAS bf16x8*)(lds + PG8_SA(b, h) + aoff + m * 2048 + k * 1024); } while (0)
; #define PG8_LDB(dst, b, h) do { _Pragma("unroll") for (int n = 0; n < 2; ++n) _Pragma("unroll") for (int k = 0; k < 2; ++k) dst[n][k] = *(const PG8_LAS bf16x8*)(lds + PG8_SB(b, h) + boff + n * 2048 + k * 1024); } while (0)
; #define PG8_MMA(ai, bj, At, Bt) do { __builtin_amdgcn_s_setprio(1); _Pragma("unroll") for (int m = 0; m < 4; ++m) _Pragma("unroll") for (int n = 0; n < 2; ++n) _Pragma("unroll") for (int k = 0; k < 2; ++k) \
;         acc[ai][bj][m][n] = __builtin_amdgcn_mfma_f32_16x16x32_bf16(Bt[n][k], At[m][k], acc[ai][bj][m][n], 0, 0, 0); __builtin_amdgcn_s_setprio(0); } while (0)
; #define PG8_WAIT_V(n) asm volatile("s_waitcnt vmcnt(" #n ")" ::: "memory")
; #define PG8_WAIT_L(n) asm volatile("s_waitcnt lgkmcnt(" #n ")" ::: "memory")
; #define PG8_BAR __builtin_amdgcn_s_barrier()
; #define PG8_SCHED __builtin_amdgcn_sched_barrier(0)
; template <class Epi, class Sched>
; __device__ __forceinline__ void gemm_phase(int wid_s, PG8_LAS unsigned char* lds, const Gemm g, const Sched& S, const Epi& E) {
;     ...
;             PG8_WAIT_V(8); PG8_WAIT_L(0); PG8_BAR; PG8_MMA(1, 0, At, B0); PG8_MMA(1, 1, At, B1); PG8_BAR; PG8_SCHED;
;             PG8_LDB(B0, 1, 0); PG8_LDB(B1, 1, 1); PG8_SCHED; PG8_LDA(At, 1, 0); PG8_STAGE(PG8_SA(0, 1), a2 + hstepA, voffA);
;             PG8_WAIT_V(8); PG8_WAIT_L(0); PG8_BAR; PG8_MMA(0, 0, At, B0); PG8_MMA(0, 1, At, B1); PG8_BAR; PG8_SCHED;
	s_waitcnt lgkmcnt(0)
	v_mfma_f32_16x16x32_bf16 v[60:63], v[154:157], v[206:209], v[60:63]
	v_mfma_f32_16x16x32_bf16 v[56:59], v[164:167], v[206:209], v[56:59]
	v_mfma_f32_16x16x32_bf16 v[44:47], v[154:157], v[214:217], v[44:47]
	v_mfma_f32_16x16x32_bf16 v[40:43], v[164:167], v[214:217], v[40:43]
	v_mfma_f32_16x16x32_bf16 v[28:31], v[154:157], v[222:225], v[28:31]
	v_mfma_f32_16x16x32_bf16 v[24:27], v[164:167], v[222:225], v[24:27]
	v_mfma_f32_16x16x32_bf16 v[12:15], v[154:157], v[230:233], v[12:15]
	v_mfma_f32_16x16x32_bf16 v[8:11], v[164:167], v[230:233], v[8:11]
	v_mfma_f32_16x16x32_bf16 v[60:63], v[158:161], v[210:213], v[60:63]
	v_mfma_f32_16x16x32_bf16 v[56:59], v[186:189], v[210:213], v[56:59]
	v_mfma_f32_16x16x32_bf16 v[44:47], v[158:161], v[218:221], v[44:47]
	v_mfma_f32_16x16x32_bf16 v[40:43], v[186:189], v[218:221], v[40:43]
	v_mfma_f32_16x16x32_bf16 v[28:31], v[158:161], v[226:229], v[28:31]
	v_mfma_f32_16x16x32_bf16 v[24:27], v[186:189], v[226:229], v[24:27]
	v_mfma_f32_16x16x32_bf16 v[12:15], v[158:161], v[234:237], v[12:15]
	v_mfma_f32_16x16x32_bf16 v[8:11], v[186:189], v[234:237], v[8:11]
	v_mfma_f32_16x16x32_bf16 v[52:55], v[190:193], v[206:209], v[52:55]
	v_mfma_f32_16x16x32_bf16 v[48:51], v[198:201], v[206:209], v[48:51]
	v_mfma_f32_16x16x32_bf16 v[36:39], v[190:193], v[214:217], v[36:39]
	v_mfma_f32_16x16x32_bf16 v[32:35], v[198:201], v[214:217], v[32:35]
	v_mfma_f32_16x16x32_bf16 v[20:23], v[190:193], v[222:225], v[20:23]
	v_mfma_f32_16x16x32_bf16 v[16:19], v[198:201], v[222:225], v[16:19]
	v_mfma_f32_16x16x32_bf16 v[4:7], v[190:193], v[230:233], v[4:7]
	v_mfma_f32_16x16x32_bf16 v[0:3], v[198:201], v[230:233], v[0:3]
	v_mfma_f32_16x16x32_bf16 v[52:55], v[194:197], v[210:213], v[52:55]
	v_mfma_f32_16x16x32_bf16 v[48:51], v[202:205], v[210:213], v[48:51]
	v_mfma_f32_16x16x32_bf16 v[36:39], v[194:197], v[218:221], v[36:39]
	v_mfma_f32_16x16x32_bf16 v[32:35], v[202:205], v[218:221], v[32:35]
	v_mfma_f32_16x16x32_bf16 v[20:23], v[194:197], v[226:229], v[20:23]
	v_mfma_f32_16x16x32_bf16 v[16:19], v[202:205], v[226:229], v[16:19]
	v_mfma_f32_16x16x32_bf16 v[4:7], v[194:197], v[234:237], v[4:7]
	v_mfma_f32_16x16x32_bf16 v[0:3], v[202:205], v[234:237], v[0:3]
	s_barrier
	s_add_i32 s34, 0, 0x18000
	v_add_u32_e32 v144, s34, v162
	s_add_i32 s35, 0, 0x1c000
	ds_read_b128 v[154:157], v144
	ds_read_b128 v[158:161], v144 offset:1024
	ds_read_b128 v[164:167], v144 offset:2048
	ds_read_b128 v[186:189], v144 offset:3072
	v_add_u32_e32 v144, s35, v162
	ds_read_b128 v[190:193], v144
	ds_read_b128 v[194:197], v144 offset:1024
	ds_read_b128 v[198:201], v144 offset:2048
	ds_read_b128 v[202:205], v144 offset:3072
	s_add_u32 s30, s30, s6
	s_addc_u32 s31, s31, s7
	s_mov_b32 m0, s53
	v_lshl_add_u64 v[250:251], s[30:31], 0, v[128:129]
	ds_read_b128 v[206:209], v163 offset:32768
	ds_read_b128 v[210:213], v163 offset:33792
	ds_read_b128 v[214:217], v163 offset:34816
	ds_read_b128 v[218:221], v163 offset:35840
	ds_read_b128 v[222:225], v163 offset:36864
	ds_read_b128 v[226:229], v163 offset:37888
	ds_read_b128 v[230:233], v163 offset:38912
	ds_read_b128 v[234:237], v163 offset:39936
	global_load_lds_dwordx4 v[250:251], off
	v_lshl_add_u64 v[250:251], s[30:31], 0, v[132:133]
	s_mov_b32 m0, s54
	s_nop 0
	global_load_lds_dwordx4 v[250:251], off
	s_waitcnt vmcnt(8)
	s_waitcnt lgkmcnt(0)
	s_barrier
	s_waitcnt lgkmcnt(0)
	v_mfma_f32_16x16x32_bf16 v[120:123], v[154:157], v[206:209], v[120:123]
	v_mfma_f32_16x16x32_bf16 v[124:127], v[164:167], v[206:209], v[124:127]
	v_mfma_f32_16x16x32_bf16 v[108:111], v[154:157], v[214:217], v[108:111]
	v_mfma_f32_16x16x32_bf16 v[104:107], v[164:167], v[214:217], v[104:107]
	v_mfma_f32_16x16x32_bf16 v[92:95], v[154:157], v[222:225], v[92:95]
	v_mfma_f32_16x16x32_bf16 v[88:91], v[164:167], v[222:225], v[88:91]
	v_mfma_f32_16x16x32_bf16 v[76:79], v[154:157], v[230:233], v[76:79]
	v_mfma_f32_16x16x32_bf16 v[72:75], v[164:167], v[230:233], v[72:75]
	v_mfma_f32_16x16x32_bf16 v[120:123], v[158:161], v[210:213], v[120:123]
	v_mfma_f32_16x16x32_bf16 v[124:127], v[186:189], v[210:213], v[124:127]
	v_mfma_f32_16x16x32_bf16 v[108:111], v[158:161], v[218:221], v[108:111]
	v_mfma_f32_16x16x32_bf16 v[104:107], v[186:189], v[218:221], v[104:107]
	v_mfma_f32_16x16x32_bf16 v[92:95], v[158:161], v[226:229], v[92:95]
	v_mfma_f32_16x16x32_bf16 v[88:91], v[186:189], v[226:229], v[88:91]
	v_mfma_f32_16x16x32_bf16 v[76:79], v[158:161], v[234:237], v[76:79]
	v_mfma_f32_16x16x32_bf16 v[72:75], v[186:189], v[234:237], v[72:75]
	v_mfma_f32_16x16x32_bf16 v[116:119], v[190:193], v[206:209], v[116:119]
	v_mfma_f32_16x16x32_bf16 v[112:115], v[198:201], v[206:209], v[112:115]
	v_mfma_f32_16x16x32_bf16 v[100:103], v[190:193], v[214:217], v[100:103]
	v_mfma_f32_16x16x32_bf16 v[96:99], v[198:201], v[214:217], v[96:99]
	v_mfma_f32_16x16x32_bf16 v[84:87], v[190:193], v[222:225], v[84:87]
	v_mfma_f32_16x16x32_bf16 v[80:83], v[198:201], v[222:225], v[80:83]
	v_mfma_f32_16x16x32_bf16 v[68:71], v[190:193], v[230:233], v[68:71]
	v_mfma_f32_16x16x32_bf16 v[64:67], v[198:201], v[230:233], v[64:67]
	v_mfma_f32_16x16x32_bf16 v[116:119], v[194:197], v[210:213], v[116:119]
	v_mfma_f32_16x16x32_bf16 v[112:115], v[202:205], v[210:213], v[112:115]
	v_mfma_f32_16x16x32_bf16 v[100:103], v[194:197], v[218:221], v[100:103]
	v_mfma_f32_16x16x32_bf16 v[96:99], v[202:205], v[218:221], v[96:99]
	v_mfma_f32_16x16x32_bf16 v[84:87], v[194:197], v[226:229], v[84:87]
	v_mfma_f32_16x16x32_bf16 v[80:83], v[202:205], v[226:229], v[80:83]
	v_mfma_f32_16x16x32_bf16 v[68:71], v[194:197], v[234:237], v[68:71]
	v_mfma_f32_16x16x32_bf16 v[64:67], v[202:205], v[234:237], v[64:67]
	s_barrier
; #define PG8_STAGE(bufoff, gbase, voff) do { _Pragma("unroll") for (int _i = 0; _i < 2; ++_i) \
;         __builtin_amdgcn_global_load_lds((const unsigned*)((const char*)(gbase) + (voff)[_i]), (PG8_LAS unsigned*)(lds + (bufoff) + ldsw + _i * 8192), 16, 0, 0); } while (0)
; #define PG8_LDA(dst, b, h) do { _Pragma("unroll") for (int m = 0; m < 4; ++m) _Pragma("unroll") for (int k = 0; k < 2; ++k) dst[m][k] = *(const PG8_LAS bf16x8*)(lds + PG8_SA(b, h) + aoff + m * 2048 + k * 1024); } while (0)
; #define PG8_MMA(ai, bj, At, Bt) do { __builtin_amdgcn_s_setprio(1); _Pragma("unroll") for (int m = 0; m < 4; ++m) _Pragma("unroll") for (int n = 0; n < 2; ++n) _Pragma("unroll") for (int k = 0; k < 2; ++k) \
;         acc[ai][bj][m][n] = __builtin_amdgcn_mfma_f32_16x16x32_bf16(Bt[n][k], At[m][k], acc[ai][bj][m][n], 0, 0, 0); __builtin_amdgcn_s_setprio(0); } while (0)
; #define PG8_WAIT_V(n) asm volatile("s_waitcnt vmcnt(" #n ")" ::: "memory")
; #define PG8_WAIT_L(n) asm volatile("s_waitcnt lgkmcnt(" #n ")" ::: "memory")
; #define PG8_BAR __builtin_amdgcn_s_barrier()
; #define PG8_SCHED __builtin_amdgcn_sched_barrier(0)
; template <class Epi, class Sched>
; __device__ __forceinline__ void gemm_phase(int wid_s, PG8_LAS unsigned char* lds, const Gemm g, const Sched& S, const Epi& E) {
;     ...
;         for (int t = 0; t < nt; t += 2) {
;     ...
;             PG8_LDA(At, 1, 1); PG8_STAGE(PG8_SB(1, 0), b3, voffB); PG8_STAGE(PG8_SB(1, 1), b3 + hstepB, voffB); PG8_STAGE(PG8_SA(1, 0), a3, voffA);
;             PG8_WAIT_V(8); PG8_WAIT_L(0); PG8_BAR; PG8_MMA(1, 0, At, B0); PG8_MMA(1, 1, At, B1); PG8_BAR; PG8_SCHED;
	s_add_i32 s30, s34, s41
	v_lshl_add_u64 v[238:239], v[238:239], 0, s[96:97]
	s_mov_b32 m0, s30
	ds_read_b128 v[206:209], v163 offset:49152
	ds_read_b128 v[210:213], v163 offset:50176
	ds_read_b128 v[214:217], v163 offset:51200
	ds_read_b128 v[218:221], v163 offset:52224
	ds_read_b128 v[222:225], v163 offset:53248
	ds_read_b128 v[226:229], v163 offset:54272
	ds_read_b128 v[230:233], v163 offset:55296
	ds_read_b128 v[234:237], v163 offset:56320
	global_load_lds_dwordx4 v[238:239], off
	v_lshl_add_u64 v[238:239], v[240:241], 0, s[96:97]
	s_add_i32 m0, s30, 0x2000
	s_add_i32 s30, s35, s41
	global_load_lds_dwordx4 v[238:239], off
	v_lshl_add_u64 v[238:239], v[242:243], 0, s[96:97]
	s_mov_b32 m0, s30
	s_nop 0
	global_load_lds_dwordx4 v[238:239], off
	v_lshl_add_u64 v[238:239], v[244:245], 0, s[96:97]
	s_add_i32 m0, s30, 0x2000
	s_nop 0
	global_load_lds_dwordx4 v[238:239], off
	v_lshl_add_u64 v[238:239], v[246:247], 0, s[96:97]
	s_mov_b32 m0, s55
	s_nop 0
	global_load_lds_dwordx4 v[238:239], off
	v_lshl_add_u64 v[238:239], v[248:249], 0, s[96:97]
	s_mov_b32 m0, s56
	s_nop 0
	global_load_lds_dwordx4 v[238:239], off
	s_waitcnt vmcnt(8)
	s_waitcnt lgkmcnt(0)
	s_barrier
	s_waitcnt lgkmcnt(0)
	v_mfma_f32_16x16x32_bf16 v[60:63], v[154:157], v[206:209], v[60:63]
	v_mfma_f32_16x16x32_bf16 v[56:59], v[164:167], v[206:209], v[56:59]
	v_mfma_f32_16x16x32_bf16 v[44:47], v[154:157], v[214:217], v[44:47]
	v_mfma_f32_16x16x32_bf16 v[40:43], v[164:167], v[214:217], v[40:43]
	v_mfma_f32_16x16x32_bf16 v[28:31], v[154:157], v[222:225], v[28:31]
	v_mfma_f32_16x16x32_bf16 v[24:27], v[164:167], v[222:225], v[24:27]
	v_mfma_f32_16x16x32_bf16 v[12:15], v[154:157], v[230:233], v[12:15]
	v_mfma_f32_16x16x32_bf16 v[8:11], v[164:167], v[230:233], v[8:11]
	v_mfma_f32_16x16x32_bf16 v[60:63], v[158:161], v[210:213], v[60:63]
	v_mfma_f32_16x16x32_bf16 v[56:59], v[186:189], v[210:213], v[56:59]
	v_mfma_f32_16x16x32_bf16 v[44:47], v[158:161], v[218:221], v[44:47]
	v_mfma_f32_16x16x32_bf16 v[40:43], v[186:189], v[218:221], v[40:43]
	v_mfma_f32_16x16x32_bf16 v[28:31], v[158:161], v[226:229], v[28:31]
	v_mfma_f32_16x16x32_bf16 v[24:27], v[186:189], v[226:229], v[24:27]
	v_mfma_f32_16x16x32_bf16 v[12:15], v[158:161], v[234:237], v[12:15]
	v_mfma_f32_16x16x32_bf16 v[8:11], v[186:189], v[234:237], v[8:11]
	v_mfma_f32_16x16x32_bf16 v[52:55], v[190:193], v[206:209], v[52:55]
	v_mfma_f32_16x16x32_bf16 v[48:51], v[198:201], v[206:209], v[48:51]
	v_mfma_f32_16x16x32_bf16 v[36:39], v[190:193], v[214:217], v[36:39]
	v_mfma_f32_16x16x32_bf16 v[32:35], v[198:201], v[214:217], v[32:35]
	v_mfma_f32_16x16x32_bf16 v[20:23], v[190:193], v[222:225], v[20:23]
	v_mfma_f32_16x16x32_bf16 v[16:19], v[198:201], v[222:225], v[16:19]
	v_mfma_f32_16x16x32_bf16 v[4:7], v[190:193], v[230:233], v[4:7]
	v_mfma_f32_16x16x32_bf16 v[0:3], v[198:201], v[230:233], v[0:3]
	v_mfma_f32_16x16x32_bf16 v[52:55], v[194:197], v[210:213], v[52:55]
	v_mfma_f32_16x16x32_bf16 v[48:51], v[202:205], v[210:213], v[48:51]
	v_mfma_f32_16x16x32_bf16 v[36:39], v[194:197], v[218:221], v[36:39]
	v_mfma_f32_16x16x32_bf16 v[32:35], v[202:205], v[218:221], v[32:35]
	v_mfma_f32_16x16x32_bf16 v[20:23], v[194:197], v[226:229], v[20:23]
	v_mfma_f32_16x16x32_bf16 v[16:19], v[202:205], v[226:229], v[16:19]
	v_mfma_f32_16x16x32_bf16 v[4:7], v[194:197], v[234:237], v[4:7]
	v_mfma_f32_16x16x32_bf16 v[0:3], v[202:205], v[234:237], v[0:3]
	s_barrier
	s_add_u32 s14, s14, 0x100
	s_addc_u32 s15, s15, 0
	s_add_u32 s4, s4, 0x100
	s_addc_u32 s5, s5, 0
	s_cmp_ge_i32 s33, s57
	s_mov_b32 s30, s33
	s_cbranch_scc0 .LBB0_1093
	s_movk_i32 s51, 0x1000

; #define PG8_STAGE(bufoff, gbase, voff) do { _Pragma("unroll") for (int _i = 0; _i < 2; ++_i) \
;         __builtin_amdgcn_global_load_lds((const unsigned*)((const char*)(gbase) + (voff)[_i]), (PG8_LAS unsigned*)(lds + (bufoff) + ldsw + _i * 8192), 16, 0, 0); } while (0)
; #define PG8_LDA(dst, b, h) do { _Pragma("unroll") for (int m = 0; m < 4; ++m) _Pragma("unroll") for (int k = 0; k < 2; ++k) dst[m][k] = *(const PG8_LAS bf16x8*)(lds + PG8_SA(b, h) + aoff + m * 2048 + k * 1024); } while (0)
; #define PG8_LDB(dst, b, h) do { _Pragma("unroll") for (int n = 0; n < 2; ++n) _Pragma("unroll") for (int k = 0; k < 2; ++k) dst[n][k] = *(const PG8_LAS bf16x8*)(lds + PG8_SB(b, h) + boff + n * 2048 + k * 1024); } while (0)
; #define PG8_MMA(ai, bj, At, Bt) do { __builtin_amdgcn_s_setprio(1); _Pragma("unroll") for (int m = 0; m < 4; ++m) _Pragma("unroll") for (int n = 0; n < 2; ++n) _Pragma("unroll") for (int k = 0; k < 2; ++k) \
;         acc[ai][bj][m][n] = __builtin_amdgcn_mfma_f32_16x16x32_bf16(Bt[n][k], At[m][k], acc[ai][bj][m][n], 0, 0, 0); __builtin_amdgcn_s_setprio(0); } while (0)
; #define PG8_WAIT_V(n) asm volatile("s_waitcnt vmcnt(" #n ")" ::: "memory")
; #define PG8_WAIT_L(n) asm volatile("s_waitcnt lgkmcnt(" #n ")" ::: "memory")
; #define PG8_BAR __builtin_amdgcn_s_barrier()
; #define PG8_SCHED __builtin_amdgcn_sched_barrier(0)
; template <class Epi, class Sched>
; __device__ __forceinline__ void gemm_phase(int wid_s, PG8_LAS unsigned char* lds, const Gemm g, const Sched& S, const Epi& E) {
;     ...
;             const bool last = (t == nt - 2);
;             const char* a1 = cA + (size_t)(t + 1) * kstep;
;             const char* a2 = last ? nA : cA + (size_t)(t + 2) * kstep; const char* b2 = last ? nB : cB + (size_t)(t + 2) * kstep;
;             const char* a3 = a2 + kstep; const char* b3 = b2 + kstep;
;             PG8_LDB(B0, 0, 0); PG8_LDB(B1, 0, 1); PG8_SCHED; PG8_LDA(At, 0, 0); PG8_STAGE(PG8_SA(1, 1), a1 + hstepA, voffA);
;             PG8_WAIT_V(8); PG8_WAIT_L(0); PG8_BAR; PG8_MMA(0, 0, At, B0); PG8_MMA(0, 1, At, B1); PG8_BAR; PG8_SCHED;
;             PG8_LDA(At, 0, 1); PG8_STAGE(PG8_SB(0, 0), b2, voffB); PG8_STAGE(PG8_SB(0, 1), b2 + hstepB, voffB); PG8_STAGE(PG8_SA(0, 0), a2, voffA);
;             PG8_WAIT_V(8); PG8_WAIT_L(0); PG8_BAR; PG8_MMA(1, 0, At, B0); PG8_MMA(1, 1, At, B1); PG8_BAR; PG8_SCHED;
.LBB0_1229:
	s_add_i32 s55, s26, 2
	s_add_u32 s56, s24, 0x80
	s_addc_u32 s27, s25, 0
	s_add_i32 s92, 0, 0x10000
	s_cmp_eq_u32 s48, s26
	s_cselect_b32 s27, s5, s27
	s_cselect_b32 s26, s4, s56
	v_add_u32_e32 v142, s92, v139
	s_cselect_b32 s57, s23, s54
	s_cselect_b32 s56, s22, s33
	s_add_i32 s94, 0, 0x14000
	ds_read_b128 v[154:157], v142
	ds_read_b128 v[158:161], v142 offset:1024
	ds_read_b128 v[162:165], v142 offset:2048
	ds_read_b128 v[186:189], v142 offset:3072
	v_add_u32_e32 v142, s94, v139
	ds_read_b128 v[190:193], v142
	ds_read_b128 v[194:197], v142 offset:1024
	ds_read_b128 v[198:201], v142 offset:2048
	ds_read_b128 v[202:205], v142 offset:3072
	v_lshl_add_u64 v[142:143], s[24:25], 0, v[136:137]
	s_add_i32 m0, s36, 0xc000
	ds_read_b128 v[206:209], v141
	ds_read_b128 v[210:213], v141 offset:1024
	ds_read_b128 v[214:217], v141 offset:2048
	ds_read_b128 v[218:221], v141 offset:3072
	ds_read_b128 v[222:225], v141 offset:4096
	ds_read_b128 v[226:229], v141 offset:5120
	ds_read_b128 v[230:233], v141 offset:6144
	ds_read_b128 v[234:237], v141 offset:7168
	global_load_lds_dwordx4 v[142:143], off
	v_lshl_add_u64 v[142:143], s[24:25], 0, v[134:135]
	s_add_i32 m0, s36, 0xe000
	s_nop 0
	global_load_lds_dwordx4 v[142:143], off
	s_waitcnt vmcnt(8)
	s_waitcnt lgkmcnt(0)
	s_barrier
	s_waitcnt lgkmcnt(0)
	v_mfma_f32_16x16x32_bf16 v[120:123], v[154:157], v[206:209], v[120:123]
	v_mfma_f32_16x16x32_bf16 v[124:127], v[162:165], v[206:209], v[124:127]
	v_mfma_f32_16x16x32_bf16 v[108:111], v[154:157], v[214:217], v[108:111]
	v_mfma_f32_16x16x32_bf16 v[104:107], v[162:165], v[214:217], v[104:107]
	v_mfma_f32_16x16x32_bf16 v[92:95], v[154:157], v[222:225], v[92:95]
	v_mfma_f32_16x16x32_bf16 v[88:91], v[162:165], v[222:225], v[88:91]
	v_mfma_f32_16x16x32_bf16 v[76:79], v[154:157], v[230:233], v[76:79]
	v_mfma_f32_16x16x32_bf16 v[72:75], v[162:165], v[230:233], v[72:75]
	v_mfma_f32_16x16x32_bf16 v[120:123], v[158:161], v[210:213], v[120:123]
	v_mfma_f32_16x16x32_bf16 v[124:127], v[186:189], v[210:213], v[124:127]
	v_mfma_f32_16x16x32_bf16 v[108:111], v[158:161], v[218:221], v[108:111]
	v_mfma_f32_16x16x32_bf16 v[104:107], v[186:189], v[218:221], v[104:107]
	v_mfma_f32_16x16x32_bf16 v[92:95], v[158:161], v[226:229], v[92:95]
	v_mfma_f32_16x16x32_bf16 v[88:91], v[186:189], v[226:229], v[88:91]
	v_mfma_f32_16x16x32_bf16 v[76:79], v[158:161], v[234:237], v[76:79]
	v_mfma_f32_16x16x32_bf16 v[72:75], v[186:189], v[234:237], v[72:75]
	v_mfma_f32_16x16x32_bf16 v[116:119], v[190:193], v[206:209], v[116:119]
	v_mfma_f32_16x16x32_bf16 v[112:115], v[198:201], v[206:209], v[112:115]
	v_mfma_f32_16x16x32_bf16 v[100:103], v[190:193], v[214:217], v[100:103]
	v_mfma_f32_16x16x32_bf16 v[96:99], v[198:201], v[214:217], v[96:99]
	v_mfma_f32_16x16x32_bf16 v[84:87], v[190:193], v[222:225], v[84:87]
	v_mfma_f32_16x16x32_bf16 v[80:83], v[198:201], v[222:225], v[80:83]
	v_mfma_f32_16x16x32_bf16 v[68:71], v[190:193], v[230:233], v[68:71]
	v_mfma_f32_16x16x32_bf16 v[64:67], v[198:201], v[230:233], v[64:67]
	v_mfma_f32_16x16x32_bf16 v[116:119], v[194:197], v[210:213], v[116:119]
	v_mfma_f32_16x16x32_bf16 v[112:115], v[202:205], v[210:213], v[112:115]
	v_mfma_f32_16x16x32_bf16 v[100:103], v[194:197], v[218:221], v[100:103]
	v_mfma_f32_16x16x32_bf16 v[96:99], v[202:205], v[218:221], v[96:99]
	v_mfma_f32_16x16x32_bf16 v[84:87], v[194:197], v[226:229], v[84:87]
	v_mfma_f32_16x16x32_bf16 v[80:83], v[202:205], v[226:229], v[80:83]
	v_mfma_f32_16x16x32_bf16 v[68:71], v[194:197], v[234:237], v[68:71]
	v_mfma_f32_16x16x32_bf16 v[64:67], v[202:205], v[234:237], v[64:67]
	s_barrier
	s_add_i32 s92, s92, s34
	v_lshl_add_u64 v[142:143], s[56:57], 0, v[144:145]
	s_mov_b32 m0, s92
	ds_read_b128 v[206:209], v141 offset:16384
	ds_read_b128 v[210:213], v141 offset:17408
	ds_read_b128 v[214:217], v141 offset:18432
	ds_read_b128 v[218:221], v141 offset:19456
	ds_read_b128 v[222:225], v141 offset:20480
	ds_read_b128 v[226:229], v141 offset:21504
	ds_read_b128 v[230:233], v141 offset:22528
	ds_read_b128 v[234:237], v141 offset:23552
	global_load_lds_dwordx4 v[142:143], off
	s_add_i32 m0, s92, 0x2000
	v_lshl_add_u64 v[166:167], s[56:57], 0, v[128:129]
	s_add_u32 s56, s56, s8
	s_addc_u32 s57, s57, s9
	s_add_i32 s92, s94, s34
	global_load_lds_dwordx4 v[166:167], off
	v_lshl_add_u64 v[238:239], s[56:57], 0, v[144:145]
	s_mov_b32 m0, s92
	v_lshl_add_u64 v[240:241], s[56:57], 0, v[128:129]
	global_load_lds_dwordx4 v[238:239], off
	s_add_i32 m0, s92, 0x2000
	v_lshl_add_u64 v[242:243], s[26:27], 0, v[132:133]
	global_load_lds_dwordx4 v[240:241], off
	s_mov_b32 m0, s36
	v_lshl_add_u64 v[244:245], s[26:27], 0, v[130:131]
	global_load_lds_dwordx4 v[242:243], off
	s_mov_b32 m0, s37
	s_nop 0
	global_load_lds_dwordx4 v[244:245], off
	s_waitcnt vmcnt(8)
	s_waitcnt lgkmcnt(0)
	s_barrier
; #define PG8_STAGE(bufoff, gbase, voff) do { _Pragma("unroll") for (int _i = 0; _i < 2; ++_i) \
;         __builtin_amdgcn_global_load_lds((const unsigned*)((const char*)(gbase) + (voff)[_i]), (PG8_LAS unsigned*)(lds + (bufoff) + ldsw + _i * 8192), 16, 0, 0); } while (0)
; #define PG8_LDA(dst, b, h) do { _Pragma("unroll") for (int m = 0; m < 4; ++m) _Pragma("unroll") for (int k = 0; k < 2; ++k) dst[m][k] = *(const PG8_LAS bf16x8*)(lds + PG8_SA(b, h) + aoff + m * 2048 + k * 1024); } while (0)
; #define PG8_LDB(dst, b, h) do { _Pragma("unroll") for (int n = 0; n < 2; ++n) _Pragma("unroll") for (int k = 0; k < 2; ++k) dst[n][k] = *(const PG8_LAS bf16x8*)(lds + PG8_SB(b, h) + boff + n * 2048 + k * 1024); } while (0)
; #define PG8_MMA(ai, bj, At, Bt) do { __builtin_amdgcn_s_setprio(1); _Pragma("unroll") for (int m = 0; m < 4; ++m) _Pragma("unroll") for (int n = 0; n < 2; ++n) _Pragma("unroll") for (int k = 0; k < 2; ++k) \
;         acc[ai][bj][m][n] = __builtin_amdgcn_mfma_f32_16x16x32_bf16(Bt[n][k], At[m][k], acc[ai][bj][m][n], 0, 0, 0); __builtin_amdgcn_s_setprio(0); } while (0)
; #define PG8_WAIT_V(n) asm volatile("s_waitcnt vmcnt(" #n ")" ::: "memory")
; #define PG8_WAIT_L(n) asm volatile("s_waitcnt lgkmcnt(" #n ")" ::: "memory")
; #define PG8_BAR __builtin_amdgcn_s_barrier()
; #define PG8_SCHED __builtin_amdgcn_sched_barrier(0)
; template <class Epi, class Sched>
; __device__ __forceinline__ void gemm_phase(int wid_s, PG8_LAS unsigned char* lds, const Gemm g, const Sched& S, const Epi& E) {
;     ...
;             PG8_WAIT_V(8); PG8_WAIT_L(0); PG8_BAR; PG8_MMA(1, 0, At, B0); PG8_MMA(1, 1, At, B1); PG8_BAR; PG8_SCHED;
;             PG8_LDB(B0, 1, 0); PG8_LDB(B1, 1, 1); PG8_SCHED; PG8_LDA(At, 1, 0); PG8_STAGE(PG8_SA(0, 1), a2 + hstepA, voffA);
;             PG8_WAIT_V(8); PG8_WAIT_L(0); PG8_BAR; PG8_MMA(0, 0, At, B0); PG8_MMA(0, 1, At, B1); PG8_BAR; PG8_SCHED;
	s_waitcnt lgkmcnt(0)
	v_mfma_f32_16x16x32_bf16 v[60:63], v[154:157], v[206:209], v[60:63]
	v_mfma_f32_16x16x32_bf16 v[56:59], v[162:165], v[206:209], v[56:59]
	v_mfma_f32_16x16x32_bf16 v[44:47], v[154:157], v[214:217], v[44:47]
	v_mfma_f32_16x16x32_bf16 v[40:43], v[162:165], v[214:217], v[40:43]
	v_mfma_f32_16x16x32_bf16 v[28:31], v[154:157], v[222:225], v[28:31]
	v_mfma_f32_16x16x32_bf16 v[24:27], v[162:165], v[222:225], v[24:27]
	v_mfma_f32_16x16x32_bf16 v[12:15], v[154:157], v[230:233], v[12:15]
	v_mfma_f32_16x16x32_bf16 v[8:11], v[162:165], v[230:233], v[8:11]
	v_mfma_f32_16x16x32_bf16 v[60:63], v[158:161], v[210:213], v[60:63]
	v_mfma_f32_16x16x32_bf16 v[56:59], v[186:189], v[210:213], v[56:59]
	v_mfma_f32_16x16x32_bf16 v[44:47], v[158:161], v[218:221], v[44:47]
	v_mfma_f32_16x16x32_bf16 v[40:43], v[186:189], v[218:221], v[40:43]
	v_mfma_f32_16x16x32_bf16 v[28:31], v[158:161], v[226:229], v[28:31]
	v_mfma_f32_16x16x32_bf16 v[24:27], v[186:189], v[226:229], v[24:27]
	v_mfma_f32_16x16x32_bf16 v[12:15], v[158:161], v[234:237], v[12:15]
	v_mfma_f32_16x16x32_bf16 v[8:11], v[186:189], v[234:237], v[8:11]
	v_mfma_f32_16x16x32_bf16 v[52:55], v[190:193], v[206:209], v[52:55]
	v_mfma_f32_16x16x32_bf16 v[48:51], v[198:201], v[206:209], v[48:51]
	v_mfma_f32_16x16x32_bf16 v[36:39], v[190:193], v[214:217], v[36:39]
	v_mfma_f32_16x16x32_bf16 v[32:35], v[198:201], v[214:217], v[32:35]
	v_mfma_f32_16x16x32_bf16 v[20:23], v[190:193], v[222:225], v[20:23]
	v_mfma_f32_16x16x32_bf16 v[16:19], v[198:201], v[222:225], v[16:19]
	v_mfma_f32_16x16x32_bf16 v[4:7], v[190:193], v[230:233], v[4:7]
	v_mfma_f32_16x16x32_bf16 v[0:3], v[198:201], v[230:233], v[0:3]
	v_mfma_f32_16x16x32_bf16 v[52:55], v[194:197], v[210:213], v[52:55]
	v_mfma_f32_16x16x32_bf16 v[48:51], v[202:205], v[210:213], v[48:51]
	v_mfma_f32_16x16x32_bf16 v[36:39], v[194:197], v[218:221], v[36:39]
	v_mfma_f32_16x16x32_bf16 v[32:35], v[202:205], v[218:221], v[32:35]
	v_mfma_f32_16x16x32_bf16 v[20:23], v[194:197], v[226:229], v[20:23]
	v_mfma_f32_16x16x32_bf16 v[16:19], v[202:205], v[226:229], v[16:19]
	v_mfma_f32_16x16x32_bf16 v[4:7], v[194:197], v[234:237], v[4:7]
	v_mfma_f32_16x16x32_bf16 v[0:3], v[202:205], v[234:237], v[0:3]
	s_barrier
	s_add_i32 s56, 0, 0x18000
	v_add_u32_e32 v185, s56, v139
	s_add_i32 s57, 0, 0x1c000
	ds_read_b128 v[154:157], v185
	ds_read_b128 v[158:161], v185 offset:1024
	ds_read_b128 v[162:165], v185 offset:2048
	ds_read_b128 v[186:189], v185 offset:3072
	v_add_u32_e32 v185, s57, v139
	ds_read_b128 v[190:193], v185
	ds_read_b128 v[194:197], v185 offset:1024
	ds_read_b128 v[198:201], v185 offset:2048
	ds_read_b128 v[202:205], v185 offset:3072
	s_add_u32 s26, s26, s6
	s_addc_u32 s27, s27, s7
	s_mov_b32 m0, s39
	v_lshl_add_u64 v[246:247], s[26:27], 0, v[132:133]
	ds_read_b128 v[206:209], v141 offset:32768
	ds_read_b128 v[210:213], v141 offset:33792
	ds_read_b128 v[214:217], v141 offset:34816
	ds_read_b128 v[218:221], v141 offset:35840
	ds_read_b128 v[222:225], v141 offset:36864
	ds_read_b128 v[226:229], v141 offset:37888
	ds_read_b128 v[230:233], v141 offset:38912
	ds_read_b128 v[234:237], v141 offset:39936
	global_load_lds_dwordx4 v[246:247], off
	v_lshl_add_u64 v[246:247], s[26:27], 0, v[130:131]
	s_mov_b32 m0, s40
	s_nop 0
	global_load_lds_dwordx4 v[246:247], off
	s_waitcnt vmcnt(8)
	s_waitcnt lgkmcnt(0)
	s_barrier
	s_waitcnt lgkmcnt(0)
	v_mfma_f32_16x16x32_bf16 v[120:123], v[154:157], v[206:209], v[120:123]
	v_mfma_f32_16x16x32_bf16 v[124:127], v[162:165], v[206:209], v[124:127]
	v_mfma_f32_16x16x32_bf16 v[108:111], v[154:157], v[214:217], v[108:111]
	v_mfma_f32_16x16x32_bf16 v[104:107], v[162:165], v[214:217], v[104:107]
	v_mfma_f32_16x16x32_bf16 v[92:95], v[154:157], v[222:225], v[92:95]
	v_mfma_f32_16x16x32_bf16 v[88:91], v[162:165], v[222:225], v[88:91]
	v_mfma_f32_16x16x32_bf16 v[76:79], v[154:157], v[230:233], v[76:79]
	v_mfma_f32_16x16x32_bf16 v[72:75], v[162:165], v[230:233], v[72:75]
	v_mfma_f32_16x16x32_bf16 v[120:123], v[158:161], v[210:213], v[120:123]
	v_mfma_f32_16x16x32_bf16 v[124:127], v[186:189], v[210:213], v[124:127]
	v_mfma_f32_16x16x32_bf16 v[108:111], v[158:161], v[218:221], v[108:111]
	v_mfma_f32_16x16x32_bf16 v[104:107], v[186:189], v[218:221], v[104:107]
	v_mfma_f32_16x16x32_bf16 v[92:95], v[158:161], v[226:229], v[92:95]
	v_mfma_f32_16x16x32_bf16 v[88:91], v[186:189], v[226:229], v[88:91]
	v_mfma_f32_16x16x32_bf16 v[76:79], v[158:161], v[234:237], v[76:79]
	v_mfma_f32_16x16x32_bf16 v[72:75], v[186:189], v[234:237], v[72:75]
	v_mfma_f32_16x16x32_bf16 v[116:119], v[190:193], v[206:209], v[116:119]
	v_mfma_f32_16x16x32_bf16 v[112:115], v[198:201], v[206:209], v[112:115]
	v_mfma_f32_16x16x32_bf16 v[100:103], v[190:193], v[214:217], v[100:103]
	v_mfma_f32_16x16x32_bf16 v[96:99], v[198:201], v[214:217], v[96:99]
	v_mfma_f32_16x16x32_bf16 v[84:87], v[190:193], v[222:225], v[84:87]
	v_mfma_f32_16x16x32_bf16 v[80:83], v[198:201], v[222:225], v[80:83]
	v_mfma_f32_16x16x32_bf16 v[68:71], v[190:193], v[230:233], v[68:71]
	v_mfma_f32_16x16x32_bf16 v[64:67], v[198:201], v[230:233], v[64:67]
	v_mfma_f32_16x16x32_bf16 v[116:119], v[194:197], v[210:213], v[116:119]
	v_mfma_f32_16x16x32_bf16 v[112:115], v[202:205], v[210:213], v[112:115]
	v_mfma_f32_16x16x32_bf16 v[100:103], v[194:197], v[218:221], v[100:103]
	v_mfma_f32_16x16x32_bf16 v[96:99], v[202:205], v[218:221], v[96:99]
	v_mfma_f32_16x16x32_bf16 v[84:87], v[194:197], v[226:229], v[84:87]
	v_mfma_f32_16x16x32_bf16 v[80:83], v[202:205], v[226:229], v[80:83]
	v_mfma_f32_16x16x32_bf16 v[68:71], v[194:197], v[234:237], v[68:71]
	v_mfma_f32_16x16x32_bf16 v[64:67], v[202:205], v[234:237], v[64:67]
	s_barrier
; #define PG8_STAGE(bufoff, gbase, voff) do { _Pragma("unroll") for (int _i = 0; _i < 2; ++_i) \
;         __builtin_amdgcn_global_load_lds((const unsigned*)((const char*)(gbase) + (voff)[_i]), (PG8_LAS unsigned*)(lds + (bufoff) + ldsw + _i * 8192), 16, 0, 0); } while (0)
; #define PG8_LDA(dst, b, h) do { _Pragma("unroll") for (int m = 0; m < 4; ++m) _Pragma("unroll") for (int k = 0; k < 2; ++k) dst[m][k] = *(const PG8_LAS bf16x8*)(lds + PG8_SA(b, h) + aoff + m * 2048 + k * 1024); } while (0)
; #define PG8_MMA(ai, bj, At, Bt) do { __builtin_amdgcn_s_setprio(1); _Pragma("unroll") for (int m = 0; m < 4; ++m) _Pragma("unroll") for (int n = 0; n < 2; ++n) _Pragma("unroll") for (int k = 0; k < 2; ++k) \
;         acc[ai][bj][m][n] = __builtin_amdgcn_mfma_f32_16x16x32_bf16(Bt[n][k], At[m][k], acc[ai][bj][m][n], 0, 0, 0); __builtin_amdgcn_s_setprio(0); } while (0)
; #define PG8_WAIT_V(n) asm volatile("s_waitcnt vmcnt(" #n ")" ::: "memory")
; #define PG8_WAIT_L(n) asm volatile("s_waitcnt lgkmcnt(" #n ")" ::: "memory")
; #define PG8_BAR __builtin_amdgcn_s_barrier()
; #define PG8_SCHED __builtin_amdgcn_sched_barrier(0)
; template <class Epi, class Sched>
; __device__ __forceinline__ void gemm_phase(int wid_s, PG8_LAS unsigned char* lds, const Gemm g, const Sched& S, const Epi& E) {
;     ...
;             PG8_LDA(At, 1, 1); PG8_STAGE(PG8_SB(1, 0), b3, voffB); PG8_STAGE(PG8_SB(1, 1), b3 + hstepB, voffB); PG8_STAGE(PG8_SA(1, 0), a3, voffA);
;             PG8_WAIT_V(8); PG8_WAIT_L(0); PG8_BAR; PG8_MMA(1, 0, At, B0); PG8_MMA(1, 1, At, B1); PG8_BAR; PG8_SCHED;
;         }
	s_add_i32 s26, s56, s34
	v_lshl_add_u64 v[142:143], v[142:143], 0, s[96:97]
	s_mov_b32 m0, s26
	ds_read_b128 v[206:209], v141 offset:49152
	ds_read_b128 v[210:213], v141 offset:50176
	ds_read_b128 v[214:217], v141 offset:51200
	ds_read_b128 v[218:221], v141 offset:52224
	ds_read_b128 v[222:225], v141 offset:53248
	ds_read_b128 v[226:229], v141 offset:54272
	ds_read_b128 v[230:233], v141 offset:55296
	ds_read_b128 v[234:237], v141 offset:56320
	global_load_lds_dwordx4 v[142:143], off
	v_lshl_add_u64 v[142:143], v[166:167], 0, s[96:97]
	s_add_i32 m0, s26, 0x2000
	s_add_i32 s26, s57, s34
	global_load_lds_dwordx4 v[142:143], off
	v_lshl_add_u64 v[142:143], v[238:239], 0, s[96:97]
	s_mov_b32 m0, s26
	s_nop 0
	global_load_lds_dwordx4 v[142:143], off
	v_lshl_add_u64 v[142:143], v[240:241], 0, s[96:97]
	s_add_i32 m0, s26, 0x2000
	s_nop 0
	global_load_lds_dwordx4 v[142:143], off
	v_lshl_add_u64 v[142:143], v[242:243], 0, s[96:97]
	s_mov_b32 m0, s46
	s_nop 0
	global_load_lds_dwordx4 v[142:143], off
	v_lshl_add_u64 v[142:143], v[244:245], 0, s[96:97]
	s_mov_b32 m0, s47
	s_nop 0
	global_load_lds_dwordx4 v[142:143], off
	s_waitcnt vmcnt(8)
	s_waitcnt lgkmcnt(0)
	s_barrier
	s_waitcnt lgkmcnt(0)
	v_mfma_f32_16x16x32_bf16 v[60:63], v[154:157], v[206:209], v[60:63]
	v_mfma_f32_16x16x32_bf16 v[56:59], v[162:165], v[206:209], v[56:59]
	v_mfma_f32_16x16x32_bf16 v[44:47], v[154:157], v[214:217], v[44:47]
	v_mfma_f32_16x16x32_bf16 v[40:43], v[162:165], v[214:217], v[40:43]
	v_mfma_f32_16x16x32_bf16 v[28:31], v[154:157], v[222:225], v[28:31]
	v_mfma_f32_16x16x32_bf16 v[24:27], v[162:165], v[222:225], v[24:27]
	v_mfma_f32_16x16x32_bf16 v[12:15], v[154:157], v[230:233], v[12:15]
	v_mfma_f32_16x16x32_bf16 v[8:11], v[162:165], v[230:233], v[8:11]
	v_mfma_f32_16x16x32_bf16 v[60:63], v[158:161], v[210:213], v[60:63]
	v_mfma_f32_16x16x32_bf16 v[56:59], v[186:189], v[210:213], v[56:59]
	v_mfma_f32_16x16x32_bf16 v[44:47], v[158:161], v[218:221], v[44:47]
	v_mfma_f32_16x16x32_bf16 v[40:43], v[186:189], v[218:221], v[40:43]
	v_mfma_f32_16x16x32_bf16 v[28:31], v[158:161], v[226:229], v[28:31]
	v_mfma_f32_16x16x32_bf16 v[24:27], v[186:189], v[226:229], v[24:27]
	v_mfma_f32_16x16x32_bf16 v[12:15], v[158:161], v[234:237], v[12:15]
	v_mfma_f32_16x16x32_bf16 v[8:11], v[186:189], v[234:237], v[8:11]
	v_mfma_f32_16x16x32_bf16 v[52:55], v[190:193], v[206:209], v[52:55]
	v_mfma_f32_16x16x32_bf16 v[48:51], v[198:201], v[206:209], v[48:51]
	v_mfma_f32_16x16x32_bf16 v[36:39], v[190:193], v[214:217], v[36:39]
	v_mfma_f32_16x16x32_bf16 v[32:35], v[198:201], v[214:217], v[32:35]
	v_mfma_f32_16x16x32_bf16 v[20:23], v[190:193], v[222:225], v[20:23]
	v_mfma_f32_16x16x32_bf16 v[16:19], v[198:201], v[222:225], v[16:19]
	v_mfma_f32_16x16x32_bf16 v[4:7], v[190:193], v[230:233], v[4:7]
	v_mfma_f32_16x16x32_bf16 v[0:3], v[198:201], v[230:233], v[0:3]
	v_mfma_f32_16x16x32_bf16 v[52:55], v[194:197], v[210:213], v[52:55]
	v_mfma_f32_16x16x32_bf16 v[48:51], v[202:205], v[210:213], v[48:51]
	v_mfma_f32_16x16x32_bf16 v[36:39], v[194:197], v[218:221], v[36:39]
	v_mfma_f32_16x16x32_bf16 v[32:35], v[202:205], v[218:221], v[32:35]
	v_mfma_f32_16x16x32_bf16 v[20:23], v[194:197], v[226:229], v[20:23]
	v_mfma_f32_16x16x32_bf16 v[16:19], v[202:205], v[226:229], v[16:19]
	v_mfma_f32_16x16x32_bf16 v[4:7], v[194:197], v[234:237], v[4:7]
	v_mfma_f32_16x16x32_bf16 v[0:3], v[202:205], v[234:237], v[0:3]
	s_barrier
	s_add_u32 s33, s33, 0x100
	s_addc_u32 s54, s54, 0
	s_add_u32 s24, s24, 0x100
	s_addc_u32 s25, s25, 0
	s_cmp_ge_i32 s55, s41
	s_mov_b32 s26, s55
	s_cbranch_scc0 .LBB0_1229
	v_readlane_b32 s54, v254, 52
	v_readlane_b32 s55, v254, 53
	v_readlane_b32 s92, v254, 54
	v_readlane_b32 s94, v254, 55
	s_movk_i32 s33, 0xc00

; #define PG8_STAGE(bufoff, gbase, voff) do { _Pragma("unroll") for (int _i = 0; _i < 2; ++_i) \
;         __builtin_amdgcn_global_load_lds((const unsigned*)((const char*)(gbase) + (voff)[_i]), (PG8_LAS unsigned*)(lds + (bufoff) + ldsw + _i * 8192), 16, 0, 0); } while (0)
; #define PG8_LDA(dst, b, h) do { _Pragma("unroll") for (int m = 0; m < 4; ++m) _Pragma("unroll") for (int k = 0; k < 2; ++k) dst[m][k] = *(const PG8_LAS bf16x8*)(lds + PG8_SA(b, h) + aoff + m * 2048 + k * 1024); } while (0)
; #define PG8_LDB(dst, b, h) do { _Pragma("unroll") for (int n = 0; n < 2; ++n) _Pragma("unroll") for (int k = 0; k < 2; ++k) dst[n][k] = *(const PG8_LAS bf16x8*)(lds + PG8_SB(b, h) + boff + n * 2048 + k * 1024); } while (0)
; #define PG8_MMA(ai, bj, At, Bt) do { __builtin_amdgcn_s_setprio(1); _Pragma("unroll") for (int m = 0; m < 4; ++m) _Pragma("unroll") for (int n = 0; n < 2; ++n) _Pragma("unroll") for (int k = 0; k < 2; ++k) \
;         acc[ai][bj][m][n] = __builtin_amdgcn_mfma_f32_16x16x32_bf16(Bt[n][k], At[m][k], acc[ai][bj][m][n], 0, 0, 0); __builtin_amdgcn_s_setprio(0); } while (0)
; #define PG8_WAIT_V(n) asm volatile("s_waitcnt vmcnt(" #n ")" ::: "memory")
; #define PG8_WAIT_L(n) asm volatile("s_waitcnt lgkmcnt(" #n ")" ::: "memory")
; #define PG8_BAR __builtin_amdgcn_s_barrier()
; #define PG8_SCHED __builtin_amdgcn_sched_barrier(0)
; template <class Epi, class Sched>
; __device__ __forceinline__ void gemm_phase(int wid_s, PG8_LAS unsigned char* lds, const Gemm g, const Sched& S, const Epi& E) {
;     ...
;             const bool last = (t == nt - 2);
;             const char* a1 = cA + (size_t)(t + 1) * kstep;
;             const char* a2 = last ? nA : cA + (size_t)(t + 2) * kstep; const char* b2 = last ? nB : cB + (size_t)(t + 2) * kstep;
;             const char* a3 = a2 + kstep; const char* b3 = b2 + kstep;
;             PG8_LDB(B0, 0, 0); PG8_LDB(B1, 0, 1); PG8_SCHED; PG8_LDA(At, 0, 0); PG8_STAGE(PG8_SA(1, 1), a1 + hstepA, voffA);
;             PG8_WAIT_V(8); PG8_WAIT_L(0); PG8_BAR; PG8_MMA(0, 0, At, B0); PG8_MMA(0, 1, At, B1); PG8_BAR; PG8_SCHED;
;             PG8_LDA(At, 0, 1); PG8_STAGE(PG8_SB(0, 0), b2, voffB); PG8_STAGE(PG8_SB(0, 1), b2 + hstepB, voffB); PG8_STAGE(PG8_SA(0, 0), a2, voffA);
;             PG8_WAIT_V(8); PG8_WAIT_L(0); PG8_BAR; PG8_MMA(1, 0, At, B0); PG8_MMA(1, 1, At, B1); PG8_BAR; PG8_SCHED;
.LBB0_1366:
	s_add_i32 s55, s28, 2
	s_add_u32 s92, s26, 0x80
	s_addc_u32 s29, s27, 0
	s_add_i32 vcc_lo, 0, 0x10000
	s_cmp_eq_u32 s47, s28
	s_cselect_b32 s29, s23, s29
	s_cselect_b32 s28, s22, s92
	v_add_u32_e32 v166, vcc_lo, v141
	s_cselect_b32 s95, s25, s54
	s_cselect_b32 s94, s24, s33
	s_add_i32 s92, 0, 0x14000
	ds_read_b128 v[154:157], v166
	ds_read_b128 v[158:161], v166 offset:1024
	ds_read_b128 v[162:165], v166 offset:2048
	ds_read_b128 v[186:189], v166 offset:3072
	v_add_u32_e32 v166, s92, v141
	ds_read_b128 v[190:193], v166
	ds_read_b128 v[194:197], v166 offset:1024
	ds_read_b128 v[198:201], v166 offset:2048
	ds_read_b128 v[202:205], v166 offset:3072
	v_lshl_add_u64 v[166:167], s[26:27], 0, v[136:137]
	s_add_i32 m0, s37, 0xc000
	ds_read_b128 v[206:209], v143
	ds_read_b128 v[210:213], v143 offset:1024
	ds_read_b128 v[214:217], v143 offset:2048
	ds_read_b128 v[218:221], v143 offset:3072
	ds_read_b128 v[222:225], v143 offset:4096
	ds_read_b128 v[226:229], v143 offset:5120
	ds_read_b128 v[230:233], v143 offset:6144
	ds_read_b128 v[234:237], v143 offset:7168
	global_load_lds_dwordx4 v[166:167], off
	v_lshl_add_u64 v[166:167], s[26:27], 0, v[134:135]
	s_add_i32 m0, s37, 0xe000
	s_nop 0
	global_load_lds_dwordx4 v[166:167], off
	s_waitcnt vmcnt(8)
	s_waitcnt lgkmcnt(0)
	s_barrier
	s_waitcnt lgkmcnt(0)
	v_mfma_f32_16x16x32_bf16 v[120:123], v[154:157], v[206:209], v[120:123]
	v_mfma_f32_16x16x32_bf16 v[124:127], v[162:165], v[206:209], v[124:127]
	v_mfma_f32_16x16x32_bf16 v[108:111], v[154:157], v[214:217], v[108:111]
	v_mfma_f32_16x16x32_bf16 v[104:107], v[162:165], v[214:217], v[104:107]
	v_mfma_f32_16x16x32_bf16 v[92:95], v[154:157], v[222:225], v[92:95]
	v_mfma_f32_16x16x32_bf16 v[88:91], v[162:165], v[222:225], v[88:91]
	v_mfma_f32_16x16x32_bf16 v[76:79], v[154:157], v[230:233], v[76:79]
	v_mfma_f32_16x16x32_bf16 v[72:75], v[162:165], v[230:233], v[72:75]
	v_mfma_f32_16x16x32_bf16 v[120:123], v[158:161], v[210:213], v[120:123]
	v_mfma_f32_16x16x32_bf16 v[124:127], v[186:189], v[210:213], v[124:127]
	v_mfma_f32_16x16x32_bf16 v[108:111], v[158:161], v[218:221], v[108:111]
	v_mfma_f32_16x16x32_bf16 v[104:107], v[186:189], v[218:221], v[104:107]
	v_mfma_f32_16x16x32_bf16 v[92:95], v[158:161], v[226:229], v[92:95]
	v_mfma_f32_16x16x32_bf16 v[88:91], v[186:189], v[226:229], v[88:91]
	v_mfma_f32_16x16x32_bf16 v[76:79], v[158:161], v[234:237], v[76:79]
	v_mfma_f32_16x16x32_bf16 v[72:75], v[186:189], v[234:237], v[72:75]
	v_mfma_f32_16x16x32_bf16 v[116:119], v[190:193], v[206:209], v[116:119]
	v_mfma_f32_16x16x32_bf16 v[112:115], v[198:201], v[206:209], v[112:115]
	v_mfma_f32_16x16x32_bf16 v[100:103], v[190:193], v[214:217], v[100:103]
	v_mfma_f32_16x16x32_bf16 v[96:99], v[198:201], v[214:217], v[96:99]
	v_mfma_f32_16x16x32_bf16 v[84:87], v[190:193], v[222:225], v[84:87]
	v_mfma_f32_16x16x32_bf16 v[80:83], v[198:201], v[222:225], v[80:83]
	v_mfma_f32_16x16x32_bf16 v[68:71], v[190:193], v[230:233], v[68:71]
	v_mfma_f32_16x16x32_bf16 v[64:67], v[198:201], v[230:233], v[64:67]
	v_mfma_f32_16x16x32_bf16 v[116:119], v[194:197], v[210:213], v[116:119]
	v_mfma_f32_16x16x32_bf16 v[112:115], v[202:205], v[210:213], v[112:115]
	v_mfma_f32_16x16x32_bf16 v[100:103], v[194:197], v[218:221], v[100:103]
	v_mfma_f32_16x16x32_bf16 v[96:99], v[202:205], v[218:221], v[96:99]
	v_mfma_f32_16x16x32_bf16 v[84:87], v[194:197], v[226:229], v[84:87]
	v_mfma_f32_16x16x32_bf16 v[80:83], v[202:205], v[226:229], v[80:83]
	v_mfma_f32_16x16x32_bf16 v[68:71], v[194:197], v[234:237], v[68:71]
	v_mfma_f32_16x16x32_bf16 v[64:67], v[202:205], v[234:237], v[64:67]
	s_barrier
	s_add_i32 vcc_lo, vcc_lo, s35
	v_lshl_add_u64 v[166:167], s[94:95], 0, v[144:145]
	s_mov_b32 m0, vcc_lo
	ds_read_b128 v[206:209], v143 offset:16384
	ds_read_b128 v[210:213], v143 offset:17408
	ds_read_b128 v[214:217], v143 offset:18432
	ds_read_b128 v[218:221], v143 offset:19456
	ds_read_b128 v[222:225], v143 offset:20480
	ds_read_b128 v[226:229], v143 offset:21504
	ds_read_b128 v[230:233], v143 offset:22528
	ds_read_b128 v[234:237], v143 offset:23552
	global_load_lds_dwordx4 v[166:167], off
	s_add_i32 m0, vcc_lo, 0x2000
	v_lshl_add_u64 v[238:239], s[94:95], 0, v[128:129]
	s_add_u32 s94, s94, s6
	s_addc_u32 s95, s95, s7
	s_add_i32 s92, s92, s35
	global_load_lds_dwordx4 v[238:239], off
	v_lshl_add_u64 v[240:241], s[94:95], 0, v[144:145]
	s_mov_b32 m0, s92
	v_lshl_add_u64 v[242:243], s[94:95], 0, v[128:129]
	global_load_lds_dwordx4 v[240:241], off
	s_add_i32 m0, s92, 0x2000
	v_lshl_add_u64 v[244:245], s[28:29], 0, v[132:133]
	global_load_lds_dwordx4 v[242:243], off
	s_mov_b32 m0, s37
	v_lshl_add_u64 v[246:247], s[28:29], 0, v[130:131]
	global_load_lds_dwordx4 v[244:245], off
	s_mov_b32 m0, s39
	s_nop 0
	global_load_lds_dwordx4 v[246:247], off
	s_waitcnt vmcnt(8)
	s_waitcnt lgkmcnt(0)
	s_barrier
; #define PG8_STAGE(bufoff, gbase, voff) do { _Pragma("unroll") for (int _i = 0; _i < 2; ++_i) \
;         __builtin_amdgcn_global_load_lds((const unsigned*)((const char*)(gbase) + (voff)[_i]), (PG8_LAS unsigned*)(lds + (bufoff) + ldsw + _i * 8192), 16, 0, 0); } while (0)
; #define PG8_LDA(dst, b, h) do { _Pragma("unroll") for (int m = 0; m < 4; ++m) _Pragma("unroll") for (int k = 0; k < 2; ++k) dst[m][k] = *(const PG8_LAS bf16x8*)(lds + PG8_SA(b, h) + aoff + m * 2048 + k * 1024); } while (0)
; #define PG8_LDB(dst, b, h) do { _Pragma("unroll") for (int n = 0; n < 2; ++n) _Pragma("unroll") for (int k = 0; k < 2; ++k) dst[n][k] = *(const PG8_LAS bf16x8*)(lds + PG8_SB(b, h) + boff + n * 2048 + k * 1024); } while (0)
; #define PG8_MMA(ai, bj, At, Bt) do { __builtin_amdgcn_s_setprio(1); _Pragma("unroll") for (int m = 0; m < 4; ++m) _Pragma("unroll") for (int n = 0; n < 2; ++n) _Pragma("unroll") for (int k = 0; k < 2; ++k) \
;         acc[ai][bj][m][n] = __builtin_amdgcn_mfma_f32_16x16x32_bf16(Bt[n][k], At[m][k], acc[ai][bj][m][n], 0, 0, 0); __builtin_amdgcn_s_setprio(0); } while (0)
; #define PG8_WAIT_V(n) asm volatile("s_waitcnt vmcnt(" #n ")" ::: "memory")
; #define PG8_WAIT_L(n) asm volatile("s_waitcnt lgkmcnt(" #n ")" ::: "memory")
; #define PG8_BAR __builtin_amdgcn_s_barrier()
; #define PG8_SCHED __builtin_amdgcn_sched_barrier(0)
; template <class Epi, class Sched>
; __device__ __forceinline__ void gemm_phase(int wid_s, PG8_LAS unsigned char* lds, const Gemm g, const Sched& S, const Epi& E) {
;     ...
;             PG8_WAIT_V(8); PG8_WAIT_L(0); PG8_BAR; PG8_MMA(1, 0, At, B0); PG8_MMA(1, 1, At, B1); PG8_BAR; PG8_SCHED;
;             PG8_LDB(B0, 1, 0); PG8_LDB(B1, 1, 1); PG8_SCHED; PG8_LDA(At, 1, 0); PG8_STAGE(PG8_SA(0, 1), a2 + hstepA, voffA);
;             PG8_WAIT_V(8); PG8_WAIT_L(0); PG8_BAR; PG8_MMA(0, 0, At, B0); PG8_MMA(0, 1, At, B1); PG8_BAR; PG8_SCHED;
	s_waitcnt lgkmcnt(0)
	v_mfma_f32_16x16x32_bf16 v[60:63], v[154:157], v[206:209], v[60:63]
	v_mfma_f32_16x16x32_bf16 v[56:59], v[162:165], v[206:209], v[56:59]
	v_mfma_f32_16x16x32_bf16 v[44:47], v[154:157], v[214:217], v[44:47]
	v_mfma_f32_16x16x32_bf16 v[40:43], v[162:165], v[214:217], v[40:43]
	v_mfma_f32_16x16x32_bf16 v[28:31], v[154:157], v[222:225], v[28:31]
	v_mfma_f32_16x16x32_bf16 v[24:27], v[162:165], v[222:225], v[24:27]
	v_mfma_f32_16x16x32_bf16 v[12:15], v[154:157], v[230:233], v[12:15]
	v_mfma_f32_16x16x32_bf16 v[8:11], v[162:165], v[230:233], v[8:11]
	v_mfma_f32_16x16x32_bf16 v[60:63], v[158:161], v[210:213], v[60:63]
	v_mfma_f32_16x16x32_bf16 v[56:59], v[186:189], v[210:213], v[56:59]
	v_mfma_f32_16x16x32_bf16 v[44:47], v[158:161], v[218:221], v[44:47]
	v_mfma_f32_16x16x32_bf16 v[40:43], v[186:189], v[218:221], v[40:43]
	v_mfma_f32_16x16x32_bf16 v[28:31], v[158:161], v[226:229], v[28:31]
	v_mfma_f32_16x16x32_bf16 v[24:27], v[186:189], v[226:229], v[24:27]
	v_mfma_f32_16x16x32_bf16 v[12:15], v[158:161], v[234:237], v[12:15]
	v_mfma_f32_16x16x32_bf16 v[8:11], v[186:189], v[234:237], v[8:11]
	v_mfma_f32_16x16x32_bf16 v[52:55], v[190:193], v[206:209], v[52:55]
	v_mfma_f32_16x16x32_bf16 v[48:51], v[198:201], v[206:209], v[48:51]
	v_mfma_f32_16x16x32_bf16 v[36:39], v[190:193], v[214:217], v[36:39]
	v_mfma_f32_16x16x32_bf16 v[32:35], v[198:201], v[214:217], v[32:35]
	v_mfma_f32_16x16x32_bf16 v[20:23], v[190:193], v[222:225], v[20:23]
	v_mfma_f32_16x16x32_bf16 v[16:19], v[198:201], v[222:225], v[16:19]
	v_mfma_f32_16x16x32_bf16 v[4:7], v[190:193], v[230:233], v[4:7]
	v_mfma_f32_16x16x32_bf16 v[0:3], v[198:201], v[230:233], v[0:3]
	v_mfma_f32_16x16x32_bf16 v[52:55], v[194:197], v[210:213], v[52:55]
	v_mfma_f32_16x16x32_bf16 v[48:51], v[202:205], v[210:213], v[48:51]
	v_mfma_f32_16x16x32_bf16 v[36:39], v[194:197], v[218:221], v[36:39]
	v_mfma_f32_16x16x32_bf16 v[32:35], v[202:205], v[218:221], v[32:35]
	v_mfma_f32_16x16x32_bf16 v[20:23], v[194:197], v[226:229], v[20:23]
	v_mfma_f32_16x16x32_bf16 v[16:19], v[202:205], v[226:229], v[16:19]
	v_mfma_f32_16x16x32_bf16 v[4:7], v[194:197], v[234:237], v[4:7]
	v_mfma_f32_16x16x32_bf16 v[0:3], v[202:205], v[234:237], v[0:3]
	s_barrier
	s_add_i32 s92, 0, 0x18000
	v_add_u32_e32 v185, s92, v141
	s_add_i32 s94, 0, 0x1c000
	ds_read_b128 v[154:157], v185
	ds_read_b128 v[158:161], v185 offset:1024
	ds_read_b128 v[162:165], v185 offset:2048
	ds_read_b128 v[186:189], v185 offset:3072
	v_add_u32_e32 v185, s94, v141
	ds_read_b128 v[190:193], v185
	ds_read_b128 v[194:197], v185 offset:1024
	ds_read_b128 v[198:201], v185 offset:2048
	ds_read_b128 v[202:205], v185 offset:3072
	s_add_u32 s28, s28, s4
	s_addc_u32 s29, s29, s5
	s_mov_b32 m0, s40
	v_lshl_add_u64 v[248:249], s[28:29], 0, v[132:133]
	ds_read_b128 v[206:209], v143 offset:32768
	ds_read_b128 v[210:213], v143 offset:33792
	ds_read_b128 v[214:217], v143 offset:34816
	ds_read_b128 v[218:221], v143 offset:35840
	ds_read_b128 v[222:225], v143 offset:36864
	ds_read_b128 v[226:229], v143 offset:37888
	ds_read_b128 v[230:233], v143 offset:38912
	ds_read_b128 v[234:237], v143 offset:39936
	global_load_lds_dwordx4 v[248:249], off
	v_lshl_add_u64 v[248:249], s[28:29], 0, v[130:131]
	s_mov_b32 m0, s41
	s_nop 0
	global_load_lds_dwordx4 v[248:249], off
	s_waitcnt vmcnt(8)
	s_waitcnt lgkmcnt(0)
	s_barrier
	s_waitcnt lgkmcnt(0)
	v_mfma_f32_16x16x32_bf16 v[120:123], v[154:157], v[206:209], v[120:123]
	v_mfma_f32_16x16x32_bf16 v[124:127], v[162:165], v[206:209], v[124:127]
	v_mfma_f32_16x16x32_bf16 v[108:111], v[154:157], v[214:217], v[108:111]
	v_mfma_f32_16x16x32_bf16 v[104:107], v[162:165], v[214:217], v[104:107]
	v_mfma_f32_16x16x32_bf16 v[92:95], v[154:157], v[222:225], v[92:95]
	v_mfma_f32_16x16x32_bf16 v[88:91], v[162:165], v[222:225], v[88:91]
	v_mfma_f32_16x16x32_bf16 v[76:79], v[154:157], v[230:233], v[76:79]
	v_mfma_f32_16x16x32_bf16 v[72:75], v[162:165], v[230:233], v[72:75]
	v_mfma_f32_16x16x32_bf16 v[120:123], v[158:161], v[210:213], v[120:123]
	v_mfma_f32_16x16x32_bf16 v[124:127], v[186:189], v[210:213], v[124:127]
	v_mfma_f32_16x16x32_bf16 v[108:111], v[158:161], v[218:221], v[108:111]
	v_mfma_f32_16x16x32_bf16 v[104:107], v[186:189], v[218:221], v[104:107]
	v_mfma_f32_16x16x32_bf16 v[92:95], v[158:161], v[226:229], v[92:95]
	v_mfma_f32_16x16x32_bf16 v[88:91], v[186:189], v[226:229], v[88:91]
	v_mfma_f32_16x16x32_bf16 v[76:79], v[158:161], v[234:237], v[76:79]
	v_mfma_f32_16x16x32_bf16 v[72:75], v[186:189], v[234:237], v[72:75]
	v_mfma_f32_16x16x32_bf16 v[116:119], v[190:193], v[206:209], v[116:119]
	v_mfma_f32_16x16x32_bf16 v[112:115], v[198:201], v[206:209], v[112:115]
	v_mfma_f32_16x16x32_bf16 v[100:103], v[190:193], v[214:217], v[100:103]
	v_mfma_f32_16x16x32_bf16 v[96:99], v[198:201], v[214:217], v[96:99]
	v_mfma_f32_16x16x32_bf16 v[84:87], v[190:193], v[222:225], v[84:87]
	v_mfma_f32_16x16x32_bf16 v[80:83], v[198:201], v[222:225], v[80:83]
	v_mfma_f32_16x16x32_bf16 v[68:71], v[190:193], v[230:233], v[68:71]
	v_mfma_f32_16x16x32_bf16 v[64:67], v[198:201], v[230:233], v[64:67]
	v_mfma_f32_16x16x32_bf16 v[116:119], v[194:197], v[210:213], v[116:119]
	v_mfma_f32_16x16x32_bf16 v[112:115], v[202:205], v[210:213], v[112:115]
	v_mfma_f32_16x16x32_bf16 v[100:103], v[194:197], v[218:221], v[100:103]
	v_mfma_f32_16x16x32_bf16 v[96:99], v[202:205], v[218:221], v[96:99]
	v_mfma_f32_16x16x32_bf16 v[84:87], v[194:197], v[226:229], v[84:87]
	v_mfma_f32_16x16x32_bf16 v[80:83], v[202:205], v[226:229], v[80:83]
	v_mfma_f32_16x16x32_bf16 v[68:71], v[194:197], v[234:237], v[68:71]
	v_mfma_f32_16x16x32_bf16 v[64:67], v[202:205], v[234:237], v[64:67]
	s_barrier
; #define PG8_STAGE(bufoff, gbase, voff) do { _Pragma("unroll") for (int _i = 0; _i < 2; ++_i) \
;         __builtin_amdgcn_global_load_lds((const unsigned*)((const char*)(gbase) + (voff)[_i]), (PG8_LAS unsigned*)(lds + (bufoff) + ldsw + _i * 8192), 16, 0, 0); } while (0)
; #define PG8_LDA(dst, b, h) do { _Pragma("unroll") for (int m = 0; m < 4; ++m) _Pragma("unroll") for (int k = 0; k < 2; ++k) dst[m][k] = *(const PG8_LAS bf16x8*)(lds + PG8_SA(b, h) + aoff + m * 2048 + k * 1024); } while (0)
; #define PG8_MMA(ai, bj, At, Bt) do { __builtin_amdgcn_s_setprio(1); _Pragma("unroll") for (int m = 0; m < 4; ++m) _Pragma("unroll") for (int n = 0; n < 2; ++n) _Pragma("unroll") for (int k = 0; k < 2; ++k) \
;         acc[ai][bj][m][n] = __builtin_amdgcn_mfma_f32_16x16x32_bf16(Bt[n][k], At[m][k], acc[ai][bj][m][n], 0, 0, 0); __builtin_amdgcn_s_setprio(0); } while (0)
; #define PG8_WAIT_V(n) asm volatile("s_waitcnt vmcnt(" #n ")" ::: "memory")
; #define PG8_WAIT_L(n) asm volatile("s_waitcnt lgkmcnt(" #n ")" ::: "memory")
; #define PG8_BAR __builtin_amdgcn_s_barrier()
; #define PG8_SCHED __builtin_amdgcn_sched_barrier(0)
; template <class Epi, class Sched>
; __device__ __forceinline__ void gemm_phase(int wid_s, PG8_LAS unsigned char* lds, const Gemm g, const Sched& S, const Epi& E) {
;     ...
;             PG8_LDA(At, 1, 1); PG8_STAGE(PG8_SB(1, 0), b3, voffB); PG8_STAGE(PG8_SB(1, 1), b3 + hstepB, voffB); PG8_STAGE(PG8_SA(1, 0), a3, voffA);
;             PG8_WAIT_V(8); PG8_WAIT_L(0); PG8_BAR; PG8_MMA(1, 0, At, B0); PG8_MMA(1, 1, At, B1); PG8_BAR; PG8_SCHED;
;         }
	s_add_i32 s28, s92, s35
	v_lshl_add_u64 v[166:167], v[166:167], 0, s[96:97]
	s_mov_b32 m0, s28
	ds_read_b128 v[206:209], v143 offset:49152
	ds_read_b128 v[210:213], v143 offset:50176
	ds_read_b128 v[214:217], v143 offset:51200
	ds_read_b128 v[218:221], v143 offset:52224
	ds_read_b128 v[222:225], v143 offset:53248
	ds_read_b128 v[226:229], v143 offset:54272
	ds_read_b128 v[230:233], v143 offset:55296
	ds_read_b128 v[234:237], v143 offset:56320
	global_load_lds_dwordx4 v[166:167], off
	v_lshl_add_u64 v[166:167], v[238:239], 0, s[96:97]
	s_add_i32 m0, s28, 0x2000
	s_add_i32 s28, s94, s35
	global_load_lds_dwordx4 v[166:167], off
	v_lshl_add_u64 v[166:167], v[240:241], 0, s[96:97]
	s_mov_b32 m0, s28
	s_nop 0
	global_load_lds_dwordx4 v[166:167], off
	v_lshl_add_u64 v[166:167], v[242:243], 0, s[96:97]
	s_add_i32 m0, s28, 0x2000
	s_nop 0
	global_load_lds_dwordx4 v[166:167], off
	v_lshl_add_u64 v[166:167], v[244:245], 0, s[96:97]
	s_mov_b32 m0, s45
	s_nop 0
	global_load_lds_dwordx4 v[166:167], off
	v_lshl_add_u64 v[166:167], v[246:247], 0, s[96:97]
	s_mov_b32 m0, s46
	s_nop 0
	global_load_lds_dwordx4 v[166:167], off
	s_waitcnt vmcnt(8)
	s_waitcnt lgkmcnt(0)
	s_barrier
	s_waitcnt lgkmcnt(0)
	v_mfma_f32_16x16x32_bf16 v[60:63], v[154:157], v[206:209], v[60:63]
	v_mfma_f32_16x16x32_bf16 v[56:59], v[162:165], v[206:209], v[56:59]
	v_mfma_f32_16x16x32_bf16 v[44:47], v[154:157], v[214:217], v[44:47]
	v_mfma_f32_16x16x32_bf16 v[40:43], v[162:165], v[214:217], v[40:43]
	v_mfma_f32_16x16x32_bf16 v[28:31], v[154:157], v[222:225], v[28:31]
	v_mfma_f32_16x16x32_bf16 v[24:27], v[162:165], v[222:225], v[24:27]
	v_mfma_f32_16x16x32_bf16 v[12:15], v[154:157], v[230:233], v[12:15]
	v_mfma_f32_16x16x32_bf16 v[8:11], v[162:165], v[230:233], v[8:11]
	v_mfma_f32_16x16x32_bf16 v[60:63], v[158:161], v[210:213], v[60:63]
	v_mfma_f32_16x16x32_bf16 v[56:59], v[186:189], v[210:213], v[56:59]
	v_mfma_f32_16x16x32_bf16 v[44:47], v[158:161], v[218:221], v[44:47]
	v_mfma_f32_16x16x32_bf16 v[40:43], v[186:189], v[218:221], v[40:43]
	v_mfma_f32_16x16x32_bf16 v[28:31], v[158:161], v[226:229], v[28:31]
	v_mfma_f32_16x16x32_bf16 v[24:27], v[186:189], v[226:229], v[24:27]
	v_mfma_f32_16x16x32_bf16 v[12:15], v[158:161], v[234:237], v[12:15]
	v_mfma_f32_16x16x32_bf16 v[8:11], v[186:189], v[234:237], v[8:11]
	v_mfma_f32_16x16x32_bf16 v[52:55], v[190:193], v[206:209], v[52:55]
	v_mfma_f32_16x16x32_bf16 v[48:51], v[198:201], v[206:209], v[48:51]
	v_mfma_f32_16x16x32_bf16 v[36:39], v[190:193], v[214:217], v[36:39]
	v_mfma_f32_16x16x32_bf16 v[32:35], v[198:201], v[214:217], v[32:35]
	v_mfma_f32_16x16x32_bf16 v[20:23], v[190:193], v[222:225], v[20:23]
	v_mfma_f32_16x16x32_bf16 v[16:19], v[198:201], v[222:225], v[16:19]
	v_mfma_f32_16x16x32_bf16 v[4:7], v[190:193], v[230:233], v[4:7]
	v_mfma_f32_16x16x32_bf16 v[0:3], v[198:201], v[230:233], v[0:3]
	v_mfma_f32_16x16x32_bf16 v[52:55], v[194:197], v[210:213], v[52:55]
	v_mfma_f32_16x16x32_bf16 v[48:51], v[202:205], v[210:213], v[48:51]
	v_mfma_f32_16x16x32_bf16 v[36:39], v[194:197], v[218:221], v[36:39]
	v_mfma_f32_16x16x32_bf16 v[32:35], v[202:205], v[218:221], v[32:35]
	v_mfma_f32_16x16x32_bf16 v[20:23], v[194:197], v[226:229], v[20:23]
	v_mfma_f32_16x16x32_bf16 v[16:19], v[202:205], v[226:229], v[16:19]
	v_mfma_f32_16x16x32_bf16 v[4:7], v[194:197], v[234:237], v[4:7]
	v_mfma_f32_16x16x32_bf16 v[0:3], v[202:205], v[234:237], v[0:3]
	s_barrier
	s_add_u32 s33, s33, 0x100
	s_addc_u32 s54, s54, 0
	s_add_u32 s26, s26, 0x100
	s_addc_u32 s27, s27, 0
	s_cmp_ge_i32 s55, s42
	s_mov_b32 s28, s55
	s_cbranch_scc0 .LBB0_1366
	v_readlane_b32 s54, v254, 52
	v_readlane_b32 s95, v254, 51
	v_readlane_b32 s55, v254, 53
	v_readlane_b32 s92, v254, 54
	v_readlane_b32 s94, v254, 55
	s_movk_i32 s33, 0x300

; #define PG8_STAGE(bufoff, gbase, voff) do { _Pragma("unroll") for (int _i = 0; _i < 2; ++_i) \
;         __builtin_amdgcn_global_load_lds((const unsigned*)((const char*)(gbase) + (voff)[_i]), (PG8_LAS unsigned*)(lds + (bufoff) + ldsw + _i * 8192), 16, 0, 0); } while (0)
; #define PG8_LDA(dst, b, h) do { _Pragma("unroll") for (int m = 0; m < 4; ++m) _Pragma("unroll") for (int k = 0; k < 2; ++k) dst[m][k] = *(const PG8_LAS bf16x8*)(lds + PG8_SA(b, h) + aoff + m * 2048 + k * 1024); } while (0)
; #define PG8_LDB(dst, b, h) do { _Pragma("unroll") for (int n = 0; n < 2; ++n) _Pragma("unroll") for (int k = 0; k < 2; ++k) dst[n][k] = *(const PG8_LAS bf16x8*)(lds + PG8_SB(b, h) + boff + n * 2048 + k * 1024); } while (0)
; #define PG8_MMA(ai, bj, At, Bt) do { __builtin_amdgcn_s_setprio(1); _Pragma("unroll") for (int m = 0; m < 4; ++m) _Pragma("unroll") for (int n = 0; n < 2; ++n) _Pragma("unroll") for (int k = 0; k < 2; ++k) \
;         acc[ai][bj][m][n] = __builtin_amdgcn_mfma_f32_16x16x32_bf16(Bt[n][k], At[m][k], acc[ai][bj][m][n], 0, 0, 0); __builtin_amdgcn_s_setprio(0); } while (0)
; #define PG8_WAIT_V(n) asm volatile("s_waitcnt vmcnt(" #n ")" ::: "memory")
; #define PG8_WAIT_L(n) asm volatile("s_waitcnt lgkmcnt(" #n ")" ::: "memory")
; #define PG8_BAR __builtin_amdgcn_s_barrier()
; #define PG8_SCHED __builtin_amdgcn_sched_barrier(0)
; template <class Epi, class Sched>
; __device__ __forceinline__ void gemm_phase(int wid_s, PG8_LAS unsigned char* lds, const Gemm g, const Sched& S, const Epi& E) {
;     ...
;             const bool last = (t == nt - 2);
;             const char* a1 = cA + (size_t)(t + 1) * kstep;
;             const char* a2 = last ? nA : cA + (size_t)(t + 2) * kstep; const char* b2 = last ? nB : cB + (size_t)(t + 2) * kstep;
;             const char* a3 = a2 + kstep; const char* b3 = b2 + kstep;
;             PG8_LDB(B0, 0, 0); PG8_LDB(B1, 0, 1); PG8_SCHED; PG8_LDA(At, 0, 0); PG8_STAGE(PG8_SA(1, 1), a1 + hstepA, voffA);
;             PG8_WAIT_V(8); PG8_WAIT_L(0); PG8_BAR; PG8_MMA(0, 0, At, B0); PG8_MMA(0, 1, At, B1); PG8_BAR; PG8_SCHED;
;             PG8_LDA(At, 0, 1); PG8_STAGE(PG8_SB(0, 0), b2, voffB); PG8_STAGE(PG8_SB(0, 1), b2 + hstepB, voffB); PG8_STAGE(PG8_SA(0, 0), a2, voffA);
;             PG8_WAIT_V(8); PG8_WAIT_L(0); PG8_BAR; PG8_MMA(1, 0, At, B0); PG8_MMA(1, 1, At, B1); PG8_BAR; PG8_SCHED;
.LBB0_1574:
	s_add_i32 s37, s28, 2
	s_add_u32 s39, s26, 0x80
	s_addc_u32 s29, s27, 0
	s_add_i32 s48, 0, 0x10000
	s_cmp_eq_u32 s45, s28
	s_cselect_b32 s29, s25, s29
	s_cselect_b32 s28, s24, s39
	s_cselect_b32 s41, s3, s36
	s_cselect_b32 s40, s2, s33
	s_add_i32 s39, 0, 0x14000
	v_add_u32_e32 v44, s48, v193
	v_add_u32_e32 v188, s39, v193
	ds_read_b128 v[24:27], v44
	ds_read_b128 v[28:31], v44 offset:1024
	ds_read_b128 v[40:43], v44 offset:2048
	ds_read_b128 v[44:47], v44 offset:3072
	ds_read_b128 v[164:167], v188
	ds_read_b128 v[196:199], v188 offset:1024
	ds_read_b128 v[200:203], v188 offset:2048
	ds_read_b128 v[204:207], v188 offset:3072
	v_lshl_add_u64 v[240:241], s[26:27], 0, v[162:163]
	s_add_i32 m0, s35, 0xc000
	ds_read_b128 v[208:211], v195
	ds_read_b128 v[212:215], v195 offset:1024
	ds_read_b128 v[216:219], v195 offset:2048
	ds_read_b128 v[220:223], v195 offset:3072
	ds_read_b128 v[224:227], v195 offset:4096
	ds_read_b128 v[228:231], v195 offset:5120
	ds_read_b128 v[232:235], v195 offset:6144
	ds_read_b128 v[236:239], v195 offset:7168
	global_load_lds_dwordx4 v[240:241], off
	v_lshl_add_u64 v[240:241], s[26:27], 0, v[160:161]
	s_add_i32 m0, s35, 0xe000
	s_nop 0
	global_load_lds_dwordx4 v[240:241], off
	s_waitcnt vmcnt(8)
	s_waitcnt lgkmcnt(0)
	s_barrier
	s_waitcnt lgkmcnt(0)
	v_mfma_f32_16x16x32_bf16 v[140:143], v[24:27], v[208:211], v[140:143]
	v_mfma_f32_16x16x32_bf16 v[136:139], v[40:43], v[208:211], v[136:139]
	v_mfma_f32_16x16x32_bf16 v[124:127], v[24:27], v[216:219], v[124:127]
	v_mfma_f32_16x16x32_bf16 v[120:123], v[40:43], v[216:219], v[120:123]
	v_mfma_f32_16x16x32_bf16 v[108:111], v[24:27], v[224:227], v[108:111]
	v_mfma_f32_16x16x32_bf16 v[104:107], v[40:43], v[224:227], v[104:107]
	v_mfma_f32_16x16x32_bf16 v[92:95], v[24:27], v[232:235], v[92:95]
	v_mfma_f32_16x16x32_bf16 v[88:91], v[40:43], v[232:235], v[88:91]
	v_mfma_f32_16x16x32_bf16 v[140:143], v[28:31], v[212:215], v[140:143]
	v_mfma_f32_16x16x32_bf16 v[136:139], v[44:47], v[212:215], v[136:139]
	v_mfma_f32_16x16x32_bf16 v[124:127], v[28:31], v[220:223], v[124:127]
	v_mfma_f32_16x16x32_bf16 v[120:123], v[44:47], v[220:223], v[120:123]
	v_mfma_f32_16x16x32_bf16 v[108:111], v[28:31], v[228:231], v[108:111]
	v_mfma_f32_16x16x32_bf16 v[104:107], v[44:47], v[228:231], v[104:107]
	v_mfma_f32_16x16x32_bf16 v[92:95], v[28:31], v[236:239], v[92:95]
	v_mfma_f32_16x16x32_bf16 v[88:91], v[44:47], v[236:239], v[88:91]
	v_mfma_f32_16x16x32_bf16 v[132:135], v[164:167], v[208:211], v[132:135]
	v_mfma_f32_16x16x32_bf16 v[128:131], v[200:203], v[208:211], v[128:131]
	v_mfma_f32_16x16x32_bf16 v[116:119], v[164:167], v[216:219], v[116:119]
	v_mfma_f32_16x16x32_bf16 v[112:115], v[200:203], v[216:219], v[112:115]
	v_mfma_f32_16x16x32_bf16 v[100:103], v[164:167], v[224:227], v[100:103]
	v_mfma_f32_16x16x32_bf16 v[96:99], v[200:203], v[224:227], v[96:99]
	v_mfma_f32_16x16x32_bf16 v[84:87], v[164:167], v[232:235], v[84:87]
	v_mfma_f32_16x16x32_bf16 v[80:83], v[200:203], v[232:235], v[80:83]
	v_mfma_f32_16x16x32_bf16 v[132:135], v[196:199], v[212:215], v[132:135]
	v_mfma_f32_16x16x32_bf16 v[128:131], v[204:207], v[212:215], v[128:131]
	v_mfma_f32_16x16x32_bf16 v[116:119], v[196:199], v[220:223], v[116:119]
	v_mfma_f32_16x16x32_bf16 v[112:115], v[204:207], v[220:223], v[112:115]
	v_mfma_f32_16x16x32_bf16 v[100:103], v[196:199], v[228:231], v[100:103]
	v_mfma_f32_16x16x32_bf16 v[96:99], v[204:207], v[228:231], v[96:99]
	v_mfma_f32_16x16x32_bf16 v[84:87], v[196:199], v[236:239], v[84:87]
	v_mfma_f32_16x16x32_bf16 v[80:83], v[204:207], v[236:239], v[80:83]
	s_barrier
	s_add_i32 s48, s48, s34
	v_lshl_add_u64 v[240:241], s[40:41], 0, v[144:145]
	s_mov_b32 m0, s48
	ds_read_b128 v[208:211], v195 offset:16384
	ds_read_b128 v[212:215], v195 offset:17408
	ds_read_b128 v[216:219], v195 offset:18432
	ds_read_b128 v[220:223], v195 offset:19456
	ds_read_b128 v[224:227], v195 offset:20480
	ds_read_b128 v[228:231], v195 offset:21504
	ds_read_b128 v[232:235], v195 offset:22528
	ds_read_b128 v[236:239], v195 offset:23552
	global_load_lds_dwordx4 v[240:241], off
	s_add_i32 m0, s48, 0x2000
	v_lshl_add_u64 v[242:243], s[40:41], 0, v[158:159]
	s_add_u32 s40, s40, s6
	s_addc_u32 s41, s41, s7
	s_add_i32 s39, s39, s34
	global_load_lds_dwordx4 v[242:243], off
	v_lshl_add_u64 v[244:245], s[40:41], 0, v[144:145]
	s_mov_b32 m0, s39
	v_lshl_add_u64 v[246:247], s[40:41], 0, v[158:159]
	global_load_lds_dwordx4 v[244:245], off
	s_add_i32 m0, s39, 0x2000
	v_lshl_add_u64 v[248:249], s[28:29], 0, v[154:155]
	global_load_lds_dwordx4 v[246:247], off
	s_mov_b32 m0, s35
	v_lshl_add_u64 v[250:251], s[28:29], 0, v[156:157]
	global_load_lds_dwordx4 v[248:249], off
	s_mov_b32 m0, s42
	s_nop 0
	global_load_lds_dwordx4 v[250:251], off
	s_waitcnt vmcnt(8)
	s_waitcnt lgkmcnt(0)
	s_barrier
; #define PG8_STAGE(bufoff, gbase, voff) do { _Pragma("unroll") for (int _i = 0; _i < 2; ++_i) \
;         __builtin_amdgcn_global_load_lds((const unsigned*)((const char*)(gbase) + (voff)[_i]), (PG8_LAS unsigned*)(lds + (bufoff) + ldsw + _i * 8192), 16, 0, 0); } while (0)
; #define PG8_LDA(dst, b, h) do { _Pragma("unroll") for (int m = 0; m < 4; ++m) _Pragma("unroll") for (int k = 0; k < 2; ++k) dst[m][k] = *(const PG8_LAS bf16x8*)(lds + PG8_SA(b, h) + aoff + m * 2048 + k * 1024); } while (0)
; #define PG8_LDB(dst, b, h) do { _Pragma("unroll") for (int n = 0; n < 2; ++n) _Pragma("unroll") for (int k = 0; k < 2; ++k) dst[n][k] = *(const PG8_LAS bf16x8*)(lds + PG8_SB(b, h) + boff + n * 2048 + k * 1024); } while (0)
; #define PG8_MMA(ai, bj, At, Bt) do { __builtin_amdgcn_s_setprio(1); _Pragma("unroll") for (int m = 0; m < 4; ++m) _Pragma("unroll") for (int n = 0; n < 2; ++n) _Pragma("unroll") for (int k = 0; k < 2; ++k) \
;         acc[ai][bj][m][n] = __builtin_amdgcn_mfma_f32_16x16x32_bf16(Bt[n][k], At[m][k], acc[ai][bj][m][n], 0, 0, 0); __builtin_amdgcn_s_setprio(0); } while (0)
; #define PG8_WAIT_V(n) asm volatile("s_waitcnt vmcnt(" #n ")" ::: "memory")
; #define PG8_WAIT_L(n) asm volatile("s_waitcnt lgkmcnt(" #n ")" ::: "memory")
; #define PG8_BAR __builtin_amdgcn_s_barrier()
; #define PG8_SCHED __builtin_amdgcn_sched_barrier(0)
; template <class Epi, class Sched>
; __device__ __forceinline__ void gemm_phase(int wid_s, PG8_LAS unsigned char* lds, const Gemm g, const Sched& S, const Epi& E) {
;     ...
;             PG8_WAIT_V(8); PG8_WAIT_L(0); PG8_BAR; PG8_MMA(1, 0, At, B0); PG8_MMA(1, 1, At, B1); PG8_BAR; PG8_SCHED;
;             PG8_LDB(B0, 1, 0); PG8_LDB(B1, 1, 1); PG8_SCHED; PG8_LDA(At, 1, 0); PG8_STAGE(PG8_SA(0, 1), a2 + hstepA, voffA);
;             PG8_WAIT_V(8); PG8_WAIT_L(0); PG8_BAR; PG8_MMA(0, 0, At, B0); PG8_MMA(0, 1, At, B1); PG8_BAR; PG8_SCHED;
	s_waitcnt lgkmcnt(0)
	v_mfma_f32_16x16x32_bf16 v[76:79], v[24:27], v[208:211], v[76:79]
	v_mfma_f32_16x16x32_bf16 v[72:75], v[40:43], v[208:211], v[72:75]
	v_mfma_f32_16x16x32_bf16 v[60:63], v[24:27], v[216:219], v[60:63]
	v_mfma_f32_16x16x32_bf16 v[56:59], v[40:43], v[216:219], v[56:59]
	v_mfma_f32_16x16x32_bf16 v[36:39], v[24:27], v[224:227], v[36:39]
	v_mfma_f32_16x16x32_bf16 v[32:35], v[40:43], v[224:227], v[32:35]
	v_mfma_f32_16x16x32_bf16 v[12:15], v[24:27], v[232:235], v[12:15]
	v_mfma_f32_16x16x32_bf16 v[8:11], v[40:43], v[232:235], v[8:11]
	v_mfma_f32_16x16x32_bf16 v[76:79], v[28:31], v[212:215], v[76:79]
	v_mfma_f32_16x16x32_bf16 v[72:75], v[44:47], v[212:215], v[72:75]
	v_mfma_f32_16x16x32_bf16 v[60:63], v[28:31], v[220:223], v[60:63]
	v_mfma_f32_16x16x32_bf16 v[56:59], v[44:47], v[220:223], v[56:59]
	v_mfma_f32_16x16x32_bf16 v[36:39], v[28:31], v[228:231], v[36:39]
	v_mfma_f32_16x16x32_bf16 v[32:35], v[44:47], v[228:231], v[32:35]
	v_mfma_f32_16x16x32_bf16 v[12:15], v[28:31], v[236:239], v[12:15]
	v_mfma_f32_16x16x32_bf16 v[8:11], v[44:47], v[236:239], v[8:11]
	v_mfma_f32_16x16x32_bf16 v[20:23], v[164:167], v[224:227], v[20:23]
	v_mfma_f32_16x16x32_bf16 v[16:19], v[200:203], v[224:227], v[16:19]
	v_mfma_f32_16x16x32_bf16 v[4:7], v[164:167], v[232:235], v[4:7]
	v_mfma_f32_16x16x32_bf16 v[0:3], v[200:203], v[232:235], v[0:3]
	v_mfma_f32_16x16x32_bf16 v[24:27], v[164:167], v[208:211], v[68:71]
	v_mfma_f32_16x16x32_bf16 v[28:31], v[200:203], v[208:211], v[64:67]
	v_mfma_f32_16x16x32_bf16 v[40:43], v[164:167], v[216:219], v[52:55]
	v_mfma_f32_16x16x32_bf16 v[44:47], v[200:203], v[216:219], v[48:51]
	v_mfma_f32_16x16x32_bf16 v[20:23], v[196:199], v[228:231], v[20:23]
	v_mfma_f32_16x16x32_bf16 v[16:19], v[204:207], v[228:231], v[16:19]
	v_mfma_f32_16x16x32_bf16 v[4:7], v[196:199], v[236:239], v[4:7]
	v_mfma_f32_16x16x32_bf16 v[0:3], v[204:207], v[236:239], v[0:3]
	v_mfma_f32_16x16x32_bf16 v[24:27], v[196:199], v[212:215], v[24:27]
	v_mfma_f32_16x16x32_bf16 v[28:31], v[204:207], v[212:215], v[28:31]
	v_mfma_f32_16x16x32_bf16 v[40:43], v[196:199], v[220:223], v[40:43]
	v_mfma_f32_16x16x32_bf16 v[44:47], v[204:207], v[220:223], v[44:47]
	s_barrier
	s_add_i32 s39, 0, 0x18000
	s_add_i32 s40, 0, 0x1c000
	v_add_u32_e32 v68, s39, v193
	v_add_u32_e32 v188, s40, v193
	ds_read_b128 v[48:51], v68
	ds_read_b128 v[52:55], v68 offset:1024
	ds_read_b128 v[64:67], v68 offset:2048
	ds_read_b128 v[68:71], v68 offset:3072
	ds_read_b128 v[164:167], v188
	ds_read_b128 v[196:199], v188 offset:1024
	ds_read_b128 v[200:203], v188 offset:2048
	ds_read_b128 v[204:207], v188 offset:3072
	s_add_u32 s28, s28, s4
	s_addc_u32 s29, s29, s5
	s_mov_b32 m0, s46
	v_lshl_add_u64 v[252:253], s[28:29], 0, v[154:155]
	ds_read_b128 v[208:211], v195 offset:32768
	ds_read_b128 v[212:215], v195 offset:33792
	ds_read_b128 v[216:219], v195 offset:34816
	ds_read_b128 v[220:223], v195 offset:35840
	ds_read_b128 v[224:227], v195 offset:36864
	ds_read_b128 v[228:231], v195 offset:37888
	ds_read_b128 v[232:235], v195 offset:38912
	ds_read_b128 v[236:239], v195 offset:39936
	global_load_lds_dwordx4 v[252:253], off
	v_lshl_add_u64 v[252:253], s[28:29], 0, v[156:157]
	s_mov_b32 m0, s47
	s_nop 0
	global_load_lds_dwordx4 v[252:253], off
	s_waitcnt vmcnt(8)
	s_waitcnt lgkmcnt(0)
	s_barrier
	s_waitcnt lgkmcnt(0)
	v_mfma_f32_16x16x32_bf16 v[140:143], v[48:51], v[208:211], v[140:143]
	v_mfma_f32_16x16x32_bf16 v[136:139], v[64:67], v[208:211], v[136:139]
	v_mfma_f32_16x16x32_bf16 v[124:127], v[48:51], v[216:219], v[124:127]
	v_mfma_f32_16x16x32_bf16 v[120:123], v[64:67], v[216:219], v[120:123]
	v_mfma_f32_16x16x32_bf16 v[108:111], v[48:51], v[224:227], v[108:111]
	v_mfma_f32_16x16x32_bf16 v[104:107], v[64:67], v[224:227], v[104:107]
	v_mfma_f32_16x16x32_bf16 v[92:95], v[48:51], v[232:235], v[92:95]
	v_mfma_f32_16x16x32_bf16 v[88:91], v[64:67], v[232:235], v[88:91]
	v_mfma_f32_16x16x32_bf16 v[140:143], v[52:55], v[212:215], v[140:143]
	v_mfma_f32_16x16x32_bf16 v[136:139], v[68:71], v[212:215], v[136:139]
	v_mfma_f32_16x16x32_bf16 v[124:127], v[52:55], v[220:223], v[124:127]
	v_mfma_f32_16x16x32_bf16 v[120:123], v[68:71], v[220:223], v[120:123]
	v_mfma_f32_16x16x32_bf16 v[108:111], v[52:55], v[228:231], v[108:111]
	v_mfma_f32_16x16x32_bf16 v[104:107], v[68:71], v[228:231], v[104:107]
	v_mfma_f32_16x16x32_bf16 v[92:95], v[52:55], v[236:239], v[92:95]
	v_mfma_f32_16x16x32_bf16 v[88:91], v[68:71], v[236:239], v[88:91]
	v_mfma_f32_16x16x32_bf16 v[132:135], v[164:167], v[208:211], v[132:135]
	v_mfma_f32_16x16x32_bf16 v[128:131], v[200:203], v[208:211], v[128:131]
	v_mfma_f32_16x16x32_bf16 v[116:119], v[164:167], v[216:219], v[116:119]
	v_mfma_f32_16x16x32_bf16 v[112:115], v[200:203], v[216:219], v[112:115]
	v_mfma_f32_16x16x32_bf16 v[100:103], v[164:167], v[224:227], v[100:103]
	v_mfma_f32_16x16x32_bf16 v[96:99], v[200:203], v[224:227], v[96:99]
	v_mfma_f32_16x16x32_bf16 v[84:87], v[164:167], v[232:235], v[84:87]
	v_mfma_f32_16x16x32_bf16 v[80:83], v[200:203], v[232:235], v[80:83]
	v_mfma_f32_16x16x32_bf16 v[132:135], v[196:199], v[212:215], v[132:135]
	v_mfma_f32_16x16x32_bf16 v[128:131], v[204:207], v[212:215], v[128:131]
	v_mfma_f32_16x16x32_bf16 v[116:119], v[196:199], v[220:223], v[116:119]
	v_mfma_f32_16x16x32_bf16 v[112:115], v[204:207], v[220:223], v[112:115]
	v_mfma_f32_16x16x32_bf16 v[100:103], v[196:199], v[228:231], v[100:103]
	v_mfma_f32_16x16x32_bf16 v[96:99], v[204:207], v[228:231], v[96:99]
	v_mfma_f32_16x16x32_bf16 v[84:87], v[196:199], v[236:239], v[84:87]
	v_mfma_f32_16x16x32_bf16 v[80:83], v[204:207], v[236:239], v[80:83]
	s_barrier
; #define PG8_STAGE(bufoff, gbase, voff) do { _Pragma("unroll") for (int _i = 0; _i < 2; ++_i) \
;         __builtin_amdgcn_global_load_lds((const unsigned*)((const char*)(gbase) + (voff)[_i]), (PG8_LAS unsigned*)(lds + (bufoff) + ldsw + _i * 8192), 16, 0, 0); } while (0)
; #define PG8_LDA(dst, b, h) do { _Pragma("unroll") for (int m = 0; m < 4; ++m) _Pragma("unroll") for (int k = 0; k < 2; ++k) dst[m][k] = *(const PG8_LAS bf16x8*)(lds + PG8_SA(b, h) + aoff + m * 2048 + k * 1024); } while (0)
; #define PG8_MMA(ai, bj, At, Bt) do { __builtin_amdgcn_s_setprio(1); _Pragma("unroll") for (int m = 0; m < 4; ++m) _Pragma("unroll") for (int n = 0; n < 2; ++n) _Pragma("unroll") for (int k = 0; k < 2; ++k) \
;         acc[ai][bj][m][n] = __builtin_amdgcn_mfma_f32_16x16x32_bf16(Bt[n][k], At[m][k], acc[ai][bj][m][n], 0, 0, 0); __builtin_amdgcn_s_setprio(0); } while (0)
; #define PG8_WAIT_V(n) asm volatile("s_waitcnt vmcnt(" #n ")" ::: "memory")
; #define PG8_WAIT_L(n) asm volatile("s_waitcnt lgkmcnt(" #n ")" ::: "memory")
; #define PG8_BAR __builtin_amdgcn_s_barrier()
; #define PG8_SCHED __builtin_amdgcn_sched_barrier(0)
; template <class Epi, class Sched>
; __device__ __forceinline__ void gemm_phase(int wid_s, PG8_LAS unsigned char* lds, const Gemm g, const Sched& S, const Epi& E) {
;     ...
;             PG8_LDA(At, 1, 1); PG8_STAGE(PG8_SB(1, 0), b3, voffB); PG8_STAGE(PG8_SB(1, 1), b3 + hstepB, voffB); PG8_STAGE(PG8_SA(1, 0), a3, voffA);
;             PG8_WAIT_V(8); PG8_WAIT_L(0); PG8_BAR; PG8_MMA(1, 0, At, B0); PG8_MMA(1, 1, At, B1); PG8_BAR; PG8_SCHED;
;         }
	s_add_i32 s28, s39, s34
	v_lshl_add_u64 v[240:241], v[240:241], 0, s[96:97]
	s_mov_b32 m0, s28
	ds_read_b128 v[208:211], v195 offset:49152
	ds_read_b128 v[212:215], v195 offset:50176
	ds_read_b128 v[216:219], v195 offset:51200
	ds_read_b128 v[220:223], v195 offset:52224
	ds_read_b128 v[224:227], v195 offset:53248
	ds_read_b128 v[228:231], v195 offset:54272
	ds_read_b128 v[232:235], v195 offset:55296
	ds_read_b128 v[236:239], v195 offset:56320
	global_load_lds_dwordx4 v[240:241], off
	v_lshl_add_u64 v[240:241], v[242:243], 0, s[96:97]
	s_add_i32 m0, s28, 0x2000
	s_add_i32 s28, s40, s34
	global_load_lds_dwordx4 v[240:241], off
	v_lshl_add_u64 v[240:241], v[244:245], 0, s[96:97]
	s_mov_b32 m0, s28
	s_nop 0
	global_load_lds_dwordx4 v[240:241], off
	v_lshl_add_u64 v[240:241], v[246:247], 0, s[96:97]
	s_add_i32 m0, s28, 0x2000
	s_nop 0
	global_load_lds_dwordx4 v[240:241], off
	v_lshl_add_u64 v[240:241], v[248:249], 0, s[96:97]
	s_mov_b32 m0, s52
	s_nop 0
	global_load_lds_dwordx4 v[240:241], off
	v_lshl_add_u64 v[240:241], v[250:251], 0, s[96:97]
	s_mov_b32 m0, s53
	s_nop 0
	global_load_lds_dwordx4 v[240:241], off
	s_waitcnt vmcnt(8)
	s_waitcnt lgkmcnt(0)
	s_barrier
	s_waitcnt lgkmcnt(0)
	v_mfma_f32_16x16x32_bf16 v[76:79], v[48:51], v[208:211], v[76:79]
	v_mfma_f32_16x16x32_bf16 v[72:75], v[64:67], v[208:211], v[72:75]
	v_mfma_f32_16x16x32_bf16 v[60:63], v[48:51], v[216:219], v[60:63]
	v_mfma_f32_16x16x32_bf16 v[56:59], v[64:67], v[216:219], v[56:59]
	v_mfma_f32_16x16x32_bf16 v[36:39], v[48:51], v[224:227], v[36:39]
	v_mfma_f32_16x16x32_bf16 v[32:35], v[64:67], v[224:227], v[32:35]
	v_mfma_f32_16x16x32_bf16 v[12:15], v[48:51], v[232:235], v[12:15]
	v_mfma_f32_16x16x32_bf16 v[8:11], v[64:67], v[232:235], v[8:11]
	v_mfma_f32_16x16x32_bf16 v[76:79], v[52:55], v[212:215], v[76:79]
	v_mfma_f32_16x16x32_bf16 v[72:75], v[68:71], v[212:215], v[72:75]
	v_mfma_f32_16x16x32_bf16 v[60:63], v[52:55], v[220:223], v[60:63]
	v_mfma_f32_16x16x32_bf16 v[56:59], v[68:71], v[220:223], v[56:59]
	v_mfma_f32_16x16x32_bf16 v[36:39], v[52:55], v[228:231], v[36:39]
	v_mfma_f32_16x16x32_bf16 v[32:35], v[68:71], v[228:231], v[32:35]
	v_mfma_f32_16x16x32_bf16 v[12:15], v[52:55], v[236:239], v[12:15]
	v_mfma_f32_16x16x32_bf16 v[8:11], v[68:71], v[236:239], v[8:11]
	v_mfma_f32_16x16x32_bf16 v[24:27], v[164:167], v[208:211], v[24:27]
	v_mfma_f32_16x16x32_bf16 v[68:71], v[196:199], v[212:215], v[24:27]
	v_mfma_f32_16x16x32_bf16 v[24:27], v[200:203], v[208:211], v[28:31]
	v_mfma_f32_16x16x32_bf16 v[64:67], v[204:207], v[212:215], v[24:27]
	v_mfma_f32_16x16x32_bf16 v[24:27], v[164:167], v[216:219], v[40:43]
	v_mfma_f32_16x16x32_bf16 v[52:55], v[196:199], v[220:223], v[24:27]
	v_mfma_f32_16x16x32_bf16 v[24:27], v[200:203], v[216:219], v[44:47]
	v_mfma_f32_16x16x32_bf16 v[20:23], v[164:167], v[224:227], v[20:23]
	v_mfma_f32_16x16x32_bf16 v[16:19], v[200:203], v[224:227], v[16:19]
	v_mfma_f32_16x16x32_bf16 v[4:7], v[164:167], v[232:235], v[4:7]
	v_mfma_f32_16x16x32_bf16 v[0:3], v[200:203], v[232:235], v[0:3]
	v_mfma_f32_16x16x32_bf16 v[48:51], v[204:207], v[220:223], v[24:27]
	v_mfma_f32_16x16x32_bf16 v[20:23], v[196:199], v[228:231], v[20:23]
	v_mfma_f32_16x16x32_bf16 v[16:19], v[204:207], v[228:231], v[16:19]
	v_mfma_f32_16x16x32_bf16 v[4:7], v[196:199], v[236:239], v[4:7]
	v_mfma_f32_16x16x32_bf16 v[0:3], v[204:207], v[236:239], v[0:3]
	s_barrier
	s_add_u32 s33, s33, 0x100
	s_addc_u32 s36, s36, 0
	s_add_u32 s26, s26, 0x100
	s_addc_u32 s27, s27, 0
	s_cmp_ge_i32 s37, s44
	s_mov_b32 s28, s37
	s_cbranch_scc0 .LBB0_1574
	s_movk_i32 s39, 0x7f
	s_movk_i32 s33, 0x300

; #define PG8_STAGE(bufoff, gbase, voff) do { _Pragma("unroll") for (int _i = 0; _i < 2; ++_i) \
;         __builtin_amdgcn_global_load_lds((const unsigned*)((const char*)(gbase) + (voff)[_i]), (PG8_LAS unsigned*)(lds + (bufoff) + ldsw + _i * 8192), 16, 0, 0); } while (0)
; #define PG8_LDA(dst, b, h) do { _Pragma("unroll") for (int m = 0; m < 4; ++m) _Pragma("unroll") for (int k = 0; k < 2; ++k) dst[m][k] = *(const PG8_LAS bf16x8*)(lds + PG8_SA(b, h) + aoff + m * 2048 + k * 1024); } while (0)
; #define PG8_LDB(dst, b, h) do { _Pragma("unroll") for (int n = 0; n < 2; ++n) _Pragma("unroll") for (int k = 0; k < 2; ++k) dst[n][k] = *(const PG8_LAS bf16x8*)(lds + PG8_SB(b, h) + boff + n * 2048 + k * 1024); } while (0)
; #define PG8_MMA(ai, bj, At, Bt) do { __builtin_amdgcn_s_setprio(1); _Pragma("unroll") for (int m = 0; m < 4; ++m) _Pragma("unroll") for (int n = 0; n < 2; ++n) _Pragma("unroll") for (int k = 0; k < 2; ++k) \
;         acc[ai][bj][m][n] = __builtin_amdgcn_mfma_f32_16x16x32_bf16(Bt[n][k], At[m][k], acc[ai][bj][m][n], 0, 0, 0); __builtin_amdgcn_s_setprio(0); } while (0)
; #define PG8_WAIT_V(n) asm volatile("s_waitcnt vmcnt(" #n ")" ::: "memory")
; #define PG8_WAIT_L(n) asm volatile("s_waitcnt lgkmcnt(" #n ")" ::: "memory")
; #define PG8_BAR __builtin_amdgcn_s_barrier()
; #define PG8_SCHED __builtin_amdgcn_sched_barrier(0)
; template <class Epi, class Sched>
; __device__ __forceinline__ void gemm_phase(int wid_s, PG8_LAS unsigned char* lds, const Gemm g, const Sched& S, const Epi& E) {
;     ...
;             const bool last = (t == nt - 2);
;             const char* a1 = cA + (size_t)(t + 1) * kstep;
;             const char* a2 = last ? nA : cA + (size_t)(t + 2) * kstep; const char* b2 = last ? nB : cB + (size_t)(t + 2) * kstep;
;             const char* a3 = a2 + kstep; const char* b3 = b2 + kstep;
;             PG8_LDB(B0, 0, 0); PG8_LDB(B1, 0, 1); PG8_SCHED; PG8_LDA(At, 0, 0); PG8_STAGE(PG8_SA(1, 1), a1 + hstepA, voffA);
;             PG8_WAIT_V(8); PG8_WAIT_L(0); PG8_BAR; PG8_MMA(0, 0, At, B0); PG8_MMA(0, 1, At, B1); PG8_BAR; PG8_SCHED;
;             PG8_LDA(At, 0, 1); PG8_STAGE(PG8_SB(0, 0), b2, voffB); PG8_STAGE(PG8_SB(0, 1), b2 + hstepB, voffB); PG8_STAGE(PG8_SA(0, 0), a2, voffA);
;             PG8_WAIT_V(8); PG8_WAIT_L(0); PG8_BAR; PG8_MMA(1, 0, At, B0); PG8_MMA(1, 1, At, B1); PG8_BAR; PG8_SCHED;
.LBB0_1602:
	s_add_i32 s51, s46, 2
	s_add_u32 s52, s2, 0x80
	s_addc_u32 s47, s3, 0
	s_add_i32 vcc_lo, 0, 0x10000
	s_cmp_eq_u32 s56, s46
	s_cselect_b32 s47, s29, s47
	s_cselect_b32 s46, s28, s52
	v_add_u32_e32 v142, vcc_lo, v157
	s_cselect_b32 s53, s31, s50
	s_cselect_b32 s52, s30, s33
	s_add_i32 vcc_hi, 0, 0x14000
	ds_read_b128 v[138:141], v142
	ds_read_b128 v[160:163], v142 offset:1024
	ds_read_b128 v[164:167], v142 offset:2048
	ds_read_b128 v[192:195], v142 offset:3072
	v_add_u32_e32 v142, vcc_hi, v157
	ds_read_b128 v[196:199], v142
	ds_read_b128 v[200:203], v142 offset:1024
	ds_read_b128 v[204:207], v142 offset:2048
	ds_read_b128 v[208:211], v142 offset:3072
	v_lshl_add_u64 v[142:143], s[2:3], 0, v[136:137]
	s_add_i32 m0, s36, 0xc000
	ds_read_b128 v[212:215], v159
	ds_read_b128 v[216:219], v159 offset:1024
	ds_read_b128 v[220:223], v159 offset:2048
	ds_read_b128 v[224:227], v159 offset:3072
	ds_read_b128 v[228:231], v159 offset:4096
	ds_read_b128 v[232:235], v159 offset:5120
	ds_read_b128 v[236:239], v159 offset:6144
	ds_read_b128 v[240:243], v159 offset:7168
	global_load_lds_dwordx4 v[142:143], off
	v_lshl_add_u64 v[142:143], s[2:3], 0, v[134:135]
	s_add_i32 m0, s36, 0xe000
	s_nop 0
	global_load_lds_dwordx4 v[142:143], off
	s_waitcnt vmcnt(8)
	s_waitcnt lgkmcnt(0)
	s_barrier
	s_waitcnt lgkmcnt(0)
	v_mfma_f32_16x16x32_bf16 v[124:127], v[138:141], v[212:215], v[124:127]
	v_mfma_f32_16x16x32_bf16 v[120:123], v[164:167], v[212:215], v[120:123]
	v_mfma_f32_16x16x32_bf16 v[108:111], v[138:141], v[220:223], v[108:111]
	v_mfma_f32_16x16x32_bf16 v[104:107], v[164:167], v[220:223], v[104:107]
	v_mfma_f32_16x16x32_bf16 v[92:95], v[138:141], v[228:231], v[92:95]
	v_mfma_f32_16x16x32_bf16 v[88:91], v[164:167], v[228:231], v[88:91]
	v_mfma_f32_16x16x32_bf16 v[76:79], v[138:141], v[236:239], v[76:79]
	v_mfma_f32_16x16x32_bf16 v[72:75], v[164:167], v[236:239], v[72:75]
	v_mfma_f32_16x16x32_bf16 v[124:127], v[160:163], v[216:219], v[124:127]
	v_mfma_f32_16x16x32_bf16 v[120:123], v[192:195], v[216:219], v[120:123]
	v_mfma_f32_16x16x32_bf16 v[108:111], v[160:163], v[224:227], v[108:111]
	v_mfma_f32_16x16x32_bf16 v[104:107], v[192:195], v[224:227], v[104:107]
	v_mfma_f32_16x16x32_bf16 v[92:95], v[160:163], v[232:235], v[92:95]
	v_mfma_f32_16x16x32_bf16 v[88:91], v[192:195], v[232:235], v[88:91]
	v_mfma_f32_16x16x32_bf16 v[76:79], v[160:163], v[240:243], v[76:79]
	v_mfma_f32_16x16x32_bf16 v[72:75], v[192:195], v[240:243], v[72:75]
	v_mfma_f32_16x16x32_bf16 v[116:119], v[196:199], v[212:215], v[116:119]
	v_mfma_f32_16x16x32_bf16 v[112:115], v[204:207], v[212:215], v[112:115]
	v_mfma_f32_16x16x32_bf16 v[100:103], v[196:199], v[220:223], v[100:103]
	v_mfma_f32_16x16x32_bf16 v[96:99], v[204:207], v[220:223], v[96:99]
	v_mfma_f32_16x16x32_bf16 v[84:87], v[196:199], v[228:231], v[84:87]
	v_mfma_f32_16x16x32_bf16 v[80:83], v[204:207], v[228:231], v[80:83]
	v_mfma_f32_16x16x32_bf16 v[68:71], v[196:199], v[236:239], v[68:71]
	v_mfma_f32_16x16x32_bf16 v[64:67], v[204:207], v[236:239], v[64:67]
	v_mfma_f32_16x16x32_bf16 v[116:119], v[200:203], v[216:219], v[116:119]
	v_mfma_f32_16x16x32_bf16 v[112:115], v[208:211], v[216:219], v[112:115]
	v_mfma_f32_16x16x32_bf16 v[100:103], v[200:203], v[224:227], v[100:103]
	v_mfma_f32_16x16x32_bf16 v[96:99], v[208:211], v[224:227], v[96:99]
	v_mfma_f32_16x16x32_bf16 v[84:87], v[200:203], v[232:235], v[84:87]
	v_mfma_f32_16x16x32_bf16 v[80:83], v[208:211], v[232:235], v[80:83]
	v_mfma_f32_16x16x32_bf16 v[68:71], v[200:203], v[240:243], v[68:71]
	v_mfma_f32_16x16x32_bf16 v[64:67], v[208:211], v[240:243], v[64:67]
	s_barrier
	s_add_i32 vcc_lo, vcc_lo, s19
	v_lshl_add_u64 v[142:143], s[52:53], 0, v[144:145]
	s_mov_b32 m0, vcc_lo
	ds_read_b128 v[212:215], v159 offset:16384
	ds_read_b128 v[216:219], v159 offset:17408
	ds_read_b128 v[220:223], v159 offset:18432
	ds_read_b128 v[224:227], v159 offset:19456
	ds_read_b128 v[228:231], v159 offset:20480
	ds_read_b128 v[232:235], v159 offset:21504
	ds_read_b128 v[236:239], v159 offset:22528
	ds_read_b128 v[240:243], v159 offset:23552
	global_load_lds_dwordx4 v[142:143], off
	s_add_i32 m0, vcc_lo, 0x2000
	v_lshl_add_u64 v[154:155], s[52:53], 0, v[132:133]
	s_add_u32 s52, s52, s6
	s_addc_u32 s53, s53, s7
	s_add_i32 vcc_lo, vcc_hi, s19
	global_load_lds_dwordx4 v[154:155], off
	v_lshl_add_u64 v[244:245], s[52:53], 0, v[144:145]
	s_mov_b32 m0, vcc_lo
	v_lshl_add_u64 v[246:247], s[52:53], 0, v[132:133]
	global_load_lds_dwordx4 v[244:245], off
	s_add_i32 m0, vcc_lo, 0x2000
	v_lshl_add_u64 v[248:249], s[46:47], 0, v[128:129]
	global_load_lds_dwordx4 v[246:247], off
	s_mov_b32 m0, s36
	v_lshl_add_u64 v[250:251], s[46:47], 0, v[130:131]
	global_load_lds_dwordx4 v[248:249], off
	s_mov_b32 m0, s37
	s_nop 0
	global_load_lds_dwordx4 v[250:251], off
	s_waitcnt vmcnt(8)
	s_waitcnt lgkmcnt(0)
	s_barrier
; #define PG8_STAGE(bufoff, gbase, voff) do { _Pragma("unroll") for (int _i = 0; _i < 2; ++_i) \
;         __builtin_amdgcn_global_load_lds((const unsigned*)((const char*)(gbase) + (voff)[_i]), (PG8_LAS unsigned*)(lds + (bufoff) + ldsw + _i * 8192), 16, 0, 0); } while (0)
; #define PG8_LDA(dst, b, h) do { _Pragma("unroll") for (int m = 0; m < 4; ++m) _Pragma("unroll") for (int k = 0; k < 2; ++k) dst[m][k] = *(const PG8_LAS bf16x8*)(lds + PG8_SA(b, h) + aoff + m * 2048 + k * 1024); } while (0)
; #define PG8_LDB(dst, b, h) do { _Pragma("unroll") for (int n = 0; n < 2; ++n) _Pragma("unroll") for (int k = 0; k < 2; ++k) dst[n][k] = *(const PG8_LAS bf16x8*)(lds + PG8_SB(b, h) + boff + n * 2048 + k * 1024); } while (0)
; #define PG8_MMA(ai, bj, At, Bt) do { __builtin_amdgcn_s_setprio(1); _Pragma("unroll") for (int m = 0; m < 4; ++m) _Pragma("unroll") for (int n = 0; n < 2; ++n) _Pragma("unroll") for (int k = 0; k < 2; ++k) \
;         acc[ai][bj][m][n] = __builtin_amdgcn_mfma_f32_16x16x32_bf16(Bt[n][k], At[m][k], acc[ai][bj][m][n], 0, 0, 0); __builtin_amdgcn_s_setprio(0); } while (0)
; #define PG8_WAIT_V(n) asm volatile("s_waitcnt vmcnt(" #n ")" ::: "memory")
; #define PG8_WAIT_L(n) asm volatile("s_waitcnt lgkmcnt(" #n ")" ::: "memory")
; #define PG8_BAR __builtin_amdgcn_s_barrier()
; #define PG8_SCHED __builtin_amdgcn_sched_barrier(0)
; template <class Epi, class Sched>
; __device__ __forceinline__ void gemm_phase(int wid_s, PG8_LAS unsigned char* lds, const Gemm g, const Sched& S, const Epi& E) {
;     ...
;             PG8_WAIT_V(8); PG8_WAIT_L(0); PG8_BAR; PG8_MMA(1, 0, At, B0); PG8_MMA(1, 1, At, B1); PG8_BAR; PG8_SCHED;
;             PG8_LDB(B0, 1, 0); PG8_LDB(B1, 1, 1); PG8_SCHED; PG8_LDA(At, 1, 0); PG8_STAGE(PG8_SA(0, 1), a2 + hstepA, voffA);
;             PG8_WAIT_V(8); PG8_WAIT_L(0); PG8_BAR; PG8_MMA(0, 0, At, B0); PG8_MMA(0, 1, At, B1); PG8_BAR; PG8_SCHED;
	s_waitcnt lgkmcnt(0)
	v_mfma_f32_16x16x32_bf16 v[60:63], v[138:141], v[212:215], v[60:63]
	v_mfma_f32_16x16x32_bf16 v[56:59], v[164:167], v[212:215], v[56:59]
	v_mfma_f32_16x16x32_bf16 v[44:47], v[138:141], v[220:223], v[44:47]
	v_mfma_f32_16x16x32_bf16 v[40:43], v[164:167], v[220:223], v[40:43]
	v_mfma_f32_16x16x32_bf16 v[28:31], v[138:141], v[228:231], v[28:31]
	v_mfma_f32_16x16x32_bf16 v[24:27], v[164:167], v[228:231], v[24:27]
	v_mfma_f32_16x16x32_bf16 v[12:15], v[138:141], v[236:239], v[12:15]
	v_mfma_f32_16x16x32_bf16 v[8:11], v[164:167], v[236:239], v[8:11]
	v_mfma_f32_16x16x32_bf16 v[60:63], v[160:163], v[216:219], v[60:63]
	v_mfma_f32_16x16x32_bf16 v[56:59], v[192:195], v[216:219], v[56:59]
	v_mfma_f32_16x16x32_bf16 v[44:47], v[160:163], v[224:227], v[44:47]
	v_mfma_f32_16x16x32_bf16 v[40:43], v[192:195], v[224:227], v[40:43]
	v_mfma_f32_16x16x32_bf16 v[28:31], v[160:163], v[232:235], v[28:31]
	v_mfma_f32_16x16x32_bf16 v[24:27], v[192:195], v[232:235], v[24:27]
	v_mfma_f32_16x16x32_bf16 v[12:15], v[160:163], v[240:243], v[12:15]
	v_mfma_f32_16x16x32_bf16 v[8:11], v[192:195], v[240:243], v[8:11]
	v_mfma_f32_16x16x32_bf16 v[52:55], v[196:199], v[212:215], v[52:55]
	v_mfma_f32_16x16x32_bf16 v[48:51], v[204:207], v[212:215], v[48:51]
	v_mfma_f32_16x16x32_bf16 v[36:39], v[196:199], v[220:223], v[36:39]
	v_mfma_f32_16x16x32_bf16 v[32:35], v[204:207], v[220:223], v[32:35]
	v_mfma_f32_16x16x32_bf16 v[20:23], v[196:199], v[228:231], v[20:23]
	v_mfma_f32_16x16x32_bf16 v[16:19], v[204:207], v[228:231], v[16:19]
	v_mfma_f32_16x16x32_bf16 v[4:7], v[196:199], v[236:239], v[4:7]
	v_mfma_f32_16x16x32_bf16 v[0:3], v[204:207], v[236:239], v[0:3]
	v_mfma_f32_16x16x32_bf16 v[52:55], v[200:203], v[216:219], v[52:55]
	v_mfma_f32_16x16x32_bf16 v[48:51], v[208:211], v[216:219], v[48:51]
	v_mfma_f32_16x16x32_bf16 v[36:39], v[200:203], v[224:227], v[36:39]
	v_mfma_f32_16x16x32_bf16 v[32:35], v[208:211], v[224:227], v[32:35]
	v_mfma_f32_16x16x32_bf16 v[20:23], v[200:203], v[232:235], v[20:23]
	v_mfma_f32_16x16x32_bf16 v[16:19], v[208:211], v[232:235], v[16:19]
	v_mfma_f32_16x16x32_bf16 v[4:7], v[200:203], v[240:243], v[4:7]
	v_mfma_f32_16x16x32_bf16 v[0:3], v[208:211], v[240:243], v[0:3]
	s_barrier
	s_add_i32 s52, 0, 0x18000
	v_add_u32_e32 v188, s52, v157
	s_add_i32 s53, 0, 0x1c000
	ds_read_b128 v[138:141], v188
	ds_read_b128 v[160:163], v188 offset:1024
	ds_read_b128 v[164:167], v188 offset:2048
	ds_read_b128 v[192:195], v188 offset:3072
	v_add_u32_e32 v188, s53, v157
	ds_read_b128 v[196:199], v188
	ds_read_b128 v[200:203], v188 offset:1024
	ds_read_b128 v[204:207], v188 offset:2048
	ds_read_b128 v[208:211], v188 offset:3072
	s_add_u32 s46, s46, s4
	s_addc_u32 s47, s47, s5
	s_mov_b32 m0, s39
	v_lshl_add_u64 v[252:253], s[46:47], 0, v[128:129]
	ds_read_b128 v[212:215], v159 offset:32768
	ds_read_b128 v[216:219], v159 offset:33792
	ds_read_b128 v[220:223], v159 offset:34816
	ds_read_b128 v[224:227], v159 offset:35840
	ds_read_b128 v[228:231], v159 offset:36864
	ds_read_b128 v[232:235], v159 offset:37888
	ds_read_b128 v[236:239], v159 offset:38912
	ds_read_b128 v[240:243], v159 offset:39936
	global_load_lds_dwordx4 v[252:253], off
	v_lshl_add_u64 v[252:253], s[46:47], 0, v[130:131]
	s_mov_b32 m0, s40
	s_nop 0
	global_load_lds_dwordx4 v[252:253], off
	s_waitcnt vmcnt(8)
	s_waitcnt lgkmcnt(0)
	s_barrier
	s_waitcnt lgkmcnt(0)
	v_mfma_f32_16x16x32_bf16 v[124:127], v[138:141], v[212:215], v[124:127]
	v_mfma_f32_16x16x32_bf16 v[120:123], v[164:167], v[212:215], v[120:123]
	v_mfma_f32_16x16x32_bf16 v[108:111], v[138:141], v[220:223], v[108:111]
	v_mfma_f32_16x16x32_bf16 v[104:107], v[164:167], v[220:223], v[104:107]
	v_mfma_f32_16x16x32_bf16 v[92:95], v[138:141], v[228:231], v[92:95]
	v_mfma_f32_16x16x32_bf16 v[88:91], v[164:167], v[228:231], v[88:91]
	v_mfma_f32_16x16x32_bf16 v[76:79], v[138:141], v[236:239], v[76:79]
	v_mfma_f32_16x16x32_bf16 v[72:75], v[164:167], v[236:239], v[72:75]
	v_mfma_f32_16x16x32_bf16 v[124:127], v[160:163], v[216:219], v[124:127]
	v_mfma_f32_16x16x32_bf16 v[120:123], v[192:195], v[216:219], v[120:123]
	v_mfma_f32_16x16x32_bf16 v[108:111], v[160:163], v[224:227], v[108:111]
	v_mfma_f32_16x16x32_bf16 v[104:107], v[192:195], v[224:227], v[104:107]
	v_mfma_f32_16x16x32_bf16 v[92:95], v[160:163], v[232:235], v[92:95]
	v_mfma_f32_16x16x32_bf16 v[88:91], v[192:195], v[232:235], v[88:91]
	v_mfma_f32_16x16x32_bf16 v[76:79], v[160:163], v[240:243], v[76:79]
	v_mfma_f32_16x16x32_bf16 v[72:75], v[192:195], v[240:243], v[72:75]
	v_mfma_f32_16x16x32_bf16 v[116:119], v[196:199], v[212:215], v[116:119]
	v_mfma_f32_16x16x32_bf16 v[112:115], v[204:207], v[212:215], v[112:115]
	v_mfma_f32_16x16x32_bf16 v[100:103], v[196:199], v[220:223], v[100:103]
	v_mfma_f32_16x16x32_bf16 v[96:99], v[204:207], v[220:223], v[96:99]
	v_mfma_f32_16x16x32_bf16 v[84:87], v[196:199], v[228:231], v[84:87]
	v_mfma_f32_16x16x32_bf16 v[80:83], v[204:207], v[228:231], v[80:83]
	v_mfma_f32_16x16x32_bf16 v[68:71], v[196:199], v[236:239], v[68:71]
	v_mfma_f32_16x16x32_bf16 v[64:67], v[204:207], v[236:239], v[64:67]
	v_mfma_f32_16x16x32_bf16 v[116:119], v[200:203], v[216:219], v[116:119]
	v_mfma_f32_16x16x32_bf16 v[112:115], v[208:211], v[216:219], v[112:115]
	v_mfma_f32_16x16x32_bf16 v[100:103], v[200:203], v[224:227], v[100:103]
	v_mfma_f32_16x16x32_bf16 v[96:99], v[208:211], v[224:227], v[96:99]
	v_mfma_f32_16x16x32_bf16 v[84:87], v[200:203], v[232:235], v[84:87]
	v_mfma_f32_16x16x32_bf16 v[80:83], v[208:211], v[232:235], v[80:83]
	v_mfma_f32_16x16x32_bf16 v[68:71], v[200:203], v[240:243], v[68:71]
	v_mfma_f32_16x16x32_bf16 v[64:67], v[208:211], v[240:243], v[64:67]
	s_barrier
; #define PG8_STAGE(bufoff, gbase, voff) do { _Pragma("unroll") for (int _i = 0; _i < 2; ++_i) \
;         __builtin_amdgcn_global_load_lds((const unsigned*)((const char*)(gbase) + (voff)[_i]), (PG8_LAS unsigned*)(lds + (bufoff) + ldsw + _i * 8192), 16, 0, 0); } while (0)
; #define PG8_LDA(dst, b, h) do { _Pragma("unroll") for (int m = 0; m < 4; ++m) _Pragma("unroll") for (int k = 0; k < 2; ++k) dst[m][k] = *(const PG8_LAS bf16x8*)(lds + PG8_SA(b, h) + aoff + m * 2048 + k * 1024); } while (0)
; #define PG8_MMA(ai, bj, At, Bt) do { __builtin_amdgcn_s_setprio(1); _Pragma("unroll") for (int m = 0; m < 4; ++m) _Pragma("unroll") for (int n = 0; n < 2; ++n) _Pragma("unroll") for (int k = 0; k < 2; ++k) \
;         acc[ai][bj][m][n] = __builtin_amdgcn_mfma_f32_16x16x32_bf16(Bt[n][k], At[m][k], acc[ai][bj][m][n], 0, 0, 0); __builtin_amdgcn_s_setprio(0); } while (0)
; #define PG8_WAIT_V(n) asm volatile("s_waitcnt vmcnt(" #n ")" ::: "memory")
; #define PG8_WAIT_L(n) asm volatile("s_waitcnt lgkmcnt(" #n ")" ::: "memory")
; #define PG8_BAR __builtin_amdgcn_s_barrier()
; #define PG8_SCHED __builtin_amdgcn_sched_barrier(0)
; template <class Epi, class Sched>
; __device__ __forceinline__ void gemm_phase(int wid_s, PG8_LAS unsigned char* lds, const Gemm g, const Sched& S, const Epi& E) {
;     ...
;             PG8_LDA(At, 1, 1); PG8_STAGE(PG8_SB(1, 0), b3, voffB); PG8_STAGE(PG8_SB(1, 1), b3 + hstepB, voffB); PG8_STAGE(PG8_SA(1, 0), a3, voffA);
;             PG8_WAIT_V(8); PG8_WAIT_L(0); PG8_BAR; PG8_MMA(1, 0, At, B0); PG8_MMA(1, 1, At, B1); PG8_BAR; PG8_SCHED;
;         }
	s_add_i32 s46, s52, s19
	v_lshl_add_u64 v[142:143], v[142:143], 0, s[96:97]
	s_mov_b32 m0, s46
	ds_read_b128 v[212:215], v159 offset:49152
	ds_read_b128 v[216:219], v159 offset:50176
	ds_read_b128 v[220:223], v159 offset:51200
	ds_read_b128 v[224:227], v159 offset:52224
	ds_read_b128 v[228:231], v159 offset:53248
	ds_read_b128 v[232:235], v159 offset:54272
	ds_read_b128 v[236:239], v159 offset:55296
	ds_read_b128 v[240:243], v159 offset:56320
	global_load_lds_dwordx4 v[142:143], off
	v_lshl_add_u64 v[142:143], v[154:155], 0, s[96:97]
	s_add_i32 m0, s46, 0x2000
	s_add_i32 s46, s53, s19
	global_load_lds_dwordx4 v[142:143], off
	v_lshl_add_u64 v[142:143], v[244:245], 0, s[96:97]
	s_mov_b32 m0, s46
	s_nop 0
	global_load_lds_dwordx4 v[142:143], off
	v_lshl_add_u64 v[142:143], v[246:247], 0, s[96:97]
	s_add_i32 m0, s46, 0x2000
	s_nop 0
	global_load_lds_dwordx4 v[142:143], off
	v_lshl_add_u64 v[142:143], v[248:249], 0, s[96:97]
	s_mov_b32 m0, s54
	s_nop 0
	global_load_lds_dwordx4 v[142:143], off
	v_lshl_add_u64 v[142:143], v[250:251], 0, s[96:97]
	s_mov_b32 m0, s55
	s_nop 0
	global_load_lds_dwordx4 v[142:143], off
	s_waitcnt vmcnt(8)
	s_waitcnt lgkmcnt(0)
	s_barrier
	s_waitcnt lgkmcnt(0)
	v_mfma_f32_16x16x32_bf16 v[60:63], v[138:141], v[212:215], v[60:63]
	v_mfma_f32_16x16x32_bf16 v[56:59], v[164:167], v[212:215], v[56:59]
	v_mfma_f32_16x16x32_bf16 v[44:47], v[138:141], v[220:223], v[44:47]
	v_mfma_f32_16x16x32_bf16 v[40:43], v[164:167], v[220:223], v[40:43]
	v_mfma_f32_16x16x32_bf16 v[28:31], v[138:141], v[228:231], v[28:31]
	v_mfma_f32_16x16x32_bf16 v[24:27], v[164:167], v[228:231], v[24:27]
	v_mfma_f32_16x16x32_bf16 v[12:15], v[138:141], v[236:239], v[12:15]
	v_mfma_f32_16x16x32_bf16 v[8:11], v[164:167], v[236:239], v[8:11]
	v_mfma_f32_16x16x32_bf16 v[60:63], v[160:163], v[216:219], v[60:63]
	v_mfma_f32_16x16x32_bf16 v[56:59], v[192:195], v[216:219], v[56:59]
	v_mfma_f32_16x16x32_bf16 v[44:47], v[160:163], v[224:227], v[44:47]
	v_mfma_f32_16x16x32_bf16 v[40:43], v[192:195], v[224:227], v[40:43]
	v_mfma_f32_16x16x32_bf16 v[28:31], v[160:163], v[232:235], v[28:31]
	v_mfma_f32_16x16x32_bf16 v[24:27], v[192:195], v[232:235], v[24:27]
	v_mfma_f32_16x16x32_bf16 v[12:15], v[160:163], v[240:243], v[12:15]
	v_mfma_f32_16x16x32_bf16 v[8:11], v[192:195], v[240:243], v[8:11]
	v_mfma_f32_16x16x32_bf16 v[52:55], v[196:199], v[212:215], v[52:55]
	v_mfma_f32_16x16x32_bf16 v[48:51], v[204:207], v[212:215], v[48:51]
	v_mfma_f32_16x16x32_bf16 v[36:39], v[196:199], v[220:223], v[36:39]
	v_mfma_f32_16x16x32_bf16 v[32:35], v[204:207], v[220:223], v[32:35]
	v_mfma_f32_16x16x32_bf16 v[20:23], v[196:199], v[228:231], v[20:23]
	v_mfma_f32_16x16x32_bf16 v[16:19], v[204:207], v[228:231], v[16:19]
	v_mfma_f32_16x16x32_bf16 v[4:7], v[196:199], v[236:239], v[4:7]
	v_mfma_f32_16x16x32_bf16 v[0:3], v[204:207], v[236:239], v[0:3]
	v_mfma_f32_16x16x32_bf16 v[52:55], v[200:203], v[216:219], v[52:55]
	v_mfma_f32_16x16x32_bf16 v[48:51], v[208:211], v[216:219], v[48:51]
	v_mfma_f32_16x16x32_bf16 v[36:39], v[200:203], v[224:227], v[36:39]
	v_mfma_f32_16x16x32_bf16 v[32:35], v[208:211], v[224:227], v[32:35]
	v_mfma_f32_16x16x32_bf16 v[20:23], v[200:203], v[232:235], v[20:23]
	v_mfma_f32_16x16x32_bf16 v[16:19], v[208:211], v[232:235], v[16:19]
	v_mfma_f32_16x16x32_bf16 v[4:7], v[200:203], v[240:243], v[4:7]
	v_mfma_f32_16x16x32_bf16 v[0:3], v[208:211], v[240:243], v[0:3]
	s_barrier
	s_add_u32 s33, s33, 0x100
	s_addc_u32 s50, s50, 0
	s_add_u32 s2, s2, 0x100
	s_addc_u32 s3, s3, 0
	s_cmp_ge_i32 s51, s45
	s_mov_b32 s46, s51
	s_cbranch_scc0 .LBB0_1602
	s_movk_i32 s51, 0x200
	s_movk_i32 s33, 0x300

; #define PG8_STAGE(bufoff, gbase, voff) do { _Pragma("unroll") for (int _i = 0; _i < 2; ++_i) \
;         __builtin_amdgcn_global_load_lds((const unsigned*)((const char*)(gbase) + (voff)[_i]), (PG8_LAS unsigned*)(lds + (bufoff) + ldsw + _i * 8192), 16, 0, 0); } while (0)
; #define PG8_LDA(dst, b, h) do { _Pragma("unroll") for (int m = 0; m < 4; ++m) _Pragma("unroll") for (int k = 0; k < 2; ++k) dst[m][k] = *(const PG8_LAS bf16x8*)(lds + PG8_SA(b, h) + aoff + m * 2048 + k * 1024); } while (0)
; #define PG8_LDB(dst, b, h) do { _Pragma("unroll") for (int n = 0; n < 2; ++n) _Pragma("unroll") for (int k = 0; k < 2; ++k) dst[n][k] = *(const PG8_LAS bf16x8*)(lds + PG8_SB(b, h) + boff + n * 2048 + k * 1024); } while (0)
; #define PG8_MMA(ai, bj, At, Bt) do { __builtin_amdgcn_s_setprio(1); _Pragma("unroll") for (int m = 0; m < 4; ++m) _Pragma("unroll") for (int n = 0; n < 2; ++n) _Pragma("unroll") for (int k = 0; k < 2; ++k) \
;         acc[ai][bj][m][n] = __builtin_amdgcn_mfma_f32_16x16x32_bf16(Bt[n][k], At[m][k], acc[ai][bj][m][n], 0, 0, 0); __builtin_amdgcn_s_setprio(0); } while (0)
; #define PG8_WAIT_V(n) asm volatile("s_waitcnt vmcnt(" #n ")" ::: "memory")
; #define PG8_WAIT_L(n) asm volatile("s_waitcnt lgkmcnt(" #n ")" ::: "memory")
; #define PG8_BAR __builtin_amdgcn_s_barrier()
; #define PG8_SCHED __builtin_amdgcn_sched_barrier(0)
; template <class Epi, class Sched>
; __device__ __forceinline__ void gemm_phase(int wid_s, PG8_LAS unsigned char* lds, const Gemm g, const Sched& S, const Epi& E) {
;     ...
;             const bool last = (t == nt - 2);
;             const char* a1 = cA + (size_t)(t + 1) * kstep;
;             const char* a2 = last ? nA : cA + (size_t)(t + 2) * kstep; const char* b2 = last ? nB : cB + (size_t)(t + 2) * kstep;
;             const char* a3 = a2 + kstep; const char* b3 = b2 + kstep;
;             PG8_LDB(B0, 0, 0); PG8_LDB(B1, 0, 1); PG8_SCHED; PG8_LDA(At, 0, 0); PG8_STAGE(PG8_SA(1, 1), a1 + hstepA, voffA);
;             PG8_WAIT_V(8); PG8_WAIT_L(0); PG8_BAR; PG8_MMA(0, 0, At, B0); PG8_MMA(0, 1, At, B1); PG8_BAR; PG8_SCHED;
;             PG8_LDA(At, 0, 1); PG8_STAGE(PG8_SB(0, 0), b2, voffB); PG8_STAGE(PG8_SB(0, 1), b2 + hstepB, voffB); PG8_STAGE(PG8_SA(0, 0), a2, voffA);
;             PG8_WAIT_V(8); PG8_WAIT_L(0); PG8_BAR; PG8_MMA(1, 0, At, B0); PG8_MMA(1, 1, At, B1); PG8_BAR; PG8_SCHED;
.LBB0_1717:
	s_add_i32 s44, s34, 2
	s_add_u32 s45, s4, 0x80
	s_addc_u32 s35, s5, 0
	s_add_i32 s18, 0, 0x10000
	s_cmp_eq_u32 s95, s34
	s_cselect_b32 s35, s29, s35
	s_cselect_b32 s34, s28, s45
	v_add_u32_e32 v142, s18, v157
	s_cselect_b32 vcc_hi, s31, s51
	s_cselect_b32 vcc_lo, s30, s33
	s_add_i32 s45, 0, 0x14000
	ds_read_b128 v[138:141], v142
	ds_read_b128 v[160:163], v142 offset:1024
	ds_read_b128 v[164:167], v142 offset:2048
	ds_read_b128 v[192:195], v142 offset:3072
	v_add_u32_e32 v142, s45, v157
	ds_read_b128 v[196:199], v142
	ds_read_b128 v[200:203], v142 offset:1024
	ds_read_b128 v[204:207], v142 offset:2048
	ds_read_b128 v[208:211], v142 offset:3072
	v_lshl_add_u64 v[142:143], s[4:5], 0, v[136:137]
	s_add_i32 m0, s52, 0xc000
	ds_read_b128 v[212:215], v159
	ds_read_b128 v[216:219], v159 offset:1024
	ds_read_b128 v[220:223], v159 offset:2048
	ds_read_b128 v[224:227], v159 offset:3072
	ds_read_b128 v[228:231], v159 offset:4096
	ds_read_b128 v[232:235], v159 offset:5120
	ds_read_b128 v[236:239], v159 offset:6144
	ds_read_b128 v[240:243], v159 offset:7168
	global_load_lds_dwordx4 v[142:143], off
	v_lshl_add_u64 v[142:143], s[4:5], 0, v[134:135]
	s_add_i32 m0, s52, 0xe000
	s_nop 0
	global_load_lds_dwordx4 v[142:143], off
	s_waitcnt vmcnt(8)
	s_waitcnt lgkmcnt(0)
	s_barrier
	s_waitcnt lgkmcnt(0)
	v_mfma_f32_16x16x32_bf16 v[124:127], v[138:141], v[212:215], v[124:127]
	v_mfma_f32_16x16x32_bf16 v[120:123], v[164:167], v[212:215], v[120:123]
	v_mfma_f32_16x16x32_bf16 v[108:111], v[138:141], v[220:223], v[108:111]
	v_mfma_f32_16x16x32_bf16 v[104:107], v[164:167], v[220:223], v[104:107]
	v_mfma_f32_16x16x32_bf16 v[92:95], v[138:141], v[228:231], v[92:95]
	v_mfma_f32_16x16x32_bf16 v[88:91], v[164:167], v[228:231], v[88:91]
	v_mfma_f32_16x16x32_bf16 v[76:79], v[138:141], v[236:239], v[76:79]
	v_mfma_f32_16x16x32_bf16 v[72:75], v[164:167], v[236:239], v[72:75]
	v_mfma_f32_16x16x32_bf16 v[124:127], v[160:163], v[216:219], v[124:127]
	v_mfma_f32_16x16x32_bf16 v[120:123], v[192:195], v[216:219], v[120:123]
	v_mfma_f32_16x16x32_bf16 v[108:111], v[160:163], v[224:227], v[108:111]
	v_mfma_f32_16x16x32_bf16 v[104:107], v[192:195], v[224:227], v[104:107]
	v_mfma_f32_16x16x32_bf16 v[92:95], v[160:163], v[232:235], v[92:95]
	v_mfma_f32_16x16x32_bf16 v[88:91], v[192:195], v[232:235], v[88:91]
	v_mfma_f32_16x16x32_bf16 v[76:79], v[160:163], v[240:243], v[76:79]
	v_mfma_f32_16x16x32_bf16 v[72:75], v[192:195], v[240:243], v[72:75]
	v_mfma_f32_16x16x32_bf16 v[116:119], v[196:199], v[212:215], v[116:119]
	v_mfma_f32_16x16x32_bf16 v[112:115], v[204:207], v[212:215], v[112:115]
	v_mfma_f32_16x16x32_bf16 v[100:103], v[196:199], v[220:223], v[100:103]
	v_mfma_f32_16x16x32_bf16 v[96:99], v[204:207], v[220:223], v[96:99]
	v_mfma_f32_16x16x32_bf16 v[84:87], v[196:199], v[228:231], v[84:87]
	v_mfma_f32_16x16x32_bf16 v[80:83], v[204:207], v[228:231], v[80:83]
	v_mfma_f32_16x16x32_bf16 v[68:71], v[196:199], v[236:239], v[68:71]
	v_mfma_f32_16x16x32_bf16 v[64:67], v[204:207], v[236:239], v[64:67]
	v_mfma_f32_16x16x32_bf16 v[116:119], v[200:203], v[216:219], v[116:119]
	v_mfma_f32_16x16x32_bf16 v[112:115], v[208:211], v[216:219], v[112:115]
	v_mfma_f32_16x16x32_bf16 v[100:103], v[200:203], v[224:227], v[100:103]
	v_mfma_f32_16x16x32_bf16 v[96:99], v[208:211], v[224:227], v[96:99]
	v_mfma_f32_16x16x32_bf16 v[84:87], v[200:203], v[232:235], v[84:87]
	v_mfma_f32_16x16x32_bf16 v[80:83], v[208:211], v[232:235], v[80:83]
	v_mfma_f32_16x16x32_bf16 v[68:71], v[200:203], v[240:243], v[68:71]
	v_mfma_f32_16x16x32_bf16 v[64:67], v[208:211], v[240:243], v[64:67]
	s_barrier
	s_add_i32 s18, s18, s47
	v_lshl_add_u64 v[142:143], vcc, 0, v[144:145]
	s_mov_b32 m0, s18
	ds_read_b128 v[212:215], v159 offset:16384
	ds_read_b128 v[216:219], v159 offset:17408
	ds_read_b128 v[220:223], v159 offset:18432
	ds_read_b128 v[224:227], v159 offset:19456
	ds_read_b128 v[228:231], v159 offset:20480
	ds_read_b128 v[232:235], v159 offset:21504
	ds_read_b128 v[236:239], v159 offset:22528
	ds_read_b128 v[240:243], v159 offset:23552
	global_load_lds_dwordx4 v[142:143], off
	s_add_i32 m0, s18, 0x2000
	v_lshl_add_u64 v[244:245], vcc, 0, v[132:133]
	s_add_u32 vcc_lo, vcc_lo, s12
	s_addc_u32 vcc_hi, vcc_hi, s13
	s_add_i32 s18, s45, s47
	global_load_lds_dwordx4 v[244:245], off
	v_lshl_add_u64 v[246:247], vcc, 0, v[144:145]
	s_mov_b32 m0, s18
	v_lshl_add_u64 v[248:249], vcc, 0, v[132:133]
	global_load_lds_dwordx4 v[246:247], off
	s_add_i32 m0, s18, 0x2000
	v_lshl_add_u64 v[250:251], s[34:35], 0, v[128:129]
	global_load_lds_dwordx4 v[248:249], off
	s_mov_b32 m0, s52
	v_lshl_add_u64 v[252:253], s[34:35], 0, v[130:131]
	global_load_lds_dwordx4 v[250:251], off
	s_mov_b32 m0, s53
	s_nop 0
	global_load_lds_dwordx4 v[252:253], off
	s_waitcnt vmcnt(8)
	s_waitcnt lgkmcnt(0)
	s_barrier
; #define PG8_STAGE(bufoff, gbase, voff) do { _Pragma("unroll") for (int _i = 0; _i < 2; ++_i) \
;         __builtin_amdgcn_global_load_lds((const unsigned*)((const char*)(gbase) + (voff)[_i]), (PG8_LAS unsigned*)(lds + (bufoff) + ldsw + _i * 8192), 16, 0, 0); } while (0)
; #define PG8_LDA(dst, b, h) do { _Pragma("unroll") for (int m = 0; m < 4; ++m) _Pragma("unroll") for (int k = 0; k < 2; ++k) dst[m][k] = *(const PG8_LAS bf16x8*)(lds + PG8_SA(b, h) + aoff + m * 2048 + k * 1024); } while (0)
; #define PG8_LDB(dst, b, h) do { _Pragma("unroll") for (int n = 0; n < 2; ++n) _Pragma("unroll") for (int k = 0; k < 2; ++k) dst[n][k] = *(const PG8_LAS bf16x8*)(lds + PG8_SB(b, h) + boff + n * 2048 + k * 1024); } while (0)
; #define PG8_MMA(ai, bj, At, Bt) do { __builtin_amdgcn_s_setprio(1); _Pragma("unroll") for (int m = 0; m < 4; ++m) _Pragma("unroll") for (int n = 0; n < 2; ++n) _Pragma("unroll") for (int k = 0; k < 2; ++k) \
;         acc[ai][bj][m][n] = __builtin_amdgcn_mfma_f32_16x16x32_bf16(Bt[n][k], At[m][k], acc[ai][bj][m][n], 0, 0, 0); __builtin_amdgcn_s_setprio(0); } while (0)
; #define PG8_WAIT_V(n) asm volatile("s_waitcnt vmcnt(" #n ")" ::: "memory")
; #define PG8_WAIT_L(n) asm volatile("s_waitcnt lgkmcnt(" #n ")" ::: "memory")
; #define PG8_BAR __builtin_amdgcn_s_barrier()
; #define PG8_SCHED __builtin_amdgcn_sched_barrier(0)
; template <class Epi, class Sched>
; __device__ __forceinline__ void gemm_phase(int wid_s, PG8_LAS unsigned char* lds, const Gemm g, const Sched& S, const Epi& E) {
;     ...
;             PG8_WAIT_V(8); PG8_WAIT_L(0); PG8_BAR; PG8_MMA(1, 0, At, B0); PG8_MMA(1, 1, At, B1); PG8_BAR; PG8_SCHED;
;             PG8_LDB(B0, 1, 0); PG8_LDB(B1, 1, 1); PG8_SCHED; PG8_LDA(At, 1, 0); PG8_STAGE(PG8_SA(0, 1), a2 + hstepA, voffA);
;             PG8_WAIT_V(8); PG8_WAIT_L(0); PG8_BAR; PG8_MMA(0, 0, At, B0); PG8_MMA(0, 1, At, B1); PG8_BAR; PG8_SCHED;
	s_waitcnt lgkmcnt(0)
	v_mfma_f32_16x16x32_bf16 v[60:63], v[138:141], v[212:215], v[60:63]
	v_mfma_f32_16x16x32_bf16 v[56:59], v[164:167], v[212:215], v[56:59]
	v_mfma_f32_16x16x32_bf16 v[44:47], v[138:141], v[220:223], v[44:47]
	v_mfma_f32_16x16x32_bf16 v[40:43], v[164:167], v[220:223], v[40:43]
	v_mfma_f32_16x16x32_bf16 v[28:31], v[138:141], v[228:231], v[28:31]
	v_mfma_f32_16x16x32_bf16 v[24:27], v[164:167], v[228:231], v[24:27]
	v_mfma_f32_16x16x32_bf16 v[12:15], v[138:141], v[236:239], v[12:15]
	v_mfma_f32_16x16x32_bf16 v[8:11], v[164:167], v[236:239], v[8:11]
	v_mfma_f32_16x16x32_bf16 v[60:63], v[160:163], v[216:219], v[60:63]
	v_mfma_f32_16x16x32_bf16 v[56:59], v[192:195], v[216:219], v[56:59]
	v_mfma_f32_16x16x32_bf16 v[44:47], v[160:163], v[224:227], v[44:47]
	v_mfma_f32_16x16x32_bf16 v[40:43], v[192:195], v[224:227], v[40:43]
	v_mfma_f32_16x16x32_bf16 v[28:31], v[160:163], v[232:235], v[28:31]
	v_mfma_f32_16x16x32_bf16 v[24:27], v[192:195], v[232:235], v[24:27]
	v_mfma_f32_16x16x32_bf16 v[12:15], v[160:163], v[240:243], v[12:15]
	v_mfma_f32_16x16x32_bf16 v[8:11], v[192:195], v[240:243], v[8:11]
	v_mfma_f32_16x16x32_bf16 v[52:55], v[196:199], v[212:215], v[52:55]
	v_mfma_f32_16x16x32_bf16 v[48:51], v[204:207], v[212:215], v[48:51]
	v_mfma_f32_16x16x32_bf16 v[36:39], v[196:199], v[220:223], v[36:39]
	v_mfma_f32_16x16x32_bf16 v[32:35], v[204:207], v[220:223], v[32:35]
	v_mfma_f32_16x16x32_bf16 v[20:23], v[196:199], v[228:231], v[20:23]
	v_mfma_f32_16x16x32_bf16 v[16:19], v[204:207], v[228:231], v[16:19]
	v_mfma_f32_16x16x32_bf16 v[4:7], v[196:199], v[236:239], v[4:7]
	v_mfma_f32_16x16x32_bf16 v[0:3], v[204:207], v[236:239], v[0:3]
	v_mfma_f32_16x16x32_bf16 v[52:55], v[200:203], v[216:219], v[52:55]
	v_mfma_f32_16x16x32_bf16 v[48:51], v[208:211], v[216:219], v[48:51]
	v_mfma_f32_16x16x32_bf16 v[36:39], v[200:203], v[224:227], v[36:39]
	v_mfma_f32_16x16x32_bf16 v[32:35], v[208:211], v[224:227], v[32:35]
	v_mfma_f32_16x16x32_bf16 v[20:23], v[200:203], v[232:235], v[20:23]
	v_mfma_f32_16x16x32_bf16 v[16:19], v[208:211], v[232:235], v[16:19]
	v_mfma_f32_16x16x32_bf16 v[4:7], v[200:203], v[240:243], v[4:7]
	v_mfma_f32_16x16x32_bf16 v[0:3], v[208:211], v[240:243], v[0:3]
	s_barrier
	s_add_i32 s18, 0, 0x18000
	v_add_u32_e32 v188, s18, v157
	s_add_i32 s45, 0, 0x1c000
	ds_read_b128 v[138:141], v188
	ds_read_b128 v[160:163], v188 offset:1024
	ds_read_b128 v[164:167], v188 offset:2048
	ds_read_b128 v[192:195], v188 offset:3072
	v_add_u32_e32 v188, s45, v157
	ds_read_b128 v[196:199], v188
	ds_read_b128 v[200:203], v188 offset:1024
	ds_read_b128 v[204:207], v188 offset:2048
	ds_read_b128 v[208:211], v188 offset:3072
	s_add_u32 s34, s34, s10
	s_addc_u32 s35, s35, s11
	s_mov_b32 m0, s54
	v_lshl_add_u64 v[188:189], s[34:35], 0, v[128:129]
	ds_read_b128 v[212:215], v159 offset:32768
	ds_read_b128 v[216:219], v159 offset:33792
	ds_read_b128 v[220:223], v159 offset:34816
	ds_read_b128 v[224:227], v159 offset:35840
	ds_read_b128 v[228:231], v159 offset:36864
	ds_read_b128 v[232:235], v159 offset:37888
	ds_read_b128 v[236:239], v159 offset:38912
	ds_read_b128 v[240:243], v159 offset:39936
	global_load_lds_dwordx4 v[188:189], off
	v_lshl_add_u64 v[188:189], s[34:35], 0, v[130:131]
	s_mov_b32 m0, s55
	s_nop 0
	global_load_lds_dwordx4 v[188:189], off
	s_waitcnt vmcnt(8)
	s_waitcnt lgkmcnt(0)
	s_barrier
	s_waitcnt lgkmcnt(0)
	v_mfma_f32_16x16x32_bf16 v[124:127], v[138:141], v[212:215], v[124:127]
	v_mfma_f32_16x16x32_bf16 v[120:123], v[164:167], v[212:215], v[120:123]
	v_mfma_f32_16x16x32_bf16 v[108:111], v[138:141], v[220:223], v[108:111]
	v_mfma_f32_16x16x32_bf16 v[104:107], v[164:167], v[220:223], v[104:107]
	v_mfma_f32_16x16x32_bf16 v[92:95], v[138:141], v[228:231], v[92:95]
	v_mfma_f32_16x16x32_bf16 v[88:91], v[164:167], v[228:231], v[88:91]
	v_mfma_f32_16x16x32_bf16 v[76:79], v[138:141], v[236:239], v[76:79]
	v_mfma_f32_16x16x32_bf16 v[72:75], v[164:167], v[236:239], v[72:75]
	v_mfma_f32_16x16x32_bf16 v[124:127], v[160:163], v[216:219], v[124:127]
	v_mfma_f32_16x16x32_bf16 v[120:123], v[192:195], v[216:219], v[120:123]
	v_mfma_f32_16x16x32_bf16 v[108:111], v[160:163], v[224:227], v[108:111]
	v_mfma_f32_16x16x32_bf16 v[104:107], v[192:195], v[224:227], v[104:107]
	v_mfma_f32_16x16x32_bf16 v[92:95], v[160:163], v[232:235], v[92:95]
	v_mfma_f32_16x16x32_bf16 v[88:91], v[192:195], v[232:235], v[88:91]
	v_mfma_f32_16x16x32_bf16 v[76:79], v[160:163], v[240:243], v[76:79]
	v_mfma_f32_16x16x32_bf16 v[72:75], v[192:195], v[240:243], v[72:75]
	v_mfma_f32_16x16x32_bf16 v[116:119], v[196:199], v[212:215], v[116:119]
	v_mfma_f32_16x16x32_bf16 v[112:115], v[204:207], v[212:215], v[112:115]
	v_mfma_f32_16x16x32_bf16 v[100:103], v[196:199], v[220:223], v[100:103]
	v_mfma_f32_16x16x32_bf16 v[96:99], v[204:207], v[220:223], v[96:99]
	v_mfma_f32_16x16x32_bf16 v[84:87], v[196:199], v[228:231], v[84:87]
	v_mfma_f32_16x16x32_bf16 v[80:83], v[204:207], v[228:231], v[80:83]
	v_mfma_f32_16x16x32_bf16 v[68:71], v[196:199], v[236:239], v[68:71]
	v_mfma_f32_16x16x32_bf16 v[64:67], v[204:207], v[236:239], v[64:67]
	v_mfma_f32_16x16x32_bf16 v[116:119], v[200:203], v[216:219], v[116:119]
	v_mfma_f32_16x16x32_bf16 v[112:115], v[208:211], v[216:219], v[112:115]
	v_mfma_f32_16x16x32_bf16 v[100:103], v[200:203], v[224:227], v[100:103]
	v_mfma_f32_16x16x32_bf16 v[96:99], v[208:211], v[224:227], v[96:99]
	v_mfma_f32_16x16x32_bf16 v[84:87], v[200:203], v[232:235], v[84:87]
	v_mfma_f32_16x16x32_bf16 v[80:83], v[208:211], v[232:235], v[80:83]
	v_mfma_f32_16x16x32_bf16 v[68:71], v[200:203], v[240:243], v[68:71]
	v_mfma_f32_16x16x32_bf16 v[64:67], v[208:211], v[240:243], v[64:67]
	s_barrier
; #define PG8_STAGE(bufoff, gbase, voff) do { _Pragma("unroll") for (int _i = 0; _i < 2; ++_i) \
;         __builtin_amdgcn_global_load_lds((const unsigned*)((const char*)(gbase) + (voff)[_i]), (PG8_LAS unsigned*)(lds + (bufoff) + ldsw + _i * 8192), 16, 0, 0); } while (0)
; #define PG8_LDA(dst, b, h) do { _Pragma("unroll") for (int m = 0; m < 4; ++m) _Pragma("unroll") for (int k = 0; k < 2; ++k) dst[m][k] = *(const PG8_LAS bf16x8*)(lds + PG8_SA(b, h) + aoff + m * 2048 + k * 1024); } while (0)
; #define PG8_MMA(ai, bj, At, Bt) do { __builtin_amdgcn_s_setprio(1); _Pragma("unroll") for (int m = 0; m < 4; ++m) _Pragma("unroll") for (int n = 0; n < 2; ++n) _Pragma("unroll") for (int k = 0; k < 2; ++k) \
;         acc[ai][bj][m][n] = __builtin_amdgcn_mfma_f32_16x16x32_bf16(Bt[n][k], At[m][k], acc[ai][bj][m][n], 0, 0, 0); __builtin_amdgcn_s_setprio(0); } while (0)
; #define PG8_WAIT_V(n) asm volatile("s_waitcnt vmcnt(" #n ")" ::: "memory")
; #define PG8_WAIT_L(n) asm volatile("s_waitcnt lgkmcnt(" #n ")" ::: "memory")
; #define PG8_BAR __builtin_amdgcn_s_barrier()
; #define PG8_SCHED __builtin_amdgcn_sched_barrier(0)
; template <class Epi, class Sched>
; __device__ __forceinline__ void gemm_phase(int wid_s, PG8_LAS unsigned char* lds, const Gemm g, const Sched& S, const Epi& E) {
;     ...
;             PG8_LDA(At, 1, 1); PG8_STAGE(PG8_SB(1, 0), b3, voffB); PG8_STAGE(PG8_SB(1, 1), b3 + hstepB, voffB); PG8_STAGE(PG8_SA(1, 0), a3, voffA);
;             PG8_WAIT_V(8); PG8_WAIT_L(0); PG8_BAR; PG8_MMA(1, 0, At, B0); PG8_MMA(1, 1, At, B1); PG8_BAR; PG8_SCHED;
;         }
	s_add_i32 s18, s18, s47
	v_lshl_add_u64 v[142:143], v[142:143], 0, s[96:97]
	s_mov_b32 m0, s18
	ds_read_b128 v[212:215], v159 offset:49152
	ds_read_b128 v[216:219], v159 offset:50176
	ds_read_b128 v[220:223], v159 offset:51200
	ds_read_b128 v[224:227], v159 offset:52224
	ds_read_b128 v[228:231], v159 offset:53248
	ds_read_b128 v[232:235], v159 offset:54272
	ds_read_b128 v[236:239], v159 offset:55296
	ds_read_b128 v[240:243], v159 offset:56320
	global_load_lds_dwordx4 v[142:143], off
	v_lshl_add_u64 v[142:143], v[244:245], 0, s[96:97]
	s_add_i32 m0, s18, 0x2000
	s_add_i32 s18, s45, s47
	global_load_lds_dwordx4 v[142:143], off
	v_lshl_add_u64 v[142:143], v[246:247], 0, s[96:97]
	s_mov_b32 m0, s18
	s_nop 0
	global_load_lds_dwordx4 v[142:143], off
	v_lshl_add_u64 v[142:143], v[248:249], 0, s[96:97]
	s_add_i32 m0, s18, 0x2000
	s_nop 0
	global_load_lds_dwordx4 v[142:143], off
	v_lshl_add_u64 v[142:143], v[250:251], 0, s[96:97]
	s_mov_b32 m0, s56
	s_nop 0
	global_load_lds_dwordx4 v[142:143], off
	v_lshl_add_u64 v[142:143], v[252:253], 0, s[96:97]
	s_mov_b32 m0, s57
	s_nop 0
	global_load_lds_dwordx4 v[142:143], off
	s_waitcnt vmcnt(8)
	s_waitcnt lgkmcnt(0)
	s_barrier
	s_waitcnt lgkmcnt(0)
	v_mfma_f32_16x16x32_bf16 v[60:63], v[138:141], v[212:215], v[60:63]
	v_mfma_f32_16x16x32_bf16 v[56:59], v[164:167], v[212:215], v[56:59]
	v_mfma_f32_16x16x32_bf16 v[44:47], v[138:141], v[220:223], v[44:47]
	v_mfma_f32_16x16x32_bf16 v[40:43], v[164:167], v[220:223], v[40:43]
	v_mfma_f32_16x16x32_bf16 v[28:31], v[138:141], v[228:231], v[28:31]
	v_mfma_f32_16x16x32_bf16 v[24:27], v[164:167], v[228:231], v[24:27]
	v_mfma_f32_16x16x32_bf16 v[12:15], v[138:141], v[236:239], v[12:15]
	v_mfma_f32_16x16x32_bf16 v[8:11], v[164:167], v[236:239], v[8:11]
	v_mfma_f32_16x16x32_bf16 v[60:63], v[160:163], v[216:219], v[60:63]
	v_mfma_f32_16x16x32_bf16 v[56:59], v[192:195], v[216:219], v[56:59]
	v_mfma_f32_16x16x32_bf16 v[44:47], v[160:163], v[224:227], v[44:47]
	v_mfma_f32_16x16x32_bf16 v[40:43], v[192:195], v[224:227], v[40:43]
	v_mfma_f32_16x16x32_bf16 v[28:31], v[160:163], v[232:235], v[28:31]
	v_mfma_f32_16x16x32_bf16 v[24:27], v[192:195], v[232:235], v[24:27]
	v_mfma_f32_16x16x32_bf16 v[12:15], v[160:163], v[240:243], v[12:15]
	v_mfma_f32_16x16x32_bf16 v[8:11], v[192:195], v[240:243], v[8:11]
	v_mfma_f32_16x16x32_bf16 v[52:55], v[196:199], v[212:215], v[52:55]
	v_mfma_f32_16x16x32_bf16 v[48:51], v[204:207], v[212:215], v[48:51]
	v_mfma_f32_16x16x32_bf16 v[36:39], v[196:199], v[220:223], v[36:39]
	v_mfma_f32_16x16x32_bf16 v[32:35], v[204:207], v[220:223], v[32:35]
	v_mfma_f32_16x16x32_bf16 v[20:23], v[196:199], v[228:231], v[20:23]
	v_mfma_f32_16x16x32_bf16 v[16:19], v[204:207], v[228:231], v[16:19]
	v_mfma_f32_16x16x32_bf16 v[4:7], v[196:199], v[236:239], v[4:7]
	v_mfma_f32_16x16x32_bf16 v[0:3], v[204:207], v[236:239], v[0:3]
	v_mfma_f32_16x16x32_bf16 v[52:55], v[200:203], v[216:219], v[52:55]
	v_mfma_f32_16x16x32_bf16 v[48:51], v[208:211], v[216:219], v[48:51]
	v_mfma_f32_16x16x32_bf16 v[36:39], v[200:203], v[224:227], v[36:39]
	v_mfma_f32_16x16x32_bf16 v[32:35], v[208:211], v[224:227], v[32:35]
	v_mfma_f32_16x16x32_bf16 v[20:23], v[200:203], v[232:235], v[20:23]
	v_mfma_f32_16x16x32_bf16 v[16:19], v[208:211], v[232:235], v[16:19]
	v_mfma_f32_16x16x32_bf16 v[4:7], v[200:203], v[240:243], v[4:7]
	v_mfma_f32_16x16x32_bf16 v[0:3], v[208:211], v[240:243], v[0:3]
	s_barrier
	s_add_u32 s33, s33, 0x100
	s_addc_u32 s51, s51, 0
	s_add_u32 s4, s4, 0x100
	s_addc_u32 s5, s5, 0
	s_cmp_ge_i32 s44, s94
	s_mov_b32 s34, s44
	s_cbranch_scc0 .LBB0_1717
	s_movk_i32 s33, 0x300

; #define PG8_STAGE(bufoff, gbase, voff) do { _Pragma("unroll") for (int _i = 0; _i < 2; ++_i) \
;         __builtin_amdgcn_global_load_lds((const unsigned*)((const char*)(gbase) + (voff)[_i]), (PG8_LAS unsigned*)(lds + (bufoff) + ldsw + _i * 8192), 16, 0, 0); } while (0)
; #define PG8_LDA(dst, b, h) do { _Pragma("unroll") for (int m = 0; m < 4; ++m) _Pragma("unroll") for (int k = 0; k < 2; ++k) dst[m][k] = *(const PG8_LAS bf16x8*)(lds + PG8_SA(b, h) + aoff + m * 2048 + k * 1024); } while (0)
; #define PG8_LDB(dst, b, h) do { _Pragma("unroll") for (int n = 0; n < 2; ++n) _Pragma("unroll") for (int k = 0; k < 2; ++k) dst[n][k] = *(const PG8_LAS bf16x8*)(lds + PG8_SB(b, h) + boff + n * 2048 + k * 1024); } while (0)
; #define PG8_MMA(ai, bj, At, Bt) do { __builtin_amdgcn_s_setprio(1); _Pragma("unroll") for (int m = 0; m < 4; ++m) _Pragma("unroll") for (int n = 0; n < 2; ++n) _Pragma("unroll") for (int k = 0; k < 2; ++k) \
;         acc[ai][bj][m][n] = __builtin_amdgcn_mfma_f32_16x16x32_bf16(Bt[n][k], At[m][k], acc[ai][bj][m][n], 0, 0, 0); __builtin_amdgcn_s_setprio(0); } while (0)
; #define PG8_WAIT_V(n) asm volatile("s_waitcnt vmcnt(" #n ")" ::: "memory")
; #define PG8_WAIT_L(n) asm volatile("s_waitcnt lgkmcnt(" #n ")" ::: "memory")
; #define PG8_BAR __builtin_amdgcn_s_barrier()
; #define PG8_SCHED __builtin_amdgcn_sched_barrier(0)
; template <class Epi, class Sched>
; __device__ __forceinline__ void gemm_phase(int wid_s, PG8_LAS unsigned char* lds, const Gemm g, const Sched& S, const Epi& E) {
;     ...
;             const bool last = (t == nt - 2);
;             const char* a1 = cA + (size_t)(t + 1) * kstep;
;             const char* a2 = last ? nA : cA + (size_t)(t + 2) * kstep; const char* b2 = last ? nB : cB + (size_t)(t + 2) * kstep;
;             const char* a3 = a2 + kstep; const char* b3 = b2 + kstep;
;             PG8_LDB(B0, 0, 0); PG8_LDB(B1, 0, 1); PG8_SCHED; PG8_LDA(At, 0, 0); PG8_STAGE(PG8_SA(1, 1), a1 + hstepA, voffA);
;             PG8_WAIT_V(8); PG8_WAIT_L(0); PG8_BAR; PG8_MMA(0, 0, At, B0); PG8_MMA(0, 1, At, B1); PG8_BAR; PG8_SCHED;
;             PG8_LDA(At, 0, 1); PG8_STAGE(PG8_SB(0, 0), b2, voffB); PG8_STAGE(PG8_SB(0, 1), b2 + hstepB, voffB); PG8_STAGE(PG8_SA(0, 0), a2, voffA);
;             PG8_WAIT_V(8); PG8_WAIT_L(0); PG8_BAR; PG8_MMA(1, 0, At, B0); PG8_MMA(1, 1, At, B1); PG8_BAR; PG8_SCHED;
.LBB0_1845:
	s_add_i32 s57, s28, 2
	s_add_u32 s92, s26, 0x80
	s_addc_u32 s29, s27, 0
	s_add_i32 vcc_lo, 0, 0x10000
	s_cmp_eq_u32 s49, s28
	s_cselect_b32 s29, s23, s29
	s_cselect_b32 s28, s22, s92
	v_add_u32_e32 v155, vcc_lo, v143
	s_cselect_b32 s95, s25, s56
	s_cselect_b32 s94, s24, s33
	s_add_i32 s92, 0, 0x14000
	ds_read_b128 v[156:159], v155
	ds_read_b128 v[160:163], v155 offset:1024
	ds_read_b128 v[164:167], v155 offset:2048
	ds_read_b128 v[192:195], v155 offset:3072
	v_add_u32_e32 v155, s92, v143
	ds_read_b128 v[196:199], v155
	ds_read_b128 v[200:203], v155 offset:1024
	ds_read_b128 v[204:207], v155 offset:2048
	ds_read_b128 v[208:211], v155 offset:3072
	v_lshl_add_u64 v[188:189], s[26:27], 0, v[140:141]
	s_add_i32 m0, s40, 0xc000
	ds_read_b128 v[212:215], v154
	ds_read_b128 v[216:219], v154 offset:1024
	ds_read_b128 v[220:223], v154 offset:2048
	ds_read_b128 v[224:227], v154 offset:3072
	ds_read_b128 v[228:231], v154 offset:4096
	ds_read_b128 v[232:235], v154 offset:5120
	ds_read_b128 v[236:239], v154 offset:6144
	ds_read_b128 v[240:243], v154 offset:7168
	global_load_lds_dwordx4 v[188:189], off
	v_lshl_add_u64 v[188:189], s[26:27], 0, v[138:139]
	s_add_i32 m0, s40, 0xe000
	s_nop 0
	global_load_lds_dwordx4 v[188:189], off
	s_waitcnt vmcnt(8)
	s_waitcnt lgkmcnt(0)
	s_barrier
	s_waitcnt lgkmcnt(0)
	v_mfma_f32_16x16x32_bf16 v[124:127], v[156:159], v[212:215], v[124:127]
	v_mfma_f32_16x16x32_bf16 v[120:123], v[164:167], v[212:215], v[120:123]
	v_mfma_f32_16x16x32_bf16 v[112:115], v[156:159], v[220:223], v[112:115]
	v_mfma_f32_16x16x32_bf16 v[108:111], v[164:167], v[220:223], v[108:111]
	v_mfma_f32_16x16x32_bf16 v[92:95], v[156:159], v[228:231], v[92:95]
	v_mfma_f32_16x16x32_bf16 v[88:91], v[164:167], v[228:231], v[88:91]
	v_mfma_f32_16x16x32_bf16 v[76:79], v[156:159], v[236:239], v[76:79]
	v_mfma_f32_16x16x32_bf16 v[72:75], v[164:167], v[236:239], v[72:75]
	v_mfma_f32_16x16x32_bf16 v[124:127], v[160:163], v[216:219], v[124:127]
	v_mfma_f32_16x16x32_bf16 v[120:123], v[192:195], v[216:219], v[120:123]
	v_mfma_f32_16x16x32_bf16 v[112:115], v[160:163], v[224:227], v[112:115]
	v_mfma_f32_16x16x32_bf16 v[108:111], v[192:195], v[224:227], v[108:111]
	v_mfma_f32_16x16x32_bf16 v[92:95], v[160:163], v[232:235], v[92:95]
	v_mfma_f32_16x16x32_bf16 v[88:91], v[192:195], v[232:235], v[88:91]
	v_mfma_f32_16x16x32_bf16 v[76:79], v[160:163], v[240:243], v[76:79]
	v_mfma_f32_16x16x32_bf16 v[72:75], v[192:195], v[240:243], v[72:75]
	v_mfma_f32_16x16x32_bf16 v[104:107], v[196:199], v[212:215], v[104:107]
	v_mfma_f32_16x16x32_bf16 v[116:119], v[204:207], v[212:215], v[116:119]
	v_mfma_f32_16x16x32_bf16 v[100:103], v[196:199], v[220:223], v[100:103]
	v_mfma_f32_16x16x32_bf16 v[96:99], v[204:207], v[220:223], v[96:99]
	v_mfma_f32_16x16x32_bf16 v[84:87], v[196:199], v[228:231], v[84:87]
	v_mfma_f32_16x16x32_bf16 v[80:83], v[204:207], v[228:231], v[80:83]
	v_mfma_f32_16x16x32_bf16 v[68:71], v[196:199], v[236:239], v[68:71]
	v_mfma_f32_16x16x32_bf16 v[64:67], v[204:207], v[236:239], v[64:67]
	v_mfma_f32_16x16x32_bf16 v[104:107], v[200:203], v[216:219], v[104:107]
	v_mfma_f32_16x16x32_bf16 v[116:119], v[208:211], v[216:219], v[116:119]
	v_mfma_f32_16x16x32_bf16 v[100:103], v[200:203], v[224:227], v[100:103]
	v_mfma_f32_16x16x32_bf16 v[96:99], v[208:211], v[224:227], v[96:99]
	v_mfma_f32_16x16x32_bf16 v[84:87], v[200:203], v[232:235], v[84:87]
	v_mfma_f32_16x16x32_bf16 v[80:83], v[208:211], v[232:235], v[80:83]
	v_mfma_f32_16x16x32_bf16 v[68:71], v[200:203], v[240:243], v[68:71]
	v_mfma_f32_16x16x32_bf16 v[64:67], v[208:211], v[240:243], v[64:67]
	s_barrier
	s_add_i32 vcc_lo, vcc_lo, s39
	v_lshl_add_u64 v[188:189], s[94:95], 0, v[130:131]
	s_mov_b32 m0, vcc_lo
	ds_read_b128 v[212:215], v154 offset:16384
	ds_read_b128 v[216:219], v154 offset:17408
	ds_read_b128 v[220:223], v154 offset:18432
	ds_read_b128 v[224:227], v154 offset:19456
	ds_read_b128 v[228:231], v154 offset:20480
	ds_read_b128 v[232:235], v154 offset:21504
	ds_read_b128 v[236:239], v154 offset:22528
	ds_read_b128 v[240:243], v154 offset:23552
	global_load_lds_dwordx4 v[188:189], off
	s_add_i32 m0, vcc_lo, 0x2000
	v_lshl_add_u64 v[244:245], s[94:95], 0, v[134:135]
	s_add_u32 s94, s94, s6
	s_addc_u32 s95, s95, s7
	s_add_i32 s92, s92, s39
	global_load_lds_dwordx4 v[244:245], off
	v_lshl_add_u64 v[246:247], s[94:95], 0, v[130:131]
	s_mov_b32 m0, s92
	v_lshl_add_u64 v[248:249], s[94:95], 0, v[134:135]
	global_load_lds_dwordx4 v[246:247], off
	s_add_i32 m0, s92, 0x2000
	v_lshl_add_u64 v[250:251], s[28:29], 0, v[128:129]
	global_load_lds_dwordx4 v[248:249], off
	s_mov_b32 m0, s40
	v_lshl_add_u64 v[252:253], s[28:29], 0, v[132:133]
	global_load_lds_dwordx4 v[250:251], off
	s_mov_b32 m0, s41
	s_nop 0
	global_load_lds_dwordx4 v[252:253], off
	s_waitcnt vmcnt(8)
	s_waitcnt lgkmcnt(0)
	s_barrier
; #define PG8_STAGE(bufoff, gbase, voff) do { _Pragma("unroll") for (int _i = 0; _i < 2; ++_i) \
;         __builtin_amdgcn_global_load_lds((const unsigned*)((const char*)(gbase) + (voff)[_i]), (PG8_LAS unsigned*)(lds + (bufoff) + ldsw + _i * 8192), 16, 0, 0); } while (0)
; #define PG8_LDA(dst, b, h) do { _Pragma("unroll") for (int m = 0; m < 4; ++m) _Pragma("unroll") for (int k = 0; k < 2; ++k) dst[m][k] = *(const PG8_LAS bf16x8*)(lds + PG8_SA(b, h) + aoff + m * 2048 + k * 1024); } while (0)
; #define PG8_LDB(dst, b, h) do { _Pragma("unroll") for (int n = 0; n < 2; ++n) _Pragma("unroll") for (int k = 0; k < 2; ++k) dst[n][k] = *(const PG8_LAS bf16x8*)(lds + PG8_SB(b, h) + boff + n * 2048 + k * 1024); } while (0)
; #define PG8_MMA(ai, bj, At, Bt) do { __builtin_amdgcn_s_setprio(1); _Pragma("unroll") for (int m = 0; m < 4; ++m) _Pragma("unroll") for (int n = 0; n < 2; ++n) _Pragma("unroll") for (int k = 0; k < 2; ++k) \
;         acc[ai][bj][m][n] = __builtin_amdgcn_mfma_f32_16x16x32_bf16(Bt[n][k], At[m][k], acc[ai][bj][m][n], 0, 0, 0); __builtin_amdgcn_s_setprio(0); } while (0)
; #define PG8_WAIT_V(n) asm volatile("s_waitcnt vmcnt(" #n ")" ::: "memory")
; #define PG8_WAIT_L(n) asm volatile("s_waitcnt lgkmcnt(" #n ")" ::: "memory")
; #define PG8_BAR __builtin_amdgcn_s_barrier()
; #define PG8_SCHED __builtin_amdgcn_sched_barrier(0)
; template <class Epi, class Sched>
; __device__ __forceinline__ void gemm_phase(int wid_s, PG8_LAS unsigned char* lds, const Gemm g, const Sched& S, const Epi& E) {
;     ...
;             PG8_WAIT_V(8); PG8_WAIT_L(0); PG8_BAR; PG8_MMA(1, 0, At, B0); PG8_MMA(1, 1, At, B1); PG8_BAR; PG8_SCHED;
;             PG8_LDB(B0, 1, 0); PG8_LDB(B1, 1, 1); PG8_SCHED; PG8_LDA(At, 1, 0); PG8_STAGE(PG8_SA(0, 1), a2 + hstepA, voffA);
;             PG8_WAIT_V(8); PG8_WAIT_L(0); PG8_BAR; PG8_MMA(0, 0, At, B0); PG8_MMA(0, 1, At, B1); PG8_BAR; PG8_SCHED;
	s_waitcnt lgkmcnt(0)
	v_mfma_f32_16x16x32_bf16 v[60:63], v[156:159], v[212:215], v[60:63]
	v_mfma_f32_16x16x32_bf16 v[56:59], v[164:167], v[212:215], v[56:59]
	v_mfma_f32_16x16x32_bf16 v[44:47], v[156:159], v[220:223], v[44:47]
	v_mfma_f32_16x16x32_bf16 v[40:43], v[164:167], v[220:223], v[40:43]
	v_mfma_f32_16x16x32_bf16 v[28:31], v[156:159], v[228:231], v[28:31]
	v_mfma_f32_16x16x32_bf16 v[24:27], v[164:167], v[228:231], v[24:27]
	v_mfma_f32_16x16x32_bf16 v[12:15], v[156:159], v[236:239], v[12:15]
	v_mfma_f32_16x16x32_bf16 v[8:11], v[164:167], v[236:239], v[8:11]
	v_mfma_f32_16x16x32_bf16 v[60:63], v[160:163], v[216:219], v[60:63]
	v_mfma_f32_16x16x32_bf16 v[56:59], v[192:195], v[216:219], v[56:59]
	v_mfma_f32_16x16x32_bf16 v[44:47], v[160:163], v[224:227], v[44:47]
	v_mfma_f32_16x16x32_bf16 v[40:43], v[192:195], v[224:227], v[40:43]
	v_mfma_f32_16x16x32_bf16 v[28:31], v[160:163], v[232:235], v[28:31]
	v_mfma_f32_16x16x32_bf16 v[24:27], v[192:195], v[232:235], v[24:27]
	v_mfma_f32_16x16x32_bf16 v[12:15], v[160:163], v[240:243], v[12:15]
	v_mfma_f32_16x16x32_bf16 v[8:11], v[192:195], v[240:243], v[8:11]
	v_mfma_f32_16x16x32_bf16 v[52:55], v[196:199], v[212:215], v[52:55]
	v_mfma_f32_16x16x32_bf16 v[48:51], v[204:207], v[212:215], v[48:51]
	v_mfma_f32_16x16x32_bf16 v[36:39], v[196:199], v[220:223], v[36:39]
	v_mfma_f32_16x16x32_bf16 v[32:35], v[204:207], v[220:223], v[32:35]
	v_mfma_f32_16x16x32_bf16 v[20:23], v[196:199], v[228:231], v[20:23]
	v_mfma_f32_16x16x32_bf16 v[16:19], v[204:207], v[228:231], v[16:19]
	v_mfma_f32_16x16x32_bf16 v[4:7], v[196:199], v[236:239], v[4:7]
	v_mfma_f32_16x16x32_bf16 v[0:3], v[204:207], v[236:239], v[0:3]
	v_mfma_f32_16x16x32_bf16 v[52:55], v[200:203], v[216:219], v[52:55]
	v_mfma_f32_16x16x32_bf16 v[48:51], v[208:211], v[216:219], v[48:51]
	v_mfma_f32_16x16x32_bf16 v[36:39], v[200:203], v[224:227], v[36:39]
	v_mfma_f32_16x16x32_bf16 v[32:35], v[208:211], v[224:227], v[32:35]
	v_mfma_f32_16x16x32_bf16 v[20:23], v[200:203], v[232:235], v[20:23]
	v_mfma_f32_16x16x32_bf16 v[16:19], v[208:211], v[232:235], v[16:19]
	v_mfma_f32_16x16x32_bf16 v[4:7], v[200:203], v[240:243], v[4:7]
	v_mfma_f32_16x16x32_bf16 v[0:3], v[208:211], v[240:243], v[0:3]
	s_barrier
	s_add_i32 s92, 0, 0x18000
	v_add_u32_e32 v155, s92, v143
	s_add_i32 s94, 0, 0x1c000
	ds_read_b128 v[156:159], v155
	ds_read_b128 v[160:163], v155 offset:1024
	ds_read_b128 v[164:167], v155 offset:2048
	ds_read_b128 v[192:195], v155 offset:3072
	v_add_u32_e32 v155, s94, v143
	ds_read_b128 v[196:199], v155
	ds_read_b128 v[200:203], v155 offset:1024
	ds_read_b128 v[204:207], v155 offset:2048
	ds_read_b128 v[208:211], v155 offset:3072
	s_add_u32 s28, s28, s4
	s_addc_u32 s29, s29, s5
	s_mov_b32 m0, s42
	v_lshl_add_u64 v[190:191], s[28:29], 0, v[128:129]
	ds_read_b128 v[212:215], v154 offset:32768
	ds_read_b128 v[216:219], v154 offset:33792
	ds_read_b128 v[220:223], v154 offset:34816
	ds_read_b128 v[224:227], v154 offset:35840
	ds_read_b128 v[228:231], v154 offset:36864
	ds_read_b128 v[232:235], v154 offset:37888
	ds_read_b128 v[236:239], v154 offset:38912
	ds_read_b128 v[240:243], v154 offset:39936
	global_load_lds_dwordx4 v[190:191], off
	v_lshl_add_u64 v[190:191], s[28:29], 0, v[132:133]
	s_mov_b32 m0, s44
	s_nop 0
	global_load_lds_dwordx4 v[190:191], off
	s_waitcnt vmcnt(8)
	s_waitcnt lgkmcnt(0)
	s_barrier
	s_waitcnt lgkmcnt(0)
	v_mfma_f32_16x16x32_bf16 v[124:127], v[156:159], v[212:215], v[124:127]
	v_mfma_f32_16x16x32_bf16 v[120:123], v[164:167], v[212:215], v[120:123]
	v_mfma_f32_16x16x32_bf16 v[112:115], v[156:159], v[220:223], v[112:115]
	v_mfma_f32_16x16x32_bf16 v[108:111], v[164:167], v[220:223], v[108:111]
	v_mfma_f32_16x16x32_bf16 v[92:95], v[156:159], v[228:231], v[92:95]
	v_mfma_f32_16x16x32_bf16 v[88:91], v[164:167], v[228:231], v[88:91]
	v_mfma_f32_16x16x32_bf16 v[76:79], v[156:159], v[236:239], v[76:79]
	v_mfma_f32_16x16x32_bf16 v[72:75], v[164:167], v[236:239], v[72:75]
	v_mfma_f32_16x16x32_bf16 v[124:127], v[160:163], v[216:219], v[124:127]
	v_mfma_f32_16x16x32_bf16 v[120:123], v[192:195], v[216:219], v[120:123]
	v_mfma_f32_16x16x32_bf16 v[112:115], v[160:163], v[224:227], v[112:115]
	v_mfma_f32_16x16x32_bf16 v[108:111], v[192:195], v[224:227], v[108:111]
	v_mfma_f32_16x16x32_bf16 v[92:95], v[160:163], v[232:235], v[92:95]
	v_mfma_f32_16x16x32_bf16 v[88:91], v[192:195], v[232:235], v[88:91]
	v_mfma_f32_16x16x32_bf16 v[76:79], v[160:163], v[240:243], v[76:79]
	v_mfma_f32_16x16x32_bf16 v[72:75], v[192:195], v[240:243], v[72:75]
	v_mfma_f32_16x16x32_bf16 v[104:107], v[196:199], v[212:215], v[104:107]
	v_mfma_f32_16x16x32_bf16 v[116:119], v[204:207], v[212:215], v[116:119]
	v_mfma_f32_16x16x32_bf16 v[100:103], v[196:199], v[220:223], v[100:103]
	v_mfma_f32_16x16x32_bf16 v[96:99], v[204:207], v[220:223], v[96:99]
	v_mfma_f32_16x16x32_bf16 v[84:87], v[196:199], v[228:231], v[84:87]
	v_mfma_f32_16x16x32_bf16 v[80:83], v[204:207], v[228:231], v[80:83]
	v_mfma_f32_16x16x32_bf16 v[68:71], v[196:199], v[236:239], v[68:71]
	v_mfma_f32_16x16x32_bf16 v[64:67], v[204:207], v[236:239], v[64:67]
	v_mfma_f32_16x16x32_bf16 v[104:107], v[200:203], v[216:219], v[104:107]
	v_mfma_f32_16x16x32_bf16 v[116:119], v[208:211], v[216:219], v[116:119]
	v_mfma_f32_16x16x32_bf16 v[100:103], v[200:203], v[224:227], v[100:103]
	v_mfma_f32_16x16x32_bf16 v[96:99], v[208:211], v[224:227], v[96:99]
	v_mfma_f32_16x16x32_bf16 v[84:87], v[200:203], v[232:235], v[84:87]
	v_mfma_f32_16x16x32_bf16 v[80:83], v[208:211], v[232:235], v[80:83]
	v_mfma_f32_16x16x32_bf16 v[68:71], v[200:203], v[240:243], v[68:71]
	v_mfma_f32_16x16x32_bf16 v[64:67], v[208:211], v[240:243], v[64:67]
	s_barrier
; #define PG8_STAGE(bufoff, gbase, voff) do { _Pragma("unroll") for (int _i = 0; _i < 2; ++_i) \
;         __builtin_amdgcn_global_load_lds((const unsigned*)((const char*)(gbase) + (voff)[_i]), (PG8_LAS unsigned*)(lds + (bufoff) + ldsw + _i * 8192), 16, 0, 0); } while (0)
; #define PG8_LDA(dst, b, h) do { _Pragma("unroll") for (int m = 0; m < 4; ++m) _Pragma("unroll") for (int k = 0; k < 2; ++k) dst[m][k] = *(const PG8_LAS bf16x8*)(lds + PG8_SA(b, h) + aoff + m * 2048 + k * 1024); } while (0)
; #define PG8_MMA(ai, bj, At, Bt) do { __builtin_amdgcn_s_setprio(1); _Pragma("unroll") for (int m = 0; m < 4; ++m) _Pragma("unroll") for (int n = 0; n < 2; ++n) _Pragma("unroll") for (int k = 0; k < 2; ++k) \
;         acc[ai][bj][m][n] = __builtin_amdgcn_mfma_f32_16x16x32_bf16(Bt[n][k], At[m][k], acc[ai][bj][m][n], 0, 0, 0); __builtin_amdgcn_s_setprio(0); } while (0)
; #define PG8_WAIT_V(n) asm volatile("s_waitcnt vmcnt(" #n ")" ::: "memory")
; #define PG8_WAIT_L(n) asm volatile("s_waitcnt lgkmcnt(" #n ")" ::: "memory")
; #define PG8_BAR __builtin_amdgcn_s_barrier()
; #define PG8_SCHED __builtin_amdgcn_sched_barrier(0)
; template <class Epi, class Sched>
; __device__ __forceinline__ void gemm_phase(int wid_s, PG8_LAS unsigned char* lds, const Gemm g, const Sched& S, const Epi& E) {
;     ...
;             PG8_LDA(At, 1, 1); PG8_STAGE(PG8_SB(1, 0), b3, voffB); PG8_STAGE(PG8_SB(1, 1), b3 + hstepB, voffB); PG8_STAGE(PG8_SA(1, 0), a3, voffA);
;             PG8_WAIT_V(8); PG8_WAIT_L(0); PG8_BAR; PG8_MMA(1, 0, At, B0); PG8_MMA(1, 1, At, B1); PG8_BAR; PG8_SCHED;
;         }
;         if (wr == 0) PG8_BAR;
;         E(acc, cur, wr, wc, fr, fq);
	s_add_i32 s28, s92, s39
	v_lshl_add_u64 v[188:189], v[188:189], 0, s[96:97]
	s_mov_b32 m0, s28
	ds_read_b128 v[212:215], v154 offset:49152
	ds_read_b128 v[216:219], v154 offset:50176
	ds_read_b128 v[220:223], v154 offset:51200
	ds_read_b128 v[224:227], v154 offset:52224
	ds_read_b128 v[228:231], v154 offset:53248
	ds_read_b128 v[232:235], v154 offset:54272
	ds_read_b128 v[236:239], v154 offset:55296
	ds_read_b128 v[240:243], v154 offset:56320
	global_load_lds_dwordx4 v[188:189], off
	v_lshl_add_u64 v[188:189], v[244:245], 0, s[96:97]
	s_add_i32 m0, s28, 0x2000
	s_add_i32 s28, s94, s39
	global_load_lds_dwordx4 v[188:189], off
	v_lshl_add_u64 v[188:189], v[246:247], 0, s[96:97]
	s_mov_b32 m0, s28
	s_nop 0
	global_load_lds_dwordx4 v[188:189], off
	v_lshl_add_u64 v[188:189], v[248:249], 0, s[96:97]
	s_add_i32 m0, s28, 0x2000
	s_nop 0
	global_load_lds_dwordx4 v[188:189], off
	v_lshl_add_u64 v[188:189], v[250:251], 0, s[96:97]
	s_mov_b32 m0, s47
	s_nop 0
	global_load_lds_dwordx4 v[188:189], off
	v_lshl_add_u64 v[188:189], v[252:253], 0, s[96:97]
	s_mov_b32 m0, s48
	s_nop 0
	global_load_lds_dwordx4 v[188:189], off
	s_waitcnt vmcnt(8)
	s_waitcnt lgkmcnt(0)
	s_barrier
	s_waitcnt lgkmcnt(0)
	v_mfma_f32_16x16x32_bf16 v[60:63], v[156:159], v[212:215], v[60:63]
	v_mfma_f32_16x16x32_bf16 v[56:59], v[164:167], v[212:215], v[56:59]
	v_mfma_f32_16x16x32_bf16 v[44:47], v[156:159], v[220:223], v[44:47]
	v_mfma_f32_16x16x32_bf16 v[40:43], v[164:167], v[220:223], v[40:43]
	v_mfma_f32_16x16x32_bf16 v[28:31], v[156:159], v[228:231], v[28:31]
	v_mfma_f32_16x16x32_bf16 v[24:27], v[164:167], v[228:231], v[24:27]
	v_mfma_f32_16x16x32_bf16 v[12:15], v[156:159], v[236:239], v[12:15]
	v_mfma_f32_16x16x32_bf16 v[8:11], v[164:167], v[236:239], v[8:11]
	v_mfma_f32_16x16x32_bf16 v[60:63], v[160:163], v[216:219], v[60:63]
	v_mfma_f32_16x16x32_bf16 v[56:59], v[192:195], v[216:219], v[56:59]
	v_mfma_f32_16x16x32_bf16 v[44:47], v[160:163], v[224:227], v[44:47]
	v_mfma_f32_16x16x32_bf16 v[40:43], v[192:195], v[224:227], v[40:43]
	v_mfma_f32_16x16x32_bf16 v[28:31], v[160:163], v[232:235], v[28:31]
	v_mfma_f32_16x16x32_bf16 v[24:27], v[192:195], v[232:235], v[24:27]
	v_mfma_f32_16x16x32_bf16 v[12:15], v[160:163], v[240:243], v[12:15]
	v_mfma_f32_16x16x32_bf16 v[8:11], v[192:195], v[240:243], v[8:11]
	v_mfma_f32_16x16x32_bf16 v[52:55], v[196:199], v[212:215], v[52:55]
	v_mfma_f32_16x16x32_bf16 v[48:51], v[204:207], v[212:215], v[48:51]
	v_mfma_f32_16x16x32_bf16 v[36:39], v[196:199], v[220:223], v[36:39]
	v_mfma_f32_16x16x32_bf16 v[32:35], v[204:207], v[220:223], v[32:35]
	v_mfma_f32_16x16x32_bf16 v[20:23], v[196:199], v[228:231], v[20:23]
	v_mfma_f32_16x16x32_bf16 v[16:19], v[204:207], v[228:231], v[16:19]
	v_mfma_f32_16x16x32_bf16 v[4:7], v[196:199], v[236:239], v[4:7]
	v_mfma_f32_16x16x32_bf16 v[0:3], v[204:207], v[236:239], v[0:3]
	v_mfma_f32_16x16x32_bf16 v[52:55], v[200:203], v[216:219], v[52:55]
	v_mfma_f32_16x16x32_bf16 v[48:51], v[208:211], v[216:219], v[48:51]
	v_mfma_f32_16x16x32_bf16 v[36:39], v[200:203], v[224:227], v[36:39]
	v_mfma_f32_16x16x32_bf16 v[32:35], v[208:211], v[224:227], v[32:35]
	v_mfma_f32_16x16x32_bf16 v[20:23], v[200:203], v[232:235], v[20:23]
	v_mfma_f32_16x16x32_bf16 v[16:19], v[208:211], v[232:235], v[16:19]
	v_mfma_f32_16x16x32_bf16 v[4:7], v[200:203], v[240:243], v[4:7]
	v_mfma_f32_16x16x32_bf16 v[0:3], v[208:211], v[240:243], v[0:3]
	s_barrier
	s_add_u32 s33, s33, 0x100
	s_addc_u32 s56, s56, 0
	s_add_u32 s26, s26, 0x100
	s_addc_u32 s27, s27, 0
	s_cmp_ge_i32 s57, s45
	s_mov_b32 s28, s57
	s_cbranch_scc0 .LBB0_1845
	v_readlane_b32 s95, v254, 51
	v_readlane_b32 s92, v254, 54
	v_readlane_b32 s94, v254, 55
	s_and_b64 vcc, exec, s[20:21]
	s_cbranch_vccnz .LBB0_1850
	s_branch .LBB0_1851

; #define PG8_STAGE(bufoff, gbase, voff) do { _Pragma("unroll") for (int _i = 0; _i < 2; ++_i) \
;         __builtin_amdgcn_global_load_lds((const unsigned*)((const char*)(gbase) + (voff)[_i]), (PG8_LAS unsigned*)(lds + (bufoff) + ldsw + _i * 8192), 16, 0, 0); } while (0)
; #define PG8_LDA(dst, b, h) do { _Pragma("unroll") for (int m = 0; m < 4; ++m) _Pragma("unroll") for (int k = 0; k < 2; ++k) dst[m][k] = *(const PG8_LAS bf16x8*)(lds + PG8_SA(b, h) + aoff + m * 2048 + k * 1024); } while (0)
; #define PG8_LDB(dst, b, h) do { _Pragma("unroll") for (int n = 0; n < 2; ++n) _Pragma("unroll") for (int k = 0; k < 2; ++k) dst[n][k] = *(const PG8_LAS bf16x8*)(lds + PG8_SB(b, h) + boff + n * 2048 + k * 1024); } while (0)
; #define PG8_MMA(ai, bj, At, Bt) do { __builtin_amdgcn_s_setprio(1); _Pragma("unroll") for (int m = 0; m < 4; ++m) _Pragma("unroll") for (int n = 0; n < 2; ++n) _Pragma("unroll") for (int k = 0; k < 2; ++k) \
;         acc[ai][bj][m][n] = __builtin_amdgcn_mfma_f32_16x16x32_bf16(Bt[n][k], At[m][k], acc[ai][bj][m][n], 0, 0, 0); __builtin_amdgcn_s_setprio(0); } while (0)
; #define PG8_WAIT_V(n) asm volatile("s_waitcnt vmcnt(" #n ")" ::: "memory")
; #define PG8_WAIT_L(n) asm volatile("s_waitcnt lgkmcnt(" #n ")" ::: "memory")
; #define PG8_BAR __builtin_amdgcn_s_barrier()
; #define PG8_SCHED __builtin_amdgcn_sched_barrier(0)
; template <class Epi, class Sched>
; __device__ __forceinline__ void gemm_phase(int wid_s, PG8_LAS unsigned char* lds, const Gemm g, const Sched& S, const Epi& E) {
;     ...
;             const bool last = (t == nt - 2);
;             const char* a1 = cA + (size_t)(t + 1) * kstep;
;             const char* a2 = last ? nA : cA + (size_t)(t + 2) * kstep; const char* b2 = last ? nB : cB + (size_t)(t + 2) * kstep;
;             const char* a3 = a2 + kstep; const char* b3 = b2 + kstep;
;             PG8_LDB(B0, 0, 0); PG8_LDB(B1, 0, 1); PG8_SCHED; PG8_LDA(At, 0, 0); PG8_STAGE(PG8_SA(1, 1), a1 + hstepA, voffA);
;             PG8_WAIT_V(8); PG8_WAIT_L(0); PG8_BAR; PG8_MMA(0, 0, At, B0); PG8_MMA(0, 1, At, B1); PG8_BAR; PG8_SCHED;
;             PG8_LDA(At, 0, 1); PG8_STAGE(PG8_SB(0, 0), b2, voffB); PG8_STAGE(PG8_SB(0, 1), b2 + hstepB, voffB); PG8_STAGE(PG8_SA(0, 0), a2, voffA);
;             PG8_WAIT_V(8); PG8_WAIT_L(0); PG8_BAR; PG8_MMA(1, 0, At, B0); PG8_MMA(1, 1, At, B1); PG8_BAR; PG8_SCHED;
.LBB0_2148:
	s_add_i32 s55, s28, 2
	s_add_u32 s56, s26, 0x80
	s_addc_u32 s29, s27, 0
	s_add_i32 s92, 0, 0x10000
	s_cmp_eq_u32 s47, s28
	s_cselect_b32 s29, s5, s29
	s_cselect_b32 s28, s4, s56
	v_add_u32_e32 v138, s92, v142
	s_cselect_b32 s57, s25, s54
	s_cselect_b32 s56, s24, s33
	s_add_i32 s94, 0, 0x14000
	ds_read_b128 v[156:159], v138
	ds_read_b128 v[160:163], v138 offset:1024
	ds_read_b128 v[164:167], v138 offset:2048
	ds_read_b128 v[188:191], v138 offset:3072
	v_add_u32_e32 v138, s94, v142
	ds_read_b128 v[192:195], v138
	ds_read_b128 v[196:199], v138 offset:1024
	ds_read_b128 v[200:203], v138 offset:2048
	ds_read_b128 v[204:207], v138 offset:3072
	v_lshl_add_u64 v[138:139], s[26:27], 0, v[136:137]
	s_add_i32 m0, s39, 0xc000
	ds_read_b128 v[208:211], v154
	ds_read_b128 v[212:215], v154 offset:1024
	ds_read_b128 v[216:219], v154 offset:2048
	ds_read_b128 v[220:223], v154 offset:3072
	ds_read_b128 v[224:227], v154 offset:4096
	ds_read_b128 v[228:231], v154 offset:5120
	ds_read_b128 v[232:235], v154 offset:6144
	ds_read_b128 v[236:239], v154 offset:7168
	global_load_lds_dwordx4 v[138:139], off
	v_lshl_add_u64 v[138:139], s[26:27], 0, v[134:135]
	s_add_i32 m0, s39, 0xe000
	s_nop 0
	global_load_lds_dwordx4 v[138:139], off
	s_waitcnt vmcnt(8)
	s_waitcnt lgkmcnt(0)
	s_barrier
	s_waitcnt lgkmcnt(0)
	v_mfma_f32_16x16x32_bf16 v[120:123], v[156:159], v[208:211], v[120:123]
	v_mfma_f32_16x16x32_bf16 v[124:127], v[164:167], v[208:211], v[124:127]
	v_mfma_f32_16x16x32_bf16 v[108:111], v[156:159], v[216:219], v[108:111]
	v_mfma_f32_16x16x32_bf16 v[104:107], v[164:167], v[216:219], v[104:107]
	v_mfma_f32_16x16x32_bf16 v[92:95], v[156:159], v[224:227], v[92:95]
	v_mfma_f32_16x16x32_bf16 v[88:91], v[164:167], v[224:227], v[88:91]
	v_mfma_f32_16x16x32_bf16 v[76:79], v[156:159], v[232:235], v[76:79]
	v_mfma_f32_16x16x32_bf16 v[72:75], v[164:167], v[232:235], v[72:75]
	v_mfma_f32_16x16x32_bf16 v[120:123], v[160:163], v[212:215], v[120:123]
	v_mfma_f32_16x16x32_bf16 v[124:127], v[188:191], v[212:215], v[124:127]
	v_mfma_f32_16x16x32_bf16 v[108:111], v[160:163], v[220:223], v[108:111]
	v_mfma_f32_16x16x32_bf16 v[104:107], v[188:191], v[220:223], v[104:107]
	v_mfma_f32_16x16x32_bf16 v[92:95], v[160:163], v[228:231], v[92:95]
	v_mfma_f32_16x16x32_bf16 v[88:91], v[188:191], v[228:231], v[88:91]
	v_mfma_f32_16x16x32_bf16 v[76:79], v[160:163], v[236:239], v[76:79]
	v_mfma_f32_16x16x32_bf16 v[72:75], v[188:191], v[236:239], v[72:75]
	v_mfma_f32_16x16x32_bf16 v[116:119], v[192:195], v[208:211], v[116:119]
	v_mfma_f32_16x16x32_bf16 v[112:115], v[200:203], v[208:211], v[112:115]
	v_mfma_f32_16x16x32_bf16 v[100:103], v[192:195], v[216:219], v[100:103]
	v_mfma_f32_16x16x32_bf16 v[96:99], v[200:203], v[216:219], v[96:99]
	v_mfma_f32_16x16x32_bf16 v[84:87], v[192:195], v[224:227], v[84:87]
	v_mfma_f32_16x16x32_bf16 v[80:83], v[200:203], v[224:227], v[80:83]
	v_mfma_f32_16x16x32_bf16 v[68:71], v[192:195], v[232:235], v[68:71]
	v_mfma_f32_16x16x32_bf16 v[64:67], v[200:203], v[232:235], v[64:67]
	v_mfma_f32_16x16x32_bf16 v[116:119], v[196:199], v[212:215], v[116:119]
	v_mfma_f32_16x16x32_bf16 v[112:115], v[204:207], v[212:215], v[112:115]
	v_mfma_f32_16x16x32_bf16 v[100:103], v[196:199], v[220:223], v[100:103]
	v_mfma_f32_16x16x32_bf16 v[96:99], v[204:207], v[220:223], v[96:99]
	v_mfma_f32_16x16x32_bf16 v[84:87], v[196:199], v[228:231], v[84:87]
	v_mfma_f32_16x16x32_bf16 v[80:83], v[204:207], v[228:231], v[80:83]
	v_mfma_f32_16x16x32_bf16 v[68:71], v[196:199], v[236:239], v[68:71]
	v_mfma_f32_16x16x32_bf16 v[64:67], v[204:207], v[236:239], v[64:67]
	s_barrier
	s_add_i32 s92, s92, s37
	v_lshl_add_u64 v[138:139], s[56:57], 0, v[144:145]
	s_mov_b32 m0, s92
	ds_read_b128 v[208:211], v154 offset:16384
	ds_read_b128 v[212:215], v154 offset:17408
	ds_read_b128 v[216:219], v154 offset:18432
	ds_read_b128 v[220:223], v154 offset:19456
	ds_read_b128 v[224:227], v154 offset:20480
	ds_read_b128 v[228:231], v154 offset:21504
	ds_read_b128 v[232:235], v154 offset:22528
	ds_read_b128 v[236:239], v154 offset:23552
	global_load_lds_dwordx4 v[138:139], off
	s_add_i32 m0, s92, 0x2000
	v_lshl_add_u64 v[240:241], s[56:57], 0, v[132:133]
	s_add_u32 s56, s56, s8
	s_addc_u32 s57, s57, s9
	s_add_i32 s92, s94, s37
	global_load_lds_dwordx4 v[240:241], off
	v_lshl_add_u64 v[242:243], s[56:57], 0, v[144:145]
	s_mov_b32 m0, s92
	v_lshl_add_u64 v[244:245], s[56:57], 0, v[132:133]
	global_load_lds_dwordx4 v[242:243], off
	s_add_i32 m0, s92, 0x2000
	v_lshl_add_u64 v[246:247], s[28:29], 0, v[128:129]
	global_load_lds_dwordx4 v[244:245], off
	s_mov_b32 m0, s39
	v_lshl_add_u64 v[248:249], s[28:29], 0, v[130:131]
	global_load_lds_dwordx4 v[246:247], off
	s_mov_b32 m0, s40
	s_nop 0
	global_load_lds_dwordx4 v[248:249], off
	s_waitcnt vmcnt(8)
	s_waitcnt lgkmcnt(0)
	s_barrier
; #define PG8_STAGE(bufoff, gbase, voff) do { _Pragma("unroll") for (int _i = 0; _i < 2; ++_i) \
;         __builtin_amdgcn_global_load_lds((const unsigned*)((const char*)(gbase) + (voff)[_i]), (PG8_LAS unsigned*)(lds + (bufoff) + ldsw + _i * 8192), 16, 0, 0); } while (0)
; #define PG8_LDA(dst, b, h) do { _Pragma("unroll") for (int m = 0; m < 4; ++m) _Pragma("unroll") for (int k = 0; k < 2; ++k) dst[m][k] = *(const PG8_LAS bf16x8*)(lds + PG8_SA(b, h) + aoff + m * 2048 + k * 1024); } while (0)
; #define PG8_LDB(dst, b, h) do { _Pragma("unroll") for (int n = 0; n < 2; ++n) _Pragma("unroll") for (int k = 0; k < 2; ++k) dst[n][k] = *(const PG8_LAS bf16x8*)(lds + PG8_SB(b, h) + boff + n * 2048 + k * 1024); } while (0)
; #define PG8_MMA(ai, bj, At, Bt) do { __builtin_amdgcn_s_setprio(1); _Pragma("unroll") for (int m = 0; m < 4; ++m) _Pragma("unroll") for (int n = 0; n < 2; ++n) _Pragma("unroll") for (int k = 0; k < 2; ++k) \
;         acc[ai][bj][m][n] = __builtin_amdgcn_mfma_f32_16x16x32_bf16(Bt[n][k], At[m][k], acc[ai][bj][m][n], 0, 0, 0); __builtin_amdgcn_s_setprio(0); } while (0)
; #define PG8_WAIT_V(n) asm volatile("s_waitcnt vmcnt(" #n ")" ::: "memory")
; #define PG8_WAIT_L(n) asm volatile("s_waitcnt lgkmcnt(" #n ")" ::: "memory")
; #define PG8_BAR __builtin_amdgcn_s_barrier()
; #define PG8_SCHED __builtin_amdgcn_sched_barrier(0)
; template <class Epi, class Sched>
; __device__ __forceinline__ void gemm_phase(int wid_s, PG8_LAS unsigned char* lds, const Gemm g, const Sched& S, const Epi& E) {
;     ...
;             PG8_WAIT_V(8); PG8_WAIT_L(0); PG8_BAR; PG8_MMA(1, 0, At, B0); PG8_MMA(1, 1, At, B1); PG8_BAR; PG8_SCHED;
;             PG8_LDB(B0, 1, 0); PG8_LDB(B1, 1, 1); PG8_SCHED; PG8_LDA(At, 1, 0); PG8_STAGE(PG8_SA(0, 1), a2 + hstepA, voffA);
;             PG8_WAIT_V(8); PG8_WAIT_L(0); PG8_BAR; PG8_MMA(0, 0, At, B0); PG8_MMA(0, 1, At, B1); PG8_BAR; PG8_SCHED;
	s_waitcnt lgkmcnt(0)
	v_mfma_f32_16x16x32_bf16 v[60:63], v[156:159], v[208:211], v[60:63]
	v_mfma_f32_16x16x32_bf16 v[56:59], v[164:167], v[208:211], v[56:59]
	v_mfma_f32_16x16x32_bf16 v[44:47], v[156:159], v[216:219], v[44:47]
	v_mfma_f32_16x16x32_bf16 v[40:43], v[164:167], v[216:219], v[40:43]
	v_mfma_f32_16x16x32_bf16 v[28:31], v[156:159], v[224:227], v[28:31]
	v_mfma_f32_16x16x32_bf16 v[24:27], v[164:167], v[224:227], v[24:27]
	v_mfma_f32_16x16x32_bf16 v[12:15], v[156:159], v[232:235], v[12:15]
	v_mfma_f32_16x16x32_bf16 v[8:11], v[164:167], v[232:235], v[8:11]
	v_mfma_f32_16x16x32_bf16 v[60:63], v[160:163], v[212:215], v[60:63]
	v_mfma_f32_16x16x32_bf16 v[56:59], v[188:191], v[212:215], v[56:59]
	v_mfma_f32_16x16x32_bf16 v[44:47], v[160:163], v[220:223], v[44:47]
	v_mfma_f32_16x16x32_bf16 v[40:43], v[188:191], v[220:223], v[40:43]
	v_mfma_f32_16x16x32_bf16 v[28:31], v[160:163], v[228:231], v[28:31]
	v_mfma_f32_16x16x32_bf16 v[24:27], v[188:191], v[228:231], v[24:27]
	v_mfma_f32_16x16x32_bf16 v[12:15], v[160:163], v[236:239], v[12:15]
	v_mfma_f32_16x16x32_bf16 v[8:11], v[188:191], v[236:239], v[8:11]
	v_mfma_f32_16x16x32_bf16 v[52:55], v[192:195], v[208:211], v[52:55]
	v_mfma_f32_16x16x32_bf16 v[48:51], v[200:203], v[208:211], v[48:51]
	v_mfma_f32_16x16x32_bf16 v[36:39], v[192:195], v[216:219], v[36:39]
	v_mfma_f32_16x16x32_bf16 v[32:35], v[200:203], v[216:219], v[32:35]
	v_mfma_f32_16x16x32_bf16 v[20:23], v[192:195], v[224:227], v[20:23]
	v_mfma_f32_16x16x32_bf16 v[16:19], v[200:203], v[224:227], v[16:19]
	v_mfma_f32_16x16x32_bf16 v[4:7], v[192:195], v[232:235], v[4:7]
	v_mfma_f32_16x16x32_bf16 v[0:3], v[200:203], v[232:235], v[0:3]
	v_mfma_f32_16x16x32_bf16 v[52:55], v[196:199], v[212:215], v[52:55]
	v_mfma_f32_16x16x32_bf16 v[48:51], v[204:207], v[212:215], v[48:51]
	v_mfma_f32_16x16x32_bf16 v[36:39], v[196:199], v[220:223], v[36:39]
	v_mfma_f32_16x16x32_bf16 v[32:35], v[204:207], v[220:223], v[32:35]
	v_mfma_f32_16x16x32_bf16 v[20:23], v[196:199], v[228:231], v[20:23]
	v_mfma_f32_16x16x32_bf16 v[16:19], v[204:207], v[228:231], v[16:19]
	v_mfma_f32_16x16x32_bf16 v[4:7], v[196:199], v[236:239], v[4:7]
	v_mfma_f32_16x16x32_bf16 v[0:3], v[204:207], v[236:239], v[0:3]
	s_barrier
	s_add_i32 s56, 0, 0x18000
	v_add_u32_e32 v140, s56, v142
	s_add_i32 s57, 0, 0x1c000
	ds_read_b128 v[156:159], v140
	ds_read_b128 v[160:163], v140 offset:1024
	ds_read_b128 v[164:167], v140 offset:2048
	ds_read_b128 v[188:191], v140 offset:3072
	v_add_u32_e32 v140, s57, v142
	ds_read_b128 v[192:195], v140
	ds_read_b128 v[196:199], v140 offset:1024
	ds_read_b128 v[200:203], v140 offset:2048
	ds_read_b128 v[204:207], v140 offset:3072
	s_add_u32 s28, s28, s6
	s_addc_u32 s29, s29, s7
	s_mov_b32 m0, s41
	v_lshl_add_u64 v[250:251], s[28:29], 0, v[128:129]
	ds_read_b128 v[208:211], v154 offset:32768
	ds_read_b128 v[212:215], v154 offset:33792
	ds_read_b128 v[216:219], v154 offset:34816
	ds_read_b128 v[220:223], v154 offset:35840
	ds_read_b128 v[224:227], v154 offset:36864
	ds_read_b128 v[228:231], v154 offset:37888
	ds_read_b128 v[232:235], v154 offset:38912
	ds_read_b128 v[236:239], v154 offset:39936
	global_load_lds_dwordx4 v[250:251], off
	v_lshl_add_u64 v[250:251], s[28:29], 0, v[130:131]
	s_mov_b32 m0, s42
	s_nop 0
	global_load_lds_dwordx4 v[250:251], off
	s_waitcnt vmcnt(8)
	s_waitcnt lgkmcnt(0)
	s_barrier
	s_waitcnt lgkmcnt(0)
	v_mfma_f32_16x16x32_bf16 v[120:123], v[156:159], v[208:211], v[120:123]
	v_mfma_f32_16x16x32_bf16 v[124:127], v[164:167], v[208:211], v[124:127]
	v_mfma_f32_16x16x32_bf16 v[108:111], v[156:159], v[216:219], v[108:111]
	v_mfma_f32_16x16x32_bf16 v[104:107], v[164:167], v[216:219], v[104:107]
	v_mfma_f32_16x16x32_bf16 v[92:95], v[156:159], v[224:227], v[92:95]
	v_mfma_f32_16x16x32_bf16 v[88:91], v[164:167], v[224:227], v[88:91]
	v_mfma_f32_16x16x32_bf16 v[76:79], v[156:159], v[232:235], v[76:79]
	v_mfma_f32_16x16x32_bf16 v[72:75], v[164:167], v[232:235], v[72:75]
	v_mfma_f32_16x16x32_bf16 v[120:123], v[160:163], v[212:215], v[120:123]
	v_mfma_f32_16x16x32_bf16 v[124:127], v[188:191], v[212:215], v[124:127]
	v_mfma_f32_16x16x32_bf16 v[108:111], v[160:163], v[220:223], v[108:111]
	v_mfma_f32_16x16x32_bf16 v[104:107], v[188:191], v[220:223], v[104:107]
	v_mfma_f32_16x16x32_bf16 v[92:95], v[160:163], v[228:231], v[92:95]
	v_mfma_f32_16x16x32_bf16 v[88:91], v[188:191], v[228:231], v[88:91]
	v_mfma_f32_16x16x32_bf16 v[76:79], v[160:163], v[236:239], v[76:79]
	v_mfma_f32_16x16x32_bf16 v[72:75], v[188:191], v[236:239], v[72:75]
	v_mfma_f32_16x16x32_bf16 v[116:119], v[192:195], v[208:211], v[116:119]
	v_mfma_f32_16x16x32_bf16 v[112:115], v[200:203], v[208:211], v[112:115]
	v_mfma_f32_16x16x32_bf16 v[100:103], v[192:195], v[216:219], v[100:103]
	v_mfma_f32_16x16x32_bf16 v[96:99], v[200:203], v[216:219], v[96:99]
	v_mfma_f32_16x16x32_bf16 v[84:87], v[192:195], v[224:227], v[84:87]
	v_mfma_f32_16x16x32_bf16 v[80:83], v[200:203], v[224:227], v[80:83]
	v_mfma_f32_16x16x32_bf16 v[68:71], v[192:195], v[232:235], v[68:71]
	v_mfma_f32_16x16x32_bf16 v[64:67], v[200:203], v[232:235], v[64:67]
	v_mfma_f32_16x16x32_bf16 v[116:119], v[196:199], v[212:215], v[116:119]
	v_mfma_f32_16x16x32_bf16 v[112:115], v[204:207], v[212:215], v[112:115]
	v_mfma_f32_16x16x32_bf16 v[100:103], v[196:199], v[220:223], v[100:103]
	v_mfma_f32_16x16x32_bf16 v[96:99], v[204:207], v[220:223], v[96:99]
	v_mfma_f32_16x16x32_bf16 v[84:87], v[196:199], v[228:231], v[84:87]
	v_mfma_f32_16x16x32_bf16 v[80:83], v[204:207], v[228:231], v[80:83]
	v_mfma_f32_16x16x32_bf16 v[68:71], v[196:199], v[236:239], v[68:71]
	v_mfma_f32_16x16x32_bf16 v[64:67], v[204:207], v[236:239], v[64:67]
	s_barrier
; #define PG8_STAGE(bufoff, gbase, voff) do { _Pragma("unroll") for (int _i = 0; _i < 2; ++_i) \
;         __builtin_amdgcn_global_load_lds((const unsigned*)((const char*)(gbase) + (voff)[_i]), (PG8_LAS unsigned*)(lds + (bufoff) + ldsw + _i * 8192), 16, 0, 0); } while (0)
; #define PG8_LDA(dst, b, h) do { _Pragma("unroll") for (int m = 0; m < 4; ++m) _Pragma("unroll") for (int k = 0; k < 2; ++k) dst[m][k] = *(const PG8_LAS bf16x8*)(lds + PG8_SA(b, h) + aoff + m * 2048 + k * 1024); } while (0)
; #define PG8_MMA(ai, bj, At, Bt) do { __builtin_amdgcn_s_setprio(1); _Pragma("unroll") for (int m = 0; m < 4; ++m) _Pragma("unroll") for (int n = 0; n < 2; ++n) _Pragma("unroll") for (int k = 0; k < 2; ++k) \
;         acc[ai][bj][m][n] = __builtin_amdgcn_mfma_f32_16x16x32_bf16(Bt[n][k], At[m][k], acc[ai][bj][m][n], 0, 0, 0); __builtin_amdgcn_s_setprio(0); } while (0)
; #define PG8_WAIT_V(n) asm volatile("s_waitcnt vmcnt(" #n ")" ::: "memory")
; #define PG8_WAIT_L(n) asm volatile("s_waitcnt lgkmcnt(" #n ")" ::: "memory")
; #define PG8_BAR __builtin_amdgcn_s_barrier()
; #define PG8_SCHED __builtin_amdgcn_sched_barrier(0)
; template <class Epi, class Sched>
; __device__ __forceinline__ void gemm_phase(int wid_s, PG8_LAS unsigned char* lds, const Gemm g, const Sched& S, const Epi& E) {
;     ...
;             PG8_LDA(At, 1, 1); PG8_STAGE(PG8_SB(1, 0), b3, voffB); PG8_STAGE(PG8_SB(1, 1), b3 + hstepB, voffB); PG8_STAGE(PG8_SA(1, 0), a3, voffA);
;             PG8_WAIT_V(8); PG8_WAIT_L(0); PG8_BAR; PG8_MMA(1, 0, At, B0); PG8_MMA(1, 1, At, B1); PG8_BAR; PG8_SCHED;
;         }
	s_add_i32 s28, s56, s37
	v_lshl_add_u64 v[138:139], v[138:139], 0, s[96:97]
	s_mov_b32 m0, s28
	ds_read_b128 v[208:211], v154 offset:49152
	ds_read_b128 v[212:215], v154 offset:50176
	ds_read_b128 v[216:219], v154 offset:51200
	ds_read_b128 v[220:223], v154 offset:52224
	ds_read_b128 v[224:227], v154 offset:53248
	ds_read_b128 v[228:231], v154 offset:54272
	ds_read_b128 v[232:235], v154 offset:55296
	ds_read_b128 v[236:239], v154 offset:56320
	global_load_lds_dwordx4 v[138:139], off
	v_lshl_add_u64 v[138:139], v[240:241], 0, s[96:97]
	s_add_i32 m0, s28, 0x2000
	s_add_i32 s28, s57, s37
	global_load_lds_dwordx4 v[138:139], off
	v_lshl_add_u64 v[138:139], v[242:243], 0, s[96:97]
	s_mov_b32 m0, s28
	s_nop 0
	global_load_lds_dwordx4 v[138:139], off
	v_lshl_add_u64 v[138:139], v[244:245], 0, s[96:97]
	s_add_i32 m0, s28, 0x2000
	s_nop 0
	global_load_lds_dwordx4 v[138:139], off
	v_lshl_add_u64 v[138:139], v[246:247], 0, s[96:97]
	s_mov_b32 m0, s44
	s_nop 0
	global_load_lds_dwordx4 v[138:139], off
	v_lshl_add_u64 v[138:139], v[248:249], 0, s[96:97]
	s_mov_b32 m0, s45
	s_nop 0
	global_load_lds_dwordx4 v[138:139], off
	s_waitcnt vmcnt(8)
	s_waitcnt lgkmcnt(0)
	s_barrier
	s_waitcnt lgkmcnt(0)
	v_mfma_f32_16x16x32_bf16 v[60:63], v[156:159], v[208:211], v[60:63]
	v_mfma_f32_16x16x32_bf16 v[56:59], v[164:167], v[208:211], v[56:59]
	v_mfma_f32_16x16x32_bf16 v[44:47], v[156:159], v[216:219], v[44:47]
	v_mfma_f32_16x16x32_bf16 v[40:43], v[164:167], v[216:219], v[40:43]
	v_mfma_f32_16x16x32_bf16 v[28:31], v[156:159], v[224:227], v[28:31]
	v_mfma_f32_16x16x32_bf16 v[24:27], v[164:167], v[224:227], v[24:27]
	v_mfma_f32_16x16x32_bf16 v[12:15], v[156:159], v[232:235], v[12:15]
	v_mfma_f32_16x16x32_bf16 v[8:11], v[164:167], v[232:235], v[8:11]
	v_mfma_f32_16x16x32_bf16 v[60:63], v[160:163], v[212:215], v[60:63]
	v_mfma_f32_16x16x32_bf16 v[56:59], v[188:191], v[212:215], v[56:59]
	v_mfma_f32_16x16x32_bf16 v[44:47], v[160:163], v[220:223], v[44:47]
	v_mfma_f32_16x16x32_bf16 v[40:43], v[188:191], v[220:223], v[40:43]
	v_mfma_f32_16x16x32_bf16 v[28:31], v[160:163], v[228:231], v[28:31]
	v_mfma_f32_16x16x32_bf16 v[24:27], v[188:191], v[228:231], v[24:27]
	v_mfma_f32_16x16x32_bf16 v[12:15], v[160:163], v[236:239], v[12:15]
	v_mfma_f32_16x16x32_bf16 v[8:11], v[188:191], v[236:239], v[8:11]
	v_mfma_f32_16x16x32_bf16 v[52:55], v[192:195], v[208:211], v[52:55]
	v_mfma_f32_16x16x32_bf16 v[48:51], v[200:203], v[208:211], v[48:51]
	v_mfma_f32_16x16x32_bf16 v[36:39], v[192:195], v[216:219], v[36:39]
	v_mfma_f32_16x16x32_bf16 v[32:35], v[200:203], v[216:219], v[32:35]
	v_mfma_f32_16x16x32_bf16 v[20:23], v[192:195], v[224:227], v[20:23]
	v_mfma_f32_16x16x32_bf16 v[16:19], v[200:203], v[224:227], v[16:19]
	v_mfma_f32_16x16x32_bf16 v[4:7], v[192:195], v[232:235], v[4:7]
	v_mfma_f32_16x16x32_bf16 v[0:3], v[200:203], v[232:235], v[0:3]
	v_mfma_f32_16x16x32_bf16 v[52:55], v[196:199], v[212:215], v[52:55]
	v_mfma_f32_16x16x32_bf16 v[48:51], v[204:207], v[212:215], v[48:51]
	v_mfma_f32_16x16x32_bf16 v[36:39], v[196:199], v[220:223], v[36:39]
	v_mfma_f32_16x16x32_bf16 v[32:35], v[204:207], v[220:223], v[32:35]
	v_mfma_f32_16x16x32_bf16 v[20:23], v[196:199], v[228:231], v[20:23]
	v_mfma_f32_16x16x32_bf16 v[16:19], v[204:207], v[228:231], v[16:19]
	v_mfma_f32_16x16x32_bf16 v[4:7], v[196:199], v[236:239], v[4:7]
	v_mfma_f32_16x16x32_bf16 v[0:3], v[204:207], v[236:239], v[0:3]
	s_barrier
	s_add_u32 s33, s33, 0x100
	s_addc_u32 s54, s54, 0
	s_add_u32 s26, s26, 0x100
	s_addc_u32 s27, s27, 0
	s_cmp_ge_i32 s55, s46
	s_mov_b32 s28, s55
	s_cbranch_scc0 .LBB0_2148
	v_readlane_b32 s54, v254, 52
	v_readlane_b32 s55, v254, 53
	v_readlane_b32 s92, v254, 54
	v_readlane_b32 s94, v254, 55

; #define PG8_STAGE(bufoff, gbase, voff) do { _Pragma("unroll") for (int _i = 0; _i < 2; ++_i) \
;         __builtin_amdgcn_global_load_lds((const unsigned*)((const char*)(gbase) + (voff)[_i]), (PG8_LAS unsigned*)(lds + (bufoff) + ldsw + _i * 8192), 16, 0, 0); } while (0)
; #define PG8_LDA(dst, b, h) do { _Pragma("unroll") for (int m = 0; m < 4; ++m) _Pragma("unroll") for (int k = 0; k < 2; ++k) dst[m][k] = *(const PG8_LAS bf16x8*)(lds + PG8_SA(b, h) + aoff + m * 2048 + k * 1024); } while (0)
; #define PG8_LDB(dst, b, h) do { _Pragma("unroll") for (int n = 0; n < 2; ++n) _Pragma("unroll") for (int k = 0; k < 2; ++k) dst[n][k] = *(const PG8_LAS bf16x8*)(lds + PG8_SB(b, h) + boff + n * 2048 + k * 1024); } while (0)
; #define PG8_MMA(ai, bj, At, Bt) do { __builtin_amdgcn_s_setprio(1); _Pragma("unroll") for (int m = 0; m < 4; ++m) _Pragma("unroll") for (int n = 0; n < 2; ++n) _Pragma("unroll") for (int k = 0; k < 2; ++k) \
;         acc[ai][bj][m][n] = __builtin_amdgcn_mfma_f32_16x16x32_bf16(Bt[n][k], At[m][k], acc[ai][bj][m][n], 0, 0, 0); __builtin_amdgcn_s_setprio(0); } while (0)
; #define PG8_WAIT_V(n) asm volatile("s_waitcnt vmcnt(" #n ")" ::: "memory")
; #define PG8_WAIT_L(n) asm volatile("s_waitcnt lgkmcnt(" #n ")" ::: "memory")
; #define PG8_BAR __builtin_amdgcn_s_barrier()
; #define PG8_SCHED __builtin_amdgcn_sched_barrier(0)
; template <class Epi, class Sched>
; __device__ __forceinline__ void gemm_phase(int wid_s, PG8_LAS unsigned char* lds, const Gemm g, const Sched& S, const Epi& E) {
;     ...
;             const bool last = (t == nt - 2);
;             const char* a1 = cA + (size_t)(t + 1) * kstep;
;             const char* a2 = last ? nA : cA + (size_t)(t + 2) * kstep; const char* b2 = last ? nB : cB + (size_t)(t + 2) * kstep;
;             const char* a3 = a2 + kstep; const char* b3 = b2 + kstep;
;             PG8_LDB(B0, 0, 0); PG8_LDB(B1, 0, 1); PG8_SCHED; PG8_LDA(At, 0, 0); PG8_STAGE(PG8_SA(1, 1), a1 + hstepA, voffA);
;             PG8_WAIT_V(8); PG8_WAIT_L(0); PG8_BAR; PG8_MMA(0, 0, At, B0); PG8_MMA(0, 1, At, B1); PG8_BAR; PG8_SCHED;
;             PG8_LDA(At, 0, 1); PG8_STAGE(PG8_SB(0, 0), b2, voffB); PG8_STAGE(PG8_SB(0, 1), b2 + hstepB, voffB); PG8_STAGE(PG8_SA(0, 0), a2, voffA);
;             PG8_WAIT_V(8); PG8_WAIT_L(0); PG8_BAR; PG8_MMA(1, 0, At, B0); PG8_MMA(1, 1, At, B1); PG8_BAR; PG8_SCHED;
.LBB0_2305:
	s_add_i32 s44, s34, 2
	s_add_u32 s45, s4, 0x80
	s_addc_u32 s35, s5, 0
	s_add_i32 s18, 0, 0x10000
	s_cmp_eq_u32 s95, s34
	s_cselect_b32 s35, s29, s35
	s_cselect_b32 s34, s28, s45
	v_add_u32_e32 v142, s18, v157
	s_cselect_b32 vcc_hi, s31, s51
	s_cselect_b32 vcc_lo, s30, s33
	s_add_i32 s45, 0, 0x14000
	ds_read_b128 v[138:141], v142
	ds_read_b128 v[160:163], v142 offset:1024
	ds_read_b128 v[164:167], v142 offset:2048
	ds_read_b128 v[188:191], v142 offset:3072
	v_add_u32_e32 v142, s45, v157
	ds_read_b128 v[192:195], v142
	ds_read_b128 v[196:199], v142 offset:1024
	ds_read_b128 v[200:203], v142 offset:2048
	ds_read_b128 v[204:207], v142 offset:3072
	v_lshl_add_u64 v[142:143], s[4:5], 0, v[136:137]
	s_add_i32 m0, s52, 0xc000
	ds_read_b128 v[208:211], v159
	ds_read_b128 v[212:215], v159 offset:1024
	ds_read_b128 v[216:219], v159 offset:2048
	ds_read_b128 v[220:223], v159 offset:3072
	ds_read_b128 v[224:227], v159 offset:4096
	ds_read_b128 v[228:231], v159 offset:5120
	ds_read_b128 v[232:235], v159 offset:6144
	ds_read_b128 v[236:239], v159 offset:7168
	global_load_lds_dwordx4 v[142:143], off
	v_lshl_add_u64 v[142:143], s[4:5], 0, v[134:135]
	s_add_i32 m0, s52, 0xe000
	s_nop 0
	global_load_lds_dwordx4 v[142:143], off
	s_waitcnt vmcnt(8)
	s_waitcnt lgkmcnt(0)
	s_barrier
	s_waitcnt lgkmcnt(0)
	v_mfma_f32_16x16x32_bf16 v[124:127], v[138:141], v[208:211], v[124:127]
	v_mfma_f32_16x16x32_bf16 v[120:123], v[164:167], v[208:211], v[120:123]
	v_mfma_f32_16x16x32_bf16 v[108:111], v[138:141], v[216:219], v[108:111]
	v_mfma_f32_16x16x32_bf16 v[104:107], v[164:167], v[216:219], v[104:107]
	v_mfma_f32_16x16x32_bf16 v[92:95], v[138:141], v[224:227], v[92:95]
	v_mfma_f32_16x16x32_bf16 v[88:91], v[164:167], v[224:227], v[88:91]
	v_mfma_f32_16x16x32_bf16 v[76:79], v[138:141], v[232:235], v[76:79]
	v_mfma_f32_16x16x32_bf16 v[72:75], v[164:167], v[232:235], v[72:75]
	v_mfma_f32_16x16x32_bf16 v[124:127], v[160:163], v[212:215], v[124:127]
	v_mfma_f32_16x16x32_bf16 v[120:123], v[188:191], v[212:215], v[120:123]
	v_mfma_f32_16x16x32_bf16 v[108:111], v[160:163], v[220:223], v[108:111]
	v_mfma_f32_16x16x32_bf16 v[104:107], v[188:191], v[220:223], v[104:107]
	v_mfma_f32_16x16x32_bf16 v[92:95], v[160:163], v[228:231], v[92:95]
	v_mfma_f32_16x16x32_bf16 v[88:91], v[188:191], v[228:231], v[88:91]
	v_mfma_f32_16x16x32_bf16 v[76:79], v[160:163], v[236:239], v[76:79]
	v_mfma_f32_16x16x32_bf16 v[72:75], v[188:191], v[236:239], v[72:75]
	v_mfma_f32_16x16x32_bf16 v[116:119], v[192:195], v[208:211], v[116:119]
	v_mfma_f32_16x16x32_bf16 v[112:115], v[200:203], v[208:211], v[112:115]
	v_mfma_f32_16x16x32_bf16 v[100:103], v[192:195], v[216:219], v[100:103]
	v_mfma_f32_16x16x32_bf16 v[96:99], v[200:203], v[216:219], v[96:99]
	v_mfma_f32_16x16x32_bf16 v[84:87], v[192:195], v[224:227], v[84:87]
	v_mfma_f32_16x16x32_bf16 v[80:83], v[200:203], v[224:227], v[80:83]
	v_mfma_f32_16x16x32_bf16 v[68:71], v[192:195], v[232:235], v[68:71]
	v_mfma_f32_16x16x32_bf16 v[64:67], v[200:203], v[232:235], v[64:67]
	v_mfma_f32_16x16x32_bf16 v[116:119], v[196:199], v[212:215], v[116:119]
	v_mfma_f32_16x16x32_bf16 v[112:115], v[204:207], v[212:215], v[112:115]
	v_mfma_f32_16x16x32_bf16 v[100:103], v[196:199], v[220:223], v[100:103]
	v_mfma_f32_16x16x32_bf16 v[96:99], v[204:207], v[220:223], v[96:99]
	v_mfma_f32_16x16x32_bf16 v[84:87], v[196:199], v[228:231], v[84:87]
	v_mfma_f32_16x16x32_bf16 v[80:83], v[204:207], v[228:231], v[80:83]
	v_mfma_f32_16x16x32_bf16 v[68:71], v[196:199], v[236:239], v[68:71]
	v_mfma_f32_16x16x32_bf16 v[64:67], v[204:207], v[236:239], v[64:67]
	s_barrier
	s_add_i32 s18, s18, s47
	v_lshl_add_u64 v[142:143], vcc, 0, v[144:145]
	s_mov_b32 m0, s18
	ds_read_b128 v[208:211], v159 offset:16384
	ds_read_b128 v[212:215], v159 offset:17408
	ds_read_b128 v[216:219], v159 offset:18432
	ds_read_b128 v[220:223], v159 offset:19456
	ds_read_b128 v[224:227], v159 offset:20480
	ds_read_b128 v[228:231], v159 offset:21504
	ds_read_b128 v[232:235], v159 offset:22528
	ds_read_b128 v[236:239], v159 offset:23552
	global_load_lds_dwordx4 v[142:143], off
	s_add_i32 m0, s18, 0x2000
	v_lshl_add_u64 v[240:241], vcc, 0, v[132:133]
	s_add_u32 vcc_lo, vcc_lo, s12
	s_addc_u32 vcc_hi, vcc_hi, s13
	s_add_i32 s18, s45, s47
	global_load_lds_dwordx4 v[240:241], off
	v_lshl_add_u64 v[242:243], vcc, 0, v[144:145]
	s_mov_b32 m0, s18
	v_lshl_add_u64 v[244:245], vcc, 0, v[132:133]
	global_load_lds_dwordx4 v[242:243], off
	s_add_i32 m0, s18, 0x2000
	v_lshl_add_u64 v[246:247], s[34:35], 0, v[128:129]
	global_load_lds_dwordx4 v[244:245], off
	s_mov_b32 m0, s52
	v_lshl_add_u64 v[248:249], s[34:35], 0, v[130:131]
	global_load_lds_dwordx4 v[246:247], off
	s_mov_b32 m0, s53
	s_nop 0
	global_load_lds_dwordx4 v[248:249], off
	s_waitcnt vmcnt(8)
	s_waitcnt lgkmcnt(0)
	s_barrier
; #define PG8_STAGE(bufoff, gbase, voff) do { _Pragma("unroll") for (int _i = 0; _i < 2; ++_i) \
;         __builtin_amdgcn_global_load_lds((const unsigned*)((const char*)(gbase) + (voff)[_i]), (PG8_LAS unsigned*)(lds + (bufoff) + ldsw + _i * 8192), 16, 0, 0); } while (0)
; #define PG8_LDA(dst, b, h) do { _Pragma("unroll") for (int m = 0; m < 4; ++m) _Pragma("unroll") for (int k = 0; k < 2; ++k) dst[m][k] = *(const PG8_LAS bf16x8*)(lds + PG8_SA(b, h) + aoff + m * 2048 + k * 1024); } while (0)
; #define PG8_LDB(dst, b, h) do { _Pragma("unroll") for (int n = 0; n < 2; ++n) _Pragma("unroll") for (int k = 0; k < 2; ++k) dst[n][k] = *(const PG8_LAS bf16x8*)(lds + PG8_SB(b, h) + boff + n * 2048 + k * 1024); } while (0)
; #define PG8_MMA(ai, bj, At, Bt) do { __builtin_amdgcn_s_setprio(1); _Pragma("unroll") for (int m = 0; m < 4; ++m) _Pragma("unroll") for (int n = 0; n < 2; ++n) _Pragma("unroll") for (int k = 0; k < 2; ++k) \
;         acc[ai][bj][m][n] = __builtin_amdgcn_mfma_f32_16x16x32_bf16(Bt[n][k], At[m][k], acc[ai][bj][m][n], 0, 0, 0); __builtin_amdgcn_s_setprio(0); } while (0)
; #define PG8_WAIT_V(n) asm volatile("s_waitcnt vmcnt(" #n ")" ::: "memory")
; #define PG8_WAIT_L(n) asm volatile("s_waitcnt lgkmcnt(" #n ")" ::: "memory")
; #define PG8_BAR __builtin_amdgcn_s_barrier()
; #define PG8_SCHED __builtin_amdgcn_sched_barrier(0)
; template <class Epi, class Sched>
; __device__ __forceinline__ void gemm_phase(int wid_s, PG8_LAS unsigned char* lds, const Gemm g, const Sched& S, const Epi& E) {
;     ...
;             PG8_WAIT_V(8); PG8_WAIT_L(0); PG8_BAR; PG8_MMA(1, 0, At, B0); PG8_MMA(1, 1, At, B1); PG8_BAR; PG8_SCHED;
;             PG8_LDB(B0, 1, 0); PG8_LDB(B1, 1, 1); PG8_SCHED; PG8_LDA(At, 1, 0); PG8_STAGE(PG8_SA(0, 1), a2 + hstepA, voffA);
;             PG8_WAIT_V(8); PG8_WAIT_L(0); PG8_BAR; PG8_MMA(0, 0, At, B0); PG8_MMA(0, 1, At, B1); PG8_BAR; PG8_SCHED;
	s_waitcnt lgkmcnt(0)
	v_mfma_f32_16x16x32_bf16 v[60:63], v[138:141], v[208:211], v[60:63]
	v_mfma_f32_16x16x32_bf16 v[56:59], v[164:167], v[208:211], v[56:59]
	v_mfma_f32_16x16x32_bf16 v[44:47], v[138:141], v[216:219], v[44:47]
	v_mfma_f32_16x16x32_bf16 v[40:43], v[164:167], v[216:219], v[40:43]
	v_mfma_f32_16x16x32_bf16 v[28:31], v[138:141], v[224:227], v[28:31]
	v_mfma_f32_16x16x32_bf16 v[24:27], v[164:167], v[224:227], v[24:27]
	v_mfma_f32_16x16x32_bf16 v[12:15], v[138:141], v[232:235], v[12:15]
	v_mfma_f32_16x16x32_bf16 v[8:11], v[164:167], v[232:235], v[8:11]
	v_mfma_f32_16x16x32_bf16 v[60:63], v[160:163], v[212:215], v[60:63]
	v_mfma_f32_16x16x32_bf16 v[56:59], v[188:191], v[212:215], v[56:59]
	v_mfma_f32_16x16x32_bf16 v[44:47], v[160:163], v[220:223], v[44:47]
	v_mfma_f32_16x16x32_bf16 v[40:43], v[188:191], v[220:223], v[40:43]
	v_mfma_f32_16x16x32_bf16 v[28:31], v[160:163], v[228:231], v[28:31]
	v_mfma_f32_16x16x32_bf16 v[24:27], v[188:191], v[228:231], v[24:27]
	v_mfma_f32_16x16x32_bf16 v[12:15], v[160:163], v[236:239], v[12:15]
	v_mfma_f32_16x16x32_bf16 v[8:11], v[188:191], v[236:239], v[8:11]
	v_mfma_f32_16x16x32_bf16 v[52:55], v[192:195], v[208:211], v[52:55]
	v_mfma_f32_16x16x32_bf16 v[48:51], v[200:203], v[208:211], v[48:51]
	v_mfma_f32_16x16x32_bf16 v[36:39], v[192:195], v[216:219], v[36:39]
	v_mfma_f32_16x16x32_bf16 v[32:35], v[200:203], v[216:219], v[32:35]
	v_mfma_f32_16x16x32_bf16 v[20:23], v[192:195], v[224:227], v[20:23]
	v_mfma_f32_16x16x32_bf16 v[16:19], v[200:203], v[224:227], v[16:19]
	v_mfma_f32_16x16x32_bf16 v[4:7], v[192:195], v[232:235], v[4:7]
	v_mfma_f32_16x16x32_bf16 v[0:3], v[200:203], v[232:235], v[0:3]
	v_mfma_f32_16x16x32_bf16 v[52:55], v[196:199], v[212:215], v[52:55]
	v_mfma_f32_16x16x32_bf16 v[48:51], v[204:207], v[212:215], v[48:51]
	v_mfma_f32_16x16x32_bf16 v[36:39], v[196:199], v[220:223], v[36:39]
	v_mfma_f32_16x16x32_bf16 v[32:35], v[204:207], v[220:223], v[32:35]
	v_mfma_f32_16x16x32_bf16 v[20:23], v[196:199], v[228:231], v[20:23]
	v_mfma_f32_16x16x32_bf16 v[16:19], v[204:207], v[228:231], v[16:19]
	v_mfma_f32_16x16x32_bf16 v[4:7], v[196:199], v[236:239], v[4:7]
	v_mfma_f32_16x16x32_bf16 v[0:3], v[204:207], v[236:239], v[0:3]
	s_barrier
	s_add_i32 s18, 0, 0x18000
	v_add_u32_e32 v185, s18, v157
	s_add_i32 s45, 0, 0x1c000
	ds_read_b128 v[138:141], v185
	ds_read_b128 v[160:163], v185 offset:1024
	ds_read_b128 v[164:167], v185 offset:2048
	ds_read_b128 v[188:191], v185 offset:3072
	v_add_u32_e32 v185, s45, v157
	ds_read_b128 v[192:195], v185
	ds_read_b128 v[196:199], v185 offset:1024
	ds_read_b128 v[200:203], v185 offset:2048
	ds_read_b128 v[204:207], v185 offset:3072
	s_add_u32 s34, s34, s10
	s_addc_u32 s35, s35, s11
	s_mov_b32 m0, s54
	v_lshl_add_u64 v[250:251], s[34:35], 0, v[128:129]
	ds_read_b128 v[208:211], v159 offset:32768
	ds_read_b128 v[212:215], v159 offset:33792
	ds_read_b128 v[216:219], v159 offset:34816
	ds_read_b128 v[220:223], v159 offset:35840
	ds_read_b128 v[224:227], v159 offset:36864
	ds_read_b128 v[228:231], v159 offset:37888
	ds_read_b128 v[232:235], v159 offset:38912
	ds_read_b128 v[236:239], v159 offset:39936
	global_load_lds_dwordx4 v[250:251], off
	v_lshl_add_u64 v[250:251], s[34:35], 0, v[130:131]
	s_mov_b32 m0, s55
	s_nop 0
	global_load_lds_dwordx4 v[250:251], off
	s_waitcnt vmcnt(8)
	s_waitcnt lgkmcnt(0)
	s_barrier
	s_waitcnt lgkmcnt(0)
	v_mfma_f32_16x16x32_bf16 v[124:127], v[138:141], v[208:211], v[124:127]
	v_mfma_f32_16x16x32_bf16 v[120:123], v[164:167], v[208:211], v[120:123]
	v_mfma_f32_16x16x32_bf16 v[108:111], v[138:141], v[216:219], v[108:111]
	v_mfma_f32_16x16x32_bf16 v[104:107], v[164:167], v[216:219], v[104:107]
	v_mfma_f32_16x16x32_bf16 v[92:95], v[138:141], v[224:227], v[92:95]
	v_mfma_f32_16x16x32_bf16 v[88:91], v[164:167], v[224:227], v[88:91]
	v_mfma_f32_16x16x32_bf16 v[76:79], v[138:141], v[232:235], v[76:79]
	v_mfma_f32_16x16x32_bf16 v[72:75], v[164:167], v[232:235], v[72:75]
	v_mfma_f32_16x16x32_bf16 v[124:127], v[160:163], v[212:215], v[124:127]
	v_mfma_f32_16x16x32_bf16 v[120:123], v[188:191], v[212:215], v[120:123]
	v_mfma_f32_16x16x32_bf16 v[108:111], v[160:163], v[220:223], v[108:111]
	v_mfma_f32_16x16x32_bf16 v[104:107], v[188:191], v[220:223], v[104:107]
	v_mfma_f32_16x16x32_bf16 v[92:95], v[160:163], v[228:231], v[92:95]
	v_mfma_f32_16x16x32_bf16 v[88:91], v[188:191], v[228:231], v[88:91]
	v_mfma_f32_16x16x32_bf16 v[76:79], v[160:163], v[236:239], v[76:79]
	v_mfma_f32_16x16x32_bf16 v[72:75], v[188:191], v[236:239], v[72:75]
	v_mfma_f32_16x16x32_bf16 v[116:119], v[192:195], v[208:211], v[116:119]
	v_mfma_f32_16x16x32_bf16 v[112:115], v[200:203], v[208:211], v[112:115]
	v_mfma_f32_16x16x32_bf16 v[100:103], v[192:195], v[216:219], v[100:103]
	v_mfma_f32_16x16x32_bf16 v[96:99], v[200:203], v[216:219], v[96:99]
	v_mfma_f32_16x16x32_bf16 v[84:87], v[192:195], v[224:227], v[84:87]
	v_mfma_f32_16x16x32_bf16 v[80:83], v[200:203], v[224:227], v[80:83]
	v_mfma_f32_16x16x32_bf16 v[68:71], v[192:195], v[232:235], v[68:71]
	v_mfma_f32_16x16x32_bf16 v[64:67], v[200:203], v[232:235], v[64:67]
	v_mfma_f32_16x16x32_bf16 v[116:119], v[196:199], v[212:215], v[116:119]
	v_mfma_f32_16x16x32_bf16 v[112:115], v[204:207], v[212:215], v[112:115]
	v_mfma_f32_16x16x32_bf16 v[100:103], v[196:199], v[220:223], v[100:103]
	v_mfma_f32_16x16x32_bf16 v[96:99], v[204:207], v[220:223], v[96:99]
	v_mfma_f32_16x16x32_bf16 v[84:87], v[196:199], v[228:231], v[84:87]
	v_mfma_f32_16x16x32_bf16 v[80:83], v[204:207], v[228:231], v[80:83]
	v_mfma_f32_16x16x32_bf16 v[68:71], v[196:199], v[236:239], v[68:71]
	v_mfma_f32_16x16x32_bf16 v[64:67], v[204:207], v[236:239], v[64:67]
	s_barrier
; #define PG8_STAGE(bufoff, gbase, voff) do { _Pragma("unroll") for (int _i = 0; _i < 2; ++_i) \
;         __builtin_amdgcn_global_load_lds((const unsigned*)((const char*)(gbase) + (voff)[_i]), (PG8_LAS unsigned*)(lds + (bufoff) + ldsw + _i * 8192), 16, 0, 0); } while (0)
; #define PG8_LDA(dst, b, h) do { _Pragma("unroll") for (int m = 0; m < 4; ++m) _Pragma("unroll") for (int k = 0; k < 2; ++k) dst[m][k] = *(const PG8_LAS bf16x8*)(lds + PG8_SA(b, h) + aoff + m * 2048 + k * 1024); } while (0)
; #define PG8_MMA(ai, bj, At, Bt) do { __builtin_amdgcn_s_setprio(1); _Pragma("unroll") for (int m = 0; m < 4; ++m) _Pragma("unroll") for (int n = 0; n < 2; ++n) _Pragma("unroll") for (int k = 0; k < 2; ++k) \
;         acc[ai][bj][m][n] = __builtin_amdgcn_mfma_f32_16x16x32_bf16(Bt[n][k], At[m][k], acc[ai][bj][m][n], 0, 0, 0); __builtin_amdgcn_s_setprio(0); } while (0)
; #define PG8_WAIT_V(n) asm volatile("s_waitcnt vmcnt(" #n ")" ::: "memory")
; #define PG8_WAIT_L(n) asm volatile("s_waitcnt lgkmcnt(" #n ")" ::: "memory")
; #define PG8_BAR __builtin_amdgcn_s_barrier()
; #define PG8_SCHED __builtin_amdgcn_sched_barrier(0)
; template <class Epi, class Sched>
; __device__ __forceinline__ void gemm_phase(int wid_s, PG8_LAS unsigned char* lds, const Gemm g, const Sched& S, const Epi& E) {
;     ...
;             PG8_LDA(At, 1, 1); PG8_STAGE(PG8_SB(1, 0), b3, voffB); PG8_STAGE(PG8_SB(1, 1), b3 + hstepB, voffB); PG8_STAGE(PG8_SA(1, 0), a3, voffA);
;             PG8_WAIT_V(8); PG8_WAIT_L(0); PG8_BAR; PG8_MMA(1, 0, At, B0); PG8_MMA(1, 1, At, B1); PG8_BAR; PG8_SCHED;
;         }
	s_add_i32 s18, s18, s47
	v_lshl_add_u64 v[142:143], v[142:143], 0, s[96:97]
	s_mov_b32 m0, s18
	ds_read_b128 v[208:211], v159 offset:49152
	ds_read_b128 v[212:215], v159 offset:50176
	ds_read_b128 v[216:219], v159 offset:51200
	ds_read_b128 v[220:223], v159 offset:52224
	ds_read_b128 v[224:227], v159 offset:53248
	ds_read_b128 v[228:231], v159 offset:54272
	ds_read_b128 v[232:235], v159 offset:55296
	ds_read_b128 v[236:239], v159 offset:56320
	global_load_lds_dwordx4 v[142:143], off
	v_lshl_add_u64 v[142:143], v[240:241], 0, s[96:97]
	s_add_i32 m0, s18, 0x2000
	s_add_i32 s18, s45, s47
	global_load_lds_dwordx4 v[142:143], off
	v_lshl_add_u64 v[142:143], v[242:243], 0, s[96:97]
	s_mov_b32 m0, s18
	s_nop 0
	global_load_lds_dwordx4 v[142:143], off
	v_lshl_add_u64 v[142:143], v[244:245], 0, s[96:97]
	s_add_i32 m0, s18, 0x2000
	s_nop 0
	global_load_lds_dwordx4 v[142:143], off
	v_lshl_add_u64 v[142:143], v[246:247], 0, s[96:97]
	s_mov_b32 m0, s56
	s_nop 0
	global_load_lds_dwordx4 v[142:143], off
	v_lshl_add_u64 v[142:143], v[248:249], 0, s[96:97]
	s_mov_b32 m0, s57
	s_nop 0
	global_load_lds_dwordx4 v[142:143], off
	s_waitcnt vmcnt(8)
	s_waitcnt lgkmcnt(0)
	s_barrier
	s_waitcnt lgkmcnt(0)
	v_mfma_f32_16x16x32_bf16 v[60:63], v[138:141], v[208:211], v[60:63]
	v_mfma_f32_16x16x32_bf16 v[56:59], v[164:167], v[208:211], v[56:59]
	v_mfma_f32_16x16x32_bf16 v[44:47], v[138:141], v[216:219], v[44:47]
	v_mfma_f32_16x16x32_bf16 v[40:43], v[164:167], v[216:219], v[40:43]
	v_mfma_f32_16x16x32_bf16 v[28:31], v[138:141], v[224:227], v[28:31]
	v_mfma_f32_16x16x32_bf16 v[24:27], v[164:167], v[224:227], v[24:27]
	v_mfma_f32_16x16x32_bf16 v[12:15], v[138:141], v[232:235], v[12:15]
	v_mfma_f32_16x16x32_bf16 v[8:11], v[164:167], v[232:235], v[8:11]
	v_mfma_f32_16x16x32_bf16 v[60:63], v[160:163], v[212:215], v[60:63]
	v_mfma_f32_16x16x32_bf16 v[56:59], v[188:191], v[212:215], v[56:59]
	v_mfma_f32_16x16x32_bf16 v[44:47], v[160:163], v[220:223], v[44:47]
	v_mfma_f32_16x16x32_bf16 v[40:43], v[188:191], v[220:223], v[40:43]
	v_mfma_f32_16x16x32_bf16 v[28:31], v[160:163], v[228:231], v[28:31]
	v_mfma_f32_16x16x32_bf16 v[24:27], v[188:191], v[228:231], v[24:27]
	v_mfma_f32_16x16x32_bf16 v[12:15], v[160:163], v[236:239], v[12:15]
	v_mfma_f32_16x16x32_bf16 v[8:11], v[188:191], v[236:239], v[8:11]
	v_mfma_f32_16x16x32_bf16 v[52:55], v[192:195], v[208:211], v[52:55]
	v_mfma_f32_16x16x32_bf16 v[48:51], v[200:203], v[208:211], v[48:51]
	v_mfma_f32_16x16x32_bf16 v[36:39], v[192:195], v[216:219], v[36:39]
	v_mfma_f32_16x16x32_bf16 v[32:35], v[200:203], v[216:219], v[32:35]
	v_mfma_f32_16x16x32_bf16 v[20:23], v[192:195], v[224:227], v[20:23]
	v_mfma_f32_16x16x32_bf16 v[16:19], v[200:203], v[224:227], v[16:19]
	v_mfma_f32_16x16x32_bf16 v[4:7], v[192:195], v[232:235], v[4:7]
	v_mfma_f32_16x16x32_bf16 v[0:3], v[200:203], v[232:235], v[0:3]
	v_mfma_f32_16x16x32_bf16 v[52:55], v[196:199], v[212:215], v[52:55]
	v_mfma_f32_16x16x32_bf16 v[48:51], v[204:207], v[212:215], v[48:51]
	v_mfma_f32_16x16x32_bf16 v[36:39], v[196:199], v[220:223], v[36:39]
	v_mfma_f32_16x16x32_bf16 v[32:35], v[204:207], v[220:223], v[32:35]
	v_mfma_f32_16x16x32_bf16 v[20:23], v[196:199], v[228:231], v[20:23]
	v_mfma_f32_16x16x32_bf16 v[16:19], v[204:207], v[228:231], v[16:19]
	v_mfma_f32_16x16x32_bf16 v[4:7], v[196:199], v[236:239], v[4:7]
	v_mfma_f32_16x16x32_bf16 v[0:3], v[204:207], v[236:239], v[0:3]
	s_barrier
	s_add_u32 s33, s33, 0x100
	s_addc_u32 s51, s51, 0
	s_add_u32 s4, s4, 0x100
	s_addc_u32 s5, s5, 0
	s_cmp_ge_i32 s44, s94
	s_mov_b32 s34, s44
	s_cbranch_scc0 .LBB0_2305
	s_movk_i32 s33, 0x300

; #define PG8_STAGE(bufoff, gbase, voff) do { _Pragma("unroll") for (int _i = 0; _i < 2; ++_i) \
;         __builtin_amdgcn_global_load_lds((const unsigned*)((const char*)(gbase) + (voff)[_i]), (PG8_LAS unsigned*)(lds + (bufoff) + ldsw + _i * 8192), 16, 0, 0); } while (0)
; #define PG8_LDA(dst, b, h) do { _Pragma("unroll") for (int m = 0; m < 4; ++m) _Pragma("unroll") for (int k = 0; k < 2; ++k) dst[m][k] = *(const PG8_LAS bf16x8*)(lds + PG8_SA(b, h) + aoff + m * 2048 + k * 1024); } while (0)
; #define PG8_LDB(dst, b, h) do { _Pragma("unroll") for (int n = 0; n < 2; ++n) _Pragma("unroll") for (int k = 0; k < 2; ++k) dst[n][k] = *(const PG8_LAS bf16x8*)(lds + PG8_SB(b, h) + boff + n * 2048 + k * 1024); } while (0)
; #define PG8_MMA(ai, bj, At, Bt) do { __builtin_amdgcn_s_setprio(1); _Pragma("unroll") for (int m = 0; m < 4; ++m) _Pragma("unroll") for (int n = 0; n < 2; ++n) _Pragma("unroll") for (int k = 0; k < 2; ++k) \
;         acc[ai][bj][m][n] = __builtin_amdgcn_mfma_f32_16x16x32_bf16(Bt[n][k], At[m][k], acc[ai][bj][m][n], 0, 0, 0); __builtin_amdgcn_s_setprio(0); } while (0)
; #define PG8_WAIT_V(n) asm volatile("s_waitcnt vmcnt(" #n ")" ::: "memory")
; #define PG8_WAIT_L(n) asm volatile("s_waitcnt lgkmcnt(" #n ")" ::: "memory")
; #define PG8_BAR __builtin_amdgcn_s_barrier()
; #define PG8_SCHED __builtin_amdgcn_sched_barrier(0)
; template <class Epi, class Sched>
; __device__ __forceinline__ void gemm_phase(int wid_s, PG8_LAS unsigned char* lds, const Gemm g, const Sched& S, const Epi& E) {
;     ...
;             const bool last = (t == nt - 2);
;             const char* a1 = cA + (size_t)(t + 1) * kstep;
;             const char* a2 = last ? nA : cA + (size_t)(t + 2) * kstep; const char* b2 = last ? nB : cB + (size_t)(t + 2) * kstep;
;             const char* a3 = a2 + kstep; const char* b3 = b2 + kstep;
;             PG8_LDB(B0, 0, 0); PG8_LDB(B1, 0, 1); PG8_SCHED; PG8_LDA(At, 0, 0); PG8_STAGE(PG8_SA(1, 1), a1 + hstepA, voffA);
;             PG8_WAIT_V(8); PG8_WAIT_L(0); PG8_BAR; PG8_MMA(0, 0, At, B0); PG8_MMA(0, 1, At, B1); PG8_BAR; PG8_SCHED;
;             PG8_LDA(At, 0, 1); PG8_STAGE(PG8_SB(0, 0), b2, voffB); PG8_STAGE(PG8_SB(0, 1), b2 + hstepB, voffB); PG8_STAGE(PG8_SA(0, 0), a2, voffA);
;             PG8_WAIT_V(8); PG8_WAIT_L(0); PG8_BAR; PG8_MMA(1, 0, At, B0); PG8_MMA(1, 1, At, B1); PG8_BAR; PG8_SCHED;
.LBB0_2473:
	s_add_i32 s51, s28, 2
	s_add_u32 s56, s26, 0x80
	s_addc_u32 s29, s27, 0
	s_add_i32 s92, 0, 0x10000
	s_cmp_eq_u32 s46, s28
	s_cselect_b32 s29, s5, s29
	s_cselect_b32 s28, s4, s56
	v_add_u32_e32 v138, s92, v154
	s_cselect_b32 s57, s25, s50
	s_cselect_b32 s56, s24, s33
	s_add_i32 s94, 0, 0x14000
	ds_read_b128 v[158:161], v138
	ds_read_b128 v[162:165], v138 offset:1024
	ds_read_b128 v[188:191], v138 offset:2048
	ds_read_b128 v[192:195], v138 offset:3072
	v_add_u32_e32 v138, s94, v154
	ds_read_b128 v[196:199], v138
	ds_read_b128 v[200:203], v138 offset:1024
	ds_read_b128 v[204:207], v138 offset:2048
	ds_read_b128 v[208:211], v138 offset:3072
	v_lshl_add_u64 v[138:139], s[26:27], 0, v[136:137]
	s_add_i32 m0, s36, 0xc000
	ds_read_b128 v[212:215], v156
	ds_read_b128 v[216:219], v156 offset:1024
	ds_read_b128 v[220:223], v156 offset:2048
	ds_read_b128 v[224:227], v156 offset:3072
	ds_read_b128 v[228:231], v156 offset:4096
	ds_read_b128 v[232:235], v156 offset:5120
	ds_read_b128 v[236:239], v156 offset:6144
	ds_read_b128 v[240:243], v156 offset:7168
	global_load_lds_dwordx4 v[138:139], off
	v_lshl_add_u64 v[138:139], s[26:27], 0, v[134:135]
	s_add_i32 m0, s36, 0xe000
	s_nop 0
	global_load_lds_dwordx4 v[138:139], off
	s_waitcnt vmcnt(8)
	s_waitcnt lgkmcnt(0)
	s_barrier
	s_waitcnt lgkmcnt(0)
	v_mfma_f32_16x16x32_bf16 v[124:127], v[158:161], v[212:215], v[124:127]
	v_mfma_f32_16x16x32_bf16 v[120:123], v[188:191], v[212:215], v[120:123]
	v_mfma_f32_16x16x32_bf16 v[108:111], v[158:161], v[220:223], v[108:111]
	v_mfma_f32_16x16x32_bf16 v[104:107], v[188:191], v[220:223], v[104:107]
	v_mfma_f32_16x16x32_bf16 v[92:95], v[158:161], v[228:231], v[92:95]
	v_mfma_f32_16x16x32_bf16 v[88:91], v[188:191], v[228:231], v[88:91]
	v_mfma_f32_16x16x32_bf16 v[76:79], v[158:161], v[236:239], v[76:79]
	v_mfma_f32_16x16x32_bf16 v[72:75], v[188:191], v[236:239], v[72:75]
	v_mfma_f32_16x16x32_bf16 v[124:127], v[162:165], v[216:219], v[124:127]
	v_mfma_f32_16x16x32_bf16 v[120:123], v[192:195], v[216:219], v[120:123]
	v_mfma_f32_16x16x32_bf16 v[108:111], v[162:165], v[224:227], v[108:111]
	v_mfma_f32_16x16x32_bf16 v[104:107], v[192:195], v[224:227], v[104:107]
	v_mfma_f32_16x16x32_bf16 v[92:95], v[162:165], v[232:235], v[92:95]
	v_mfma_f32_16x16x32_bf16 v[88:91], v[192:195], v[232:235], v[88:91]
	v_mfma_f32_16x16x32_bf16 v[76:79], v[162:165], v[240:243], v[76:79]
	v_mfma_f32_16x16x32_bf16 v[72:75], v[192:195], v[240:243], v[72:75]
	v_mfma_f32_16x16x32_bf16 v[116:119], v[196:199], v[212:215], v[116:119]
	v_mfma_f32_16x16x32_bf16 v[112:115], v[204:207], v[212:215], v[112:115]
	v_mfma_f32_16x16x32_bf16 v[100:103], v[196:199], v[220:223], v[100:103]
	v_mfma_f32_16x16x32_bf16 v[96:99], v[204:207], v[220:223], v[96:99]
	v_mfma_f32_16x16x32_bf16 v[84:87], v[196:199], v[228:231], v[84:87]
	v_mfma_f32_16x16x32_bf16 v[80:83], v[204:207], v[228:231], v[80:83]
	v_mfma_f32_16x16x32_bf16 v[68:71], v[196:199], v[236:239], v[68:71]
	v_mfma_f32_16x16x32_bf16 v[64:67], v[204:207], v[236:239], v[64:67]
	v_mfma_f32_16x16x32_bf16 v[116:119], v[200:203], v[216:219], v[116:119]
	v_mfma_f32_16x16x32_bf16 v[112:115], v[208:211], v[216:219], v[112:115]
	v_mfma_f32_16x16x32_bf16 v[100:103], v[200:203], v[224:227], v[100:103]
	v_mfma_f32_16x16x32_bf16 v[96:99], v[208:211], v[224:227], v[96:99]
	v_mfma_f32_16x16x32_bf16 v[84:87], v[200:203], v[232:235], v[84:87]
	v_mfma_f32_16x16x32_bf16 v[80:83], v[208:211], v[232:235], v[80:83]
	v_mfma_f32_16x16x32_bf16 v[68:71], v[200:203], v[240:243], v[68:71]
	v_mfma_f32_16x16x32_bf16 v[64:67], v[208:211], v[240:243], v[64:67]
	s_barrier
	s_add_i32 s92, s92, s34
	v_lshl_add_u64 v[138:139], s[56:57], 0, v[144:145]
	s_mov_b32 m0, s92
	ds_read_b128 v[212:215], v156 offset:16384
	ds_read_b128 v[216:219], v156 offset:17408
	ds_read_b128 v[220:223], v156 offset:18432
	ds_read_b128 v[224:227], v156 offset:19456
	ds_read_b128 v[228:231], v156 offset:20480
	ds_read_b128 v[232:235], v156 offset:21504
	ds_read_b128 v[236:239], v156 offset:22528
	ds_read_b128 v[240:243], v156 offset:23552
	global_load_lds_dwordx4 v[138:139], off
	s_add_i32 m0, s92, 0x2000
	v_lshl_add_u64 v[142:143], s[56:57], 0, v[128:129]
	s_add_u32 s56, s56, s8
	s_addc_u32 s57, s57, s9
	s_add_i32 s92, s94, s34
	global_load_lds_dwordx4 v[142:143], off
	v_lshl_add_u64 v[166:167], s[56:57], 0, v[144:145]
	s_mov_b32 m0, s92
	v_lshl_add_u64 v[244:245], s[56:57], 0, v[128:129]
	global_load_lds_dwordx4 v[166:167], off
	s_add_i32 m0, s92, 0x2000
	v_lshl_add_u64 v[246:247], s[28:29], 0, v[132:133]
	global_load_lds_dwordx4 v[244:245], off
	s_mov_b32 m0, s36
	v_lshl_add_u64 v[248:249], s[28:29], 0, v[130:131]
	global_load_lds_dwordx4 v[246:247], off
	s_mov_b32 m0, s37
	s_nop 0
	global_load_lds_dwordx4 v[248:249], off
	s_waitcnt vmcnt(8)
	s_waitcnt lgkmcnt(0)
	s_barrier
; #define PG8_STAGE(bufoff, gbase, voff) do { _Pragma("unroll") for (int _i = 0; _i < 2; ++_i) \
;         __builtin_amdgcn_global_load_lds((const unsigned*)((const char*)(gbase) + (voff)[_i]), (PG8_LAS unsigned*)(lds + (bufoff) + ldsw + _i * 8192), 16, 0, 0); } while (0)
; #define PG8_LDA(dst, b, h) do { _Pragma("unroll") for (int m = 0; m < 4; ++m) _Pragma("unroll") for (int k = 0; k < 2; ++k) dst[m][k] = *(const PG8_LAS bf16x8*)(lds + PG8_SA(b, h) + aoff + m * 2048 + k * 1024); } while (0)
; #define PG8_LDB(dst, b, h) do { _Pragma("unroll") for (int n = 0; n < 2; ++n) _Pragma("unroll") for (int k = 0; k < 2; ++k) dst[n][k] = *(const PG8_LAS bf16x8*)(lds + PG8_SB(b, h) + boff + n * 2048 + k * 1024); } while (0)
; #define PG8_MMA(ai, bj, At, Bt) do { __builtin_amdgcn_s_setprio(1); _Pragma("unroll") for (int m = 0; m < 4; ++m) _Pragma("unroll") for (int n = 0; n < 2; ++n) _Pragma("unroll") for (int k = 0; k < 2; ++k) \
;         acc[ai][bj][m][n] = __builtin_amdgcn_mfma_f32_16x16x32_bf16(Bt[n][k], At[m][k], acc[ai][bj][m][n], 0, 0, 0); __builtin_amdgcn_s_setprio(0); } while (0)
; #define PG8_WAIT_V(n) asm volatile("s_waitcnt vmcnt(" #n ")" ::: "memory")
; #define PG8_WAIT_L(n) asm volatile("s_waitcnt lgkmcnt(" #n ")" ::: "memory")
; #define PG8_BAR __builtin_amdgcn_s_barrier()
; #define PG8_SCHED __builtin_amdgcn_sched_barrier(0)
; template <class Epi, class Sched>
; __device__ __forceinline__ void gemm_phase(int wid_s, PG8_LAS unsigned char* lds, const Gemm g, const Sched& S, const Epi& E) {
;     ...
;             PG8_WAIT_V(8); PG8_WAIT_L(0); PG8_BAR; PG8_MMA(1, 0, At, B0); PG8_MMA(1, 1, At, B1); PG8_BAR; PG8_SCHED;
;             PG8_LDB(B0, 1, 0); PG8_LDB(B1, 1, 1); PG8_SCHED; PG8_LDA(At, 1, 0); PG8_STAGE(PG8_SA(0, 1), a2 + hstepA, voffA);
;             PG8_WAIT_V(8); PG8_WAIT_L(0); PG8_BAR; PG8_MMA(0, 0, At, B0); PG8_MMA(0, 1, At, B1); PG8_BAR; PG8_SCHED;
	s_waitcnt lgkmcnt(0)
	v_mfma_f32_16x16x32_bf16 v[60:63], v[158:161], v[212:215], v[60:63]
	v_mfma_f32_16x16x32_bf16 v[56:59], v[188:191], v[212:215], v[56:59]
	v_mfma_f32_16x16x32_bf16 v[44:47], v[158:161], v[220:223], v[44:47]
	v_mfma_f32_16x16x32_bf16 v[40:43], v[188:191], v[220:223], v[40:43]
	v_mfma_f32_16x16x32_bf16 v[28:31], v[158:161], v[228:231], v[28:31]
	v_mfma_f32_16x16x32_bf16 v[24:27], v[188:191], v[228:231], v[24:27]
	v_mfma_f32_16x16x32_bf16 v[12:15], v[158:161], v[236:239], v[12:15]
	v_mfma_f32_16x16x32_bf16 v[8:11], v[188:191], v[236:239], v[8:11]
	v_mfma_f32_16x16x32_bf16 v[60:63], v[162:165], v[216:219], v[60:63]
	v_mfma_f32_16x16x32_bf16 v[56:59], v[192:195], v[216:219], v[56:59]
	v_mfma_f32_16x16x32_bf16 v[44:47], v[162:165], v[224:227], v[44:47]
	v_mfma_f32_16x16x32_bf16 v[40:43], v[192:195], v[224:227], v[40:43]
	v_mfma_f32_16x16x32_bf16 v[28:31], v[162:165], v[232:235], v[28:31]
	v_mfma_f32_16x16x32_bf16 v[24:27], v[192:195], v[232:235], v[24:27]
	v_mfma_f32_16x16x32_bf16 v[12:15], v[162:165], v[240:243], v[12:15]
	v_mfma_f32_16x16x32_bf16 v[8:11], v[192:195], v[240:243], v[8:11]
	v_mfma_f32_16x16x32_bf16 v[52:55], v[196:199], v[212:215], v[52:55]
	v_mfma_f32_16x16x32_bf16 v[48:51], v[204:207], v[212:215], v[48:51]
	v_mfma_f32_16x16x32_bf16 v[36:39], v[196:199], v[220:223], v[36:39]
	v_mfma_f32_16x16x32_bf16 v[32:35], v[204:207], v[220:223], v[32:35]
	v_mfma_f32_16x16x32_bf16 v[20:23], v[196:199], v[228:231], v[20:23]
	v_mfma_f32_16x16x32_bf16 v[16:19], v[204:207], v[228:231], v[16:19]
	v_mfma_f32_16x16x32_bf16 v[4:7], v[196:199], v[236:239], v[4:7]
	v_mfma_f32_16x16x32_bf16 v[0:3], v[204:207], v[236:239], v[0:3]
	v_mfma_f32_16x16x32_bf16 v[52:55], v[200:203], v[216:219], v[52:55]
	v_mfma_f32_16x16x32_bf16 v[48:51], v[208:211], v[216:219], v[48:51]
	v_mfma_f32_16x16x32_bf16 v[36:39], v[200:203], v[224:227], v[36:39]
	v_mfma_f32_16x16x32_bf16 v[32:35], v[208:211], v[224:227], v[32:35]
	v_mfma_f32_16x16x32_bf16 v[20:23], v[200:203], v[232:235], v[20:23]
	v_mfma_f32_16x16x32_bf16 v[16:19], v[208:211], v[232:235], v[16:19]
	v_mfma_f32_16x16x32_bf16 v[4:7], v[200:203], v[240:243], v[4:7]
	v_mfma_f32_16x16x32_bf16 v[0:3], v[208:211], v[240:243], v[0:3]
	s_barrier
	s_add_i32 s56, 0, 0x18000
	v_add_u32_e32 v140, s56, v154
	s_add_i32 s57, 0, 0x1c000
	ds_read_b128 v[158:161], v140
	ds_read_b128 v[162:165], v140 offset:1024
	ds_read_b128 v[188:191], v140 offset:2048
	ds_read_b128 v[192:195], v140 offset:3072
	v_add_u32_e32 v140, s57, v154
	ds_read_b128 v[196:199], v140
	ds_read_b128 v[200:203], v140 offset:1024
	ds_read_b128 v[204:207], v140 offset:2048
	ds_read_b128 v[208:211], v140 offset:3072
	s_add_u32 s28, s28, s6
	s_addc_u32 s29, s29, s7
	s_mov_b32 m0, s39
	v_lshl_add_u64 v[250:251], s[28:29], 0, v[132:133]
	ds_read_b128 v[212:215], v156 offset:32768
	ds_read_b128 v[216:219], v156 offset:33792
	ds_read_b128 v[220:223], v156 offset:34816
	ds_read_b128 v[224:227], v156 offset:35840
	ds_read_b128 v[228:231], v156 offset:36864
	ds_read_b128 v[232:235], v156 offset:37888
	ds_read_b128 v[236:239], v156 offset:38912
	ds_read_b128 v[240:243], v156 offset:39936
	global_load_lds_dwordx4 v[250:251], off
	v_lshl_add_u64 v[250:251], s[28:29], 0, v[130:131]
	s_mov_b32 m0, s40
	s_nop 0
	global_load_lds_dwordx4 v[250:251], off
	s_waitcnt vmcnt(8)
	s_waitcnt lgkmcnt(0)
	s_barrier
	s_waitcnt lgkmcnt(0)
	v_mfma_f32_16x16x32_bf16 v[124:127], v[158:161], v[212:215], v[124:127]
	v_mfma_f32_16x16x32_bf16 v[120:123], v[188:191], v[212:215], v[120:123]
	v_mfma_f32_16x16x32_bf16 v[108:111], v[158:161], v[220:223], v[108:111]
	v_mfma_f32_16x16x32_bf16 v[104:107], v[188:191], v[220:223], v[104:107]
	v_mfma_f32_16x16x32_bf16 v[92:95], v[158:161], v[228:231], v[92:95]
	v_mfma_f32_16x16x32_bf16 v[88:91], v[188:191], v[228:231], v[88:91]
	v_mfma_f32_16x16x32_bf16 v[76:79], v[158:161], v[236:239], v[76:79]
	v_mfma_f32_16x16x32_bf16 v[72:75], v[188:191], v[236:239], v[72:75]
	v_mfma_f32_16x16x32_bf16 v[124:127], v[162:165], v[216:219], v[124:127]
	v_mfma_f32_16x16x32_bf16 v[120:123], v[192:195], v[216:219], v[120:123]
	v_mfma_f32_16x16x32_bf16 v[108:111], v[162:165], v[224:227], v[108:111]
	v_mfma_f32_16x16x32_bf16 v[104:107], v[192:195], v[224:227], v[104:107]
	v_mfma_f32_16x16x32_bf16 v[92:95], v[162:165], v[232:235], v[92:95]
	v_mfma_f32_16x16x32_bf16 v[88:91], v[192:195], v[232:235], v[88:91]
	v_mfma_f32_16x16x32_bf16 v[76:79], v[162:165], v[240:243], v[76:79]
	v_mfma_f32_16x16x32_bf16 v[72:75], v[192:195], v[240:243], v[72:75]
	v_mfma_f32_16x16x32_bf16 v[116:119], v[196:199], v[212:215], v[116:119]
	v_mfma_f32_16x16x32_bf16 v[112:115], v[204:207], v[212:215], v[112:115]
	v_mfma_f32_16x16x32_bf16 v[100:103], v[196:199], v[220:223], v[100:103]
	v_mfma_f32_16x16x32_bf16 v[96:99], v[204:207], v[220:223], v[96:99]
	v_mfma_f32_16x16x32_bf16 v[84:87], v[196:199], v[228:231], v[84:87]
	v_mfma_f32_16x16x32_bf16 v[80:83], v[204:207], v[228:231], v[80:83]
	v_mfma_f32_16x16x32_bf16 v[68:71], v[196:199], v[236:239], v[68:71]
	v_mfma_f32_16x16x32_bf16 v[64:67], v[204:207], v[236:239], v[64:67]
	v_mfma_f32_16x16x32_bf16 v[116:119], v[200:203], v[216:219], v[116:119]
	v_mfma_f32_16x16x32_bf16 v[112:115], v[208:211], v[216:219], v[112:115]
	v_mfma_f32_16x16x32_bf16 v[100:103], v[200:203], v[224:227], v[100:103]
	v_mfma_f32_16x16x32_bf16 v[96:99], v[208:211], v[224:227], v[96:99]
	v_mfma_f32_16x16x32_bf16 v[84:87], v[200:203], v[232:235], v[84:87]
	v_mfma_f32_16x16x32_bf16 v[80:83], v[208:211], v[232:235], v[80:83]
	v_mfma_f32_16x16x32_bf16 v[68:71], v[200:203], v[240:243], v[68:71]
	v_mfma_f32_16x16x32_bf16 v[64:67], v[208:211], v[240:243], v[64:67]
	s_barrier
; #define PG8_STAGE(bufoff, gbase, voff) do { _Pragma("unroll") for (int _i = 0; _i < 2; ++_i) \
;         __builtin_amdgcn_global_load_lds((const unsigned*)((const char*)(gbase) + (voff)[_i]), (PG8_LAS unsigned*)(lds + (bufoff) + ldsw + _i * 8192), 16, 0, 0); } while (0)
; #define PG8_LDA(dst, b, h) do { _Pragma("unroll") for (int m = 0; m < 4; ++m) _Pragma("unroll") for (int k = 0; k < 2; ++k) dst[m][k] = *(const PG8_LAS bf16x8*)(lds + PG8_SA(b, h) + aoff + m * 2048 + k * 1024); } while (0)
; #define PG8_MMA(ai, bj, At, Bt) do { __builtin_amdgcn_s_setprio(1); _Pragma("unroll") for (int m = 0; m < 4; ++m) _Pragma("unroll") for (int n = 0; n < 2; ++n) _Pragma("unroll") for (int k = 0; k < 2; ++k) \
;         acc[ai][bj][m][n] = __builtin_amdgcn_mfma_f32_16x16x32_bf16(Bt[n][k], At[m][k], acc[ai][bj][m][n], 0, 0, 0); __builtin_amdgcn_s_setprio(0); } while (0)
; #define PG8_WAIT_V(n) asm volatile("s_waitcnt vmcnt(" #n ")" ::: "memory")
; #define PG8_WAIT_L(n) asm volatile("s_waitcnt lgkmcnt(" #n ")" ::: "memory")
; #define PG8_BAR __builtin_amdgcn_s_barrier()
; #define PG8_SCHED __builtin_amdgcn_sched_barrier(0)
; template <class Epi, class Sched>
; __device__ __forceinline__ void gemm_phase(int wid_s, PG8_LAS unsigned char* lds, const Gemm g, const Sched& S, const Epi& E) {
;     ...
;             PG8_LDA(At, 1, 1); PG8_STAGE(PG8_SB(1, 0), b3, voffB); PG8_STAGE(PG8_SB(1, 1), b3 + hstepB, voffB); PG8_STAGE(PG8_SA(1, 0), a3, voffA);
;             PG8_WAIT_V(8); PG8_WAIT_L(0); PG8_BAR; PG8_MMA(1, 0, At, B0); PG8_MMA(1, 1, At, B1); PG8_BAR; PG8_SCHED;
;         }
	s_add_i32 s28, s56, s34
	v_lshl_add_u64 v[138:139], v[138:139], 0, s[96:97]
	s_mov_b32 m0, s28
	ds_read_b128 v[212:215], v156 offset:49152
	ds_read_b128 v[216:219], v156 offset:50176
	ds_read_b128 v[220:223], v156 offset:51200
	ds_read_b128 v[224:227], v156 offset:52224
	ds_read_b128 v[228:231], v156 offset:53248
	ds_read_b128 v[232:235], v156 offset:54272
	ds_read_b128 v[236:239], v156 offset:55296
	ds_read_b128 v[240:243], v156 offset:56320
	global_load_lds_dwordx4 v[138:139], off
	v_lshl_add_u64 v[138:139], v[142:143], 0, s[96:97]
	s_add_i32 m0, s28, 0x2000
	s_add_i32 s28, s57, s34
	global_load_lds_dwordx4 v[138:139], off
	v_lshl_add_u64 v[138:139], v[166:167], 0, s[96:97]
	s_mov_b32 m0, s28
	s_nop 0
	global_load_lds_dwordx4 v[138:139], off
	v_lshl_add_u64 v[138:139], v[244:245], 0, s[96:97]
	s_add_i32 m0, s28, 0x2000
	s_nop 0
	global_load_lds_dwordx4 v[138:139], off
	v_lshl_add_u64 v[138:139], v[246:247], 0, s[96:97]
	s_mov_b32 m0, s41
	s_nop 0
	global_load_lds_dwordx4 v[138:139], off
	v_lshl_add_u64 v[138:139], v[248:249], 0, s[96:97]
	s_mov_b32 m0, s44
	s_nop 0
	global_load_lds_dwordx4 v[138:139], off
	s_waitcnt vmcnt(8)
	s_waitcnt lgkmcnt(0)
	s_barrier
	s_waitcnt lgkmcnt(0)
	v_mfma_f32_16x16x32_bf16 v[60:63], v[158:161], v[212:215], v[60:63]
	v_mfma_f32_16x16x32_bf16 v[56:59], v[188:191], v[212:215], v[56:59]
	v_mfma_f32_16x16x32_bf16 v[44:47], v[158:161], v[220:223], v[44:47]
	v_mfma_f32_16x16x32_bf16 v[40:43], v[188:191], v[220:223], v[40:43]
	v_mfma_f32_16x16x32_bf16 v[28:31], v[158:161], v[228:231], v[28:31]
	v_mfma_f32_16x16x32_bf16 v[24:27], v[188:191], v[228:231], v[24:27]
	v_mfma_f32_16x16x32_bf16 v[12:15], v[158:161], v[236:239], v[12:15]
	v_mfma_f32_16x16x32_bf16 v[8:11], v[188:191], v[236:239], v[8:11]
	v_mfma_f32_16x16x32_bf16 v[60:63], v[162:165], v[216:219], v[60:63]
	v_mfma_f32_16x16x32_bf16 v[56:59], v[192:195], v[216:219], v[56:59]
	v_mfma_f32_16x16x32_bf16 v[44:47], v[162:165], v[224:227], v[44:47]
	v_mfma_f32_16x16x32_bf16 v[40:43], v[192:195], v[224:227], v[40:43]
	v_mfma_f32_16x16x32_bf16 v[28:31], v[162:165], v[232:235], v[28:31]
	v_mfma_f32_16x16x32_bf16 v[24:27], v[192:195], v[232:235], v[24:27]
	v_mfma_f32_16x16x32_bf16 v[12:15], v[162:165], v[240:243], v[12:15]
	v_mfma_f32_16x16x32_bf16 v[8:11], v[192:195], v[240:243], v[8:11]
	v_mfma_f32_16x16x32_bf16 v[52:55], v[196:199], v[212:215], v[52:55]
	v_mfma_f32_16x16x32_bf16 v[48:51], v[204:207], v[212:215], v[48:51]
	v_mfma_f32_16x16x32_bf16 v[36:39], v[196:199], v[220:223], v[36:39]
	v_mfma_f32_16x16x32_bf16 v[32:35], v[204:207], v[220:223], v[32:35]
	v_mfma_f32_16x16x32_bf16 v[20:23], v[196:199], v[228:231], v[20:23]
	v_mfma_f32_16x16x32_bf16 v[16:19], v[204:207], v[228:231], v[16:19]
	v_mfma_f32_16x16x32_bf16 v[4:7], v[196:199], v[236:239], v[4:7]
	v_mfma_f32_16x16x32_bf16 v[0:3], v[204:207], v[236:239], v[0:3]
	v_mfma_f32_16x16x32_bf16 v[52:55], v[200:203], v[216:219], v[52:55]
	v_mfma_f32_16x16x32_bf16 v[48:51], v[208:211], v[216:219], v[48:51]
	v_mfma_f32_16x16x32_bf16 v[36:39], v[200:203], v[224:227], v[36:39]
	v_mfma_f32_16x16x32_bf16 v[32:35], v[208:211], v[224:227], v[32:35]
	v_mfma_f32_16x16x32_bf16 v[20:23], v[200:203], v[232:235], v[20:23]
	v_mfma_f32_16x16x32_bf16 v[16:19], v[208:211], v[232:235], v[16:19]
	v_mfma_f32_16x16x32_bf16 v[4:7], v[200:203], v[240:243], v[4:7]
	v_mfma_f32_16x16x32_bf16 v[0:3], v[208:211], v[240:243], v[0:3]
	s_barrier
	s_add_u32 s33, s33, 0x100
	s_addc_u32 s50, s50, 0
	s_add_u32 s26, s26, 0x100
	s_addc_u32 s27, s27, 0
	s_cmp_ge_i32 s51, s45
	s_mov_b32 s28, s51
	s_cbranch_scc0 .LBB0_2473
	v_readlane_b32 s92, v254, 54
	v_readlane_b32 s94, v254, 55
	s_movk_i32 s51, 0x200
	s_movk_i32 s33, 0x300
	s_mov_b32 s50, s95

; #define PG8_STAGE(bufoff, gbase, voff) do { _Pragma("unroll") for (int _i = 0; _i < 2; ++_i) \
;         __builtin_amdgcn_global_load_lds((const unsigned*)((const char*)(gbase) + (voff)[_i]), (PG8_LAS unsigned*)(lds + (bufoff) + ldsw + _i * 8192), 16, 0, 0); } while (0)
; #define PG8_LDA(dst, b, h) do { _Pragma("unroll") for (int m = 0; m < 4; ++m) _Pragma("unroll") for (int k = 0; k < 2; ++k) dst[m][k] = *(const PG8_LAS bf16x8*)(lds + PG8_SA(b, h) + aoff + m * 2048 + k * 1024); } while (0)
; #define PG8_LDB(dst, b, h) do { _Pragma("unroll") for (int n = 0; n < 2; ++n) _Pragma("unroll") for (int k = 0; k < 2; ++k) dst[n][k] = *(const PG8_LAS bf16x8*)(lds + PG8_SB(b, h) + boff + n * 2048 + k * 1024); } while (0)
; #define PG8_MMA(ai, bj, At, Bt) do { __builtin_amdgcn_s_setprio(1); _Pragma("unroll") for (int m = 0; m < 4; ++m) _Pragma("unroll") for (int n = 0; n < 2; ++n) _Pragma("unroll") for (int k = 0; k < 2; ++k) \
;         acc[ai][bj][m][n] = __builtin_amdgcn_mfma_f32_16x16x32_bf16(Bt[n][k], At[m][k], acc[ai][bj][m][n], 0, 0, 0); __builtin_amdgcn_s_setprio(0); } while (0)
; #define PG8_WAIT_V(n) asm volatile("s_waitcnt vmcnt(" #n ")" ::: "memory")
; #define PG8_WAIT_L(n) asm volatile("s_waitcnt lgkmcnt(" #n ")" ::: "memory")
; #define PG8_BAR __builtin_amdgcn_s_barrier()
; #define PG8_SCHED __builtin_amdgcn_sched_barrier(0)
; template <class Epi, class Sched>
; __device__ __forceinline__ void gemm_phase(int wid_s, PG8_LAS unsigned char* lds, const Gemm g, const Sched& S, const Epi& E) {
;     ...
;             const bool last = (t == nt - 2);
;             const char* a1 = cA + (size_t)(t + 1) * kstep;
;             const char* a2 = last ? nA : cA + (size_t)(t + 2) * kstep; const char* b2 = last ? nB : cB + (size_t)(t + 2) * kstep;
;             const char* a3 = a2 + kstep; const char* b3 = b2 + kstep;
;             PG8_LDB(B0, 0, 0); PG8_LDB(B1, 0, 1); PG8_SCHED; PG8_LDA(At, 0, 0); PG8_STAGE(PG8_SA(1, 1), a1 + hstepA, voffA);
;             PG8_WAIT_V(8); PG8_WAIT_L(0); PG8_BAR; PG8_MMA(0, 0, At, B0); PG8_MMA(0, 1, At, B1); PG8_BAR; PG8_SCHED;
;             PG8_LDA(At, 0, 1); PG8_STAGE(PG8_SB(0, 0), b2, voffB); PG8_STAGE(PG8_SB(0, 1), b2 + hstepB, voffB); PG8_STAGE(PG8_SA(0, 0), a2, voffA);
;             PG8_WAIT_V(8); PG8_WAIT_L(0); PG8_BAR; PG8_MMA(1, 0, At, B0); PG8_MMA(1, 1, At, B1); PG8_BAR; PG8_SCHED;
.LBB0_2965:
	s_add_i32 s46, s6, 2
	s_add_u32 s47, s4, 0x80
	s_addc_u32 s7, s5, 0
	s_add_i32 s53, 0, 0x10000
	s_cmp_eq_u32 s23, s6
	s_cselect_b32 s7, s31, s7
	s_cselect_b32 s6, s30, s47
	v_add_u32_e32 v142, s53, v159
	s_cselect_b32 s51, s35, s49
	s_cselect_b32 s50, s34, s33
	s_add_i32 s47, 0, 0x14000
	ds_read_b128 v[138:141], v142
	ds_read_b128 v[162:165], v142 offset:1024
	ds_read_b128 v[186:189], v142 offset:2048
	ds_read_b128 v[190:193], v142 offset:3072
	v_add_u32_e32 v142, s47, v159
	ds_read_b128 v[194:197], v142
	ds_read_b128 v[198:201], v142 offset:1024
	ds_read_b128 v[202:205], v142 offset:2048
	ds_read_b128 v[206:209], v142 offset:3072
	v_lshl_add_u64 v[142:143], s[4:5], 0, v[136:137]
	s_add_i32 m0, s92, 0xc000
	ds_read_b128 v[210:213], v161
	ds_read_b128 v[214:217], v161 offset:1024
	ds_read_b128 v[218:221], v161 offset:2048
	ds_read_b128 v[222:225], v161 offset:3072
	ds_read_b128 v[226:229], v161 offset:4096
	ds_read_b128 v[230:233], v161 offset:5120
	ds_read_b128 v[234:237], v161 offset:6144
	ds_read_b128 v[238:241], v161 offset:7168
	global_load_lds_dwordx4 v[142:143], off
	v_lshl_add_u64 v[142:143], s[4:5], 0, v[134:135]
	s_add_i32 m0, s92, 0xe000
	s_nop 0
	global_load_lds_dwordx4 v[142:143], off
	s_waitcnt vmcnt(8)
	s_waitcnt lgkmcnt(0)
	s_barrier
	s_waitcnt lgkmcnt(0)
	v_mfma_f32_16x16x32_bf16 v[124:127], v[138:141], v[210:213], v[124:127]
	v_mfma_f32_16x16x32_bf16 v[120:123], v[186:189], v[210:213], v[120:123]
	v_mfma_f32_16x16x32_bf16 v[108:111], v[138:141], v[218:221], v[108:111]
	v_mfma_f32_16x16x32_bf16 v[104:107], v[186:189], v[218:221], v[104:107]
	v_mfma_f32_16x16x32_bf16 v[92:95], v[138:141], v[226:229], v[92:95]
	v_mfma_f32_16x16x32_bf16 v[88:91], v[186:189], v[226:229], v[88:91]
	v_mfma_f32_16x16x32_bf16 v[76:79], v[138:141], v[234:237], v[76:79]
	v_mfma_f32_16x16x32_bf16 v[72:75], v[186:189], v[234:237], v[72:75]
	v_mfma_f32_16x16x32_bf16 v[124:127], v[162:165], v[214:217], v[124:127]
	v_mfma_f32_16x16x32_bf16 v[120:123], v[190:193], v[214:217], v[120:123]
	v_mfma_f32_16x16x32_bf16 v[108:111], v[162:165], v[222:225], v[108:111]
	v_mfma_f32_16x16x32_bf16 v[104:107], v[190:193], v[222:225], v[104:107]
	v_mfma_f32_16x16x32_bf16 v[92:95], v[162:165], v[230:233], v[92:95]
	v_mfma_f32_16x16x32_bf16 v[88:91], v[190:193], v[230:233], v[88:91]
	v_mfma_f32_16x16x32_bf16 v[76:79], v[162:165], v[238:241], v[76:79]
	v_mfma_f32_16x16x32_bf16 v[72:75], v[190:193], v[238:241], v[72:75]
	v_mfma_f32_16x16x32_bf16 v[116:119], v[194:197], v[210:213], v[116:119]
	v_mfma_f32_16x16x32_bf16 v[112:115], v[202:205], v[210:213], v[112:115]
	v_mfma_f32_16x16x32_bf16 v[100:103], v[194:197], v[218:221], v[100:103]
	v_mfma_f32_16x16x32_bf16 v[96:99], v[202:205], v[218:221], v[96:99]
	v_mfma_f32_16x16x32_bf16 v[84:87], v[194:197], v[226:229], v[84:87]
	v_mfma_f32_16x16x32_bf16 v[80:83], v[202:205], v[226:229], v[80:83]
	v_mfma_f32_16x16x32_bf16 v[68:71], v[194:197], v[234:237], v[68:71]
	v_mfma_f32_16x16x32_bf16 v[64:67], v[202:205], v[234:237], v[64:67]
	v_mfma_f32_16x16x32_bf16 v[116:119], v[198:201], v[214:217], v[116:119]
	v_mfma_f32_16x16x32_bf16 v[112:115], v[206:209], v[214:217], v[112:115]
	v_mfma_f32_16x16x32_bf16 v[100:103], v[198:201], v[222:225], v[100:103]
	v_mfma_f32_16x16x32_bf16 v[96:99], v[206:209], v[222:225], v[96:99]
	v_mfma_f32_16x16x32_bf16 v[84:87], v[198:201], v[230:233], v[84:87]
	v_mfma_f32_16x16x32_bf16 v[80:83], v[206:209], v[230:233], v[80:83]
	v_mfma_f32_16x16x32_bf16 v[68:71], v[198:201], v[238:241], v[68:71]
	v_mfma_f32_16x16x32_bf16 v[64:67], v[206:209], v[238:241], v[64:67]
	s_barrier
	s_add_i32 s53, s53, s55
	v_lshl_add_u64 v[142:143], s[50:51], 0, v[144:145]
	s_mov_b32 m0, s53
	ds_read_b128 v[210:213], v161 offset:16384
	ds_read_b128 v[214:217], v161 offset:17408
	ds_read_b128 v[218:221], v161 offset:18432
	ds_read_b128 v[222:225], v161 offset:19456
	ds_read_b128 v[226:229], v161 offset:20480
	ds_read_b128 v[230:233], v161 offset:21504
	ds_read_b128 v[234:237], v161 offset:22528
	ds_read_b128 v[238:241], v161 offset:23552
	global_load_lds_dwordx4 v[142:143], off
	s_add_i32 m0, s53, 0x2000
	v_lshl_add_u64 v[154:155], s[50:51], 0, v[132:133]
	s_add_u32 s50, s50, s14
	s_addc_u32 s51, s51, s15
	s_add_i32 s47, s47, s55
	global_load_lds_dwordx4 v[154:155], off
	v_lshl_add_u64 v[166:167], s[50:51], 0, v[144:145]
	s_mov_b32 m0, s47
	v_lshl_add_u64 v[242:243], s[50:51], 0, v[132:133]
	global_load_lds_dwordx4 v[166:167], off
	s_add_i32 m0, s47, 0x2000
	v_lshl_add_u64 v[244:245], s[6:7], 0, v[128:129]
	global_load_lds_dwordx4 v[242:243], off
	s_mov_b32 m0, s92
	v_lshl_add_u64 v[246:247], s[6:7], 0, v[130:131]
	global_load_lds_dwordx4 v[244:245], off
	s_mov_b32 m0, s94
	s_nop 0
	global_load_lds_dwordx4 v[246:247], off
	s_waitcnt vmcnt(8)
	s_waitcnt lgkmcnt(0)
	s_barrier
; #define PG8_STAGE(bufoff, gbase, voff) do { _Pragma("unroll") for (int _i = 0; _i < 2; ++_i) \
;         __builtin_amdgcn_global_load_lds((const unsigned*)((const char*)(gbase) + (voff)[_i]), (PG8_LAS unsigned*)(lds + (bufoff) + ldsw + _i * 8192), 16, 0, 0); } while (0)
; #define PG8_LDA(dst, b, h) do { _Pragma("unroll") for (int m = 0; m < 4; ++m) _Pragma("unroll") for (int k = 0; k < 2; ++k) dst[m][k] = *(const PG8_LAS bf16x8*)(lds + PG8_SA(b, h) + aoff + m * 2048 + k * 1024); } while (0)
; #define PG8_LDB(dst, b, h) do { _Pragma("unroll") for (int n = 0; n < 2; ++n) _Pragma("unroll") for (int k = 0; k < 2; ++k) dst[n][k] = *(const PG8_LAS bf16x8*)(lds + PG8_SB(b, h) + boff + n * 2048 + k * 1024); } while (0)
; #define PG8_MMA(ai, bj, At, Bt) do { __builtin_amdgcn_s_setprio(1); _Pragma("unroll") for (int m = 0; m < 4; ++m) _Pragma("unroll") for (int n = 0; n < 2; ++n) _Pragma("unroll") for (int k = 0; k < 2; ++k) \
;         acc[ai][bj][m][n] = __builtin_amdgcn_mfma_f32_16x16x32_bf16(Bt[n][k], At[m][k], acc[ai][bj][m][n], 0, 0, 0); __builtin_amdgcn_s_setprio(0); } while (0)
; #define PG8_WAIT_V(n) asm volatile("s_waitcnt vmcnt(" #n ")" ::: "memory")
; #define PG8_WAIT_L(n) asm volatile("s_waitcnt lgkmcnt(" #n ")" ::: "memory")
; #define PG8_BAR __builtin_amdgcn_s_barrier()
; #define PG8_SCHED __builtin_amdgcn_sched_barrier(0)
; template <class Epi, class Sched>
; __device__ __forceinline__ void gemm_phase(int wid_s, PG8_LAS unsigned char* lds, const Gemm g, const Sched& S, const Epi& E) {
;     ...
;             PG8_WAIT_V(8); PG8_WAIT_L(0); PG8_BAR; PG8_MMA(1, 0, At, B0); PG8_MMA(1, 1, At, B1); PG8_BAR; PG8_SCHED;
;             PG8_LDB(B0, 1, 0); PG8_LDB(B1, 1, 1); PG8_SCHED; PG8_LDA(At, 1, 0); PG8_STAGE(PG8_SA(0, 1), a2 + hstepA, voffA);
;             PG8_WAIT_V(8); PG8_WAIT_L(0); PG8_BAR; PG8_MMA(0, 0, At, B0); PG8_MMA(0, 1, At, B1); PG8_BAR; PG8_SCHED;
	s_waitcnt lgkmcnt(0)
	v_mfma_f32_16x16x32_bf16 v[60:63], v[138:141], v[210:213], v[60:63]
	v_mfma_f32_16x16x32_bf16 v[56:59], v[186:189], v[210:213], v[56:59]
	v_mfma_f32_16x16x32_bf16 v[44:47], v[138:141], v[218:221], v[44:47]
	v_mfma_f32_16x16x32_bf16 v[40:43], v[186:189], v[218:221], v[40:43]
	v_mfma_f32_16x16x32_bf16 v[28:31], v[138:141], v[226:229], v[28:31]
	v_mfma_f32_16x16x32_bf16 v[24:27], v[186:189], v[226:229], v[24:27]
	v_mfma_f32_16x16x32_bf16 v[12:15], v[138:141], v[234:237], v[12:15]
	v_mfma_f32_16x16x32_bf16 v[8:11], v[186:189], v[234:237], v[8:11]
	v_mfma_f32_16x16x32_bf16 v[60:63], v[162:165], v[214:217], v[60:63]
	v_mfma_f32_16x16x32_bf16 v[56:59], v[190:193], v[214:217], v[56:59]
	v_mfma_f32_16x16x32_bf16 v[44:47], v[162:165], v[222:225], v[44:47]
	v_mfma_f32_16x16x32_bf16 v[40:43], v[190:193], v[222:225], v[40:43]
	v_mfma_f32_16x16x32_bf16 v[28:31], v[162:165], v[230:233], v[28:31]
	v_mfma_f32_16x16x32_bf16 v[24:27], v[190:193], v[230:233], v[24:27]
	v_mfma_f32_16x16x32_bf16 v[12:15], v[162:165], v[238:241], v[12:15]
	v_mfma_f32_16x16x32_bf16 v[8:11], v[190:193], v[238:241], v[8:11]
	v_mfma_f32_16x16x32_bf16 v[52:55], v[194:197], v[210:213], v[52:55]
	v_mfma_f32_16x16x32_bf16 v[48:51], v[202:205], v[210:213], v[48:51]
	v_mfma_f32_16x16x32_bf16 v[36:39], v[194:197], v[218:221], v[36:39]
	v_mfma_f32_16x16x32_bf16 v[32:35], v[202:205], v[218:221], v[32:35]
	v_mfma_f32_16x16x32_bf16 v[20:23], v[194:197], v[226:229], v[20:23]
	v_mfma_f32_16x16x32_bf16 v[16:19], v[202:205], v[226:229], v[16:19]
	v_mfma_f32_16x16x32_bf16 v[4:7], v[194:197], v[234:237], v[4:7]
	v_mfma_f32_16x16x32_bf16 v[0:3], v[202:205], v[234:237], v[0:3]
	v_mfma_f32_16x16x32_bf16 v[52:55], v[198:201], v[214:217], v[52:55]
	v_mfma_f32_16x16x32_bf16 v[48:51], v[206:209], v[214:217], v[48:51]
	v_mfma_f32_16x16x32_bf16 v[36:39], v[198:201], v[222:225], v[36:39]
	v_mfma_f32_16x16x32_bf16 v[32:35], v[206:209], v[222:225], v[32:35]
	v_mfma_f32_16x16x32_bf16 v[20:23], v[198:201], v[230:233], v[20:23]
	v_mfma_f32_16x16x32_bf16 v[16:19], v[206:209], v[230:233], v[16:19]
	v_mfma_f32_16x16x32_bf16 v[4:7], v[198:201], v[238:241], v[4:7]
	v_mfma_f32_16x16x32_bf16 v[0:3], v[206:209], v[238:241], v[0:3]
	s_barrier
	s_add_i32 s47, 0, 0x18000
	v_add_u32_e32 v185, s47, v159
	s_add_i32 s50, 0, 0x1c000
	ds_read_b128 v[138:141], v185
	ds_read_b128 v[162:165], v185 offset:1024
	ds_read_b128 v[186:189], v185 offset:2048
	ds_read_b128 v[190:193], v185 offset:3072
	v_add_u32_e32 v185, s50, v159
	ds_read_b128 v[194:197], v185
	ds_read_b128 v[198:201], v185 offset:1024
	ds_read_b128 v[202:205], v185 offset:2048
	ds_read_b128 v[206:209], v185 offset:3072
	s_add_u32 s6, s6, s12
	s_addc_u32 s7, s7, s13
	s_mov_b32 m0, s95
	v_lshl_add_u64 v[248:249], s[6:7], 0, v[128:129]
	ds_read_b128 v[210:213], v161 offset:32768
	ds_read_b128 v[214:217], v161 offset:33792
	ds_read_b128 v[218:221], v161 offset:34816
	ds_read_b128 v[222:225], v161 offset:35840
	ds_read_b128 v[226:229], v161 offset:36864
	ds_read_b128 v[230:233], v161 offset:37888
	ds_read_b128 v[234:237], v161 offset:38912
	ds_read_b128 v[238:241], v161 offset:39936
	global_load_lds_dwordx4 v[248:249], off
	v_lshl_add_u64 v[248:249], s[6:7], 0, v[130:131]
	s_mov_b32 m0, s8
	s_nop 0
	global_load_lds_dwordx4 v[248:249], off
	s_waitcnt vmcnt(8)
	s_waitcnt lgkmcnt(0)
	s_barrier
	s_waitcnt lgkmcnt(0)
	v_mfma_f32_16x16x32_bf16 v[124:127], v[138:141], v[210:213], v[124:127]
	v_mfma_f32_16x16x32_bf16 v[120:123], v[186:189], v[210:213], v[120:123]
	v_mfma_f32_16x16x32_bf16 v[108:111], v[138:141], v[218:221], v[108:111]
	v_mfma_f32_16x16x32_bf16 v[104:107], v[186:189], v[218:221], v[104:107]
	v_mfma_f32_16x16x32_bf16 v[92:95], v[138:141], v[226:229], v[92:95]
	v_mfma_f32_16x16x32_bf16 v[88:91], v[186:189], v[226:229], v[88:91]
	v_mfma_f32_16x16x32_bf16 v[76:79], v[138:141], v[234:237], v[76:79]
	v_mfma_f32_16x16x32_bf16 v[72:75], v[186:189], v[234:237], v[72:75]
	v_mfma_f32_16x16x32_bf16 v[124:127], v[162:165], v[214:217], v[124:127]
	v_mfma_f32_16x16x32_bf16 v[120:123], v[190:193], v[214:217], v[120:123]
	v_mfma_f32_16x16x32_bf16 v[108:111], v[162:165], v[222:225], v[108:111]
	v_mfma_f32_16x16x32_bf16 v[104:107], v[190:193], v[222:225], v[104:107]
	v_mfma_f32_16x16x32_bf16 v[92:95], v[162:165], v[230:233], v[92:95]
	v_mfma_f32_16x16x32_bf16 v[88:91], v[190:193], v[230:233], v[88:91]
	v_mfma_f32_16x16x32_bf16 v[76:79], v[162:165], v[238:241], v[76:79]
	v_mfma_f32_16x16x32_bf16 v[72:75], v[190:193], v[238:241], v[72:75]
	v_mfma_f32_16x16x32_bf16 v[116:119], v[194:197], v[210:213], v[116:119]
	v_mfma_f32_16x16x32_bf16 v[112:115], v[202:205], v[210:213], v[112:115]
	v_mfma_f32_16x16x32_bf16 v[100:103], v[194:197], v[218:221], v[100:103]
	v_mfma_f32_16x16x32_bf16 v[96:99], v[202:205], v[218:221], v[96:99]
	v_mfma_f32_16x16x32_bf16 v[84:87], v[194:197], v[226:229], v[84:87]
	v_mfma_f32_16x16x32_bf16 v[80:83], v[202:205], v[226:229], v[80:83]
	v_mfma_f32_16x16x32_bf16 v[68:71], v[194:197], v[234:237], v[68:71]
	v_mfma_f32_16x16x32_bf16 v[64:67], v[202:205], v[234:237], v[64:67]
	v_mfma_f32_16x16x32_bf16 v[116:119], v[198:201], v[214:217], v[116:119]
	v_mfma_f32_16x16x32_bf16 v[112:115], v[206:209], v[214:217], v[112:115]
	v_mfma_f32_16x16x32_bf16 v[100:103], v[198:201], v[222:225], v[100:103]
	v_mfma_f32_16x16x32_bf16 v[96:99], v[206:209], v[222:225], v[96:99]
	v_mfma_f32_16x16x32_bf16 v[84:87], v[198:201], v[230:233], v[84:87]
	v_mfma_f32_16x16x32_bf16 v[80:83], v[206:209], v[230:233], v[80:83]
	v_mfma_f32_16x16x32_bf16 v[68:71], v[198:201], v[238:241], v[68:71]
	v_mfma_f32_16x16x32_bf16 v[64:67], v[206:209], v[238:241], v[64:67]
	s_barrier
; #define PG8_STAGE(bufoff, gbase, voff) do { _Pragma("unroll") for (int _i = 0; _i < 2; ++_i) \
;         __builtin_amdgcn_global_load_lds((const unsigned*)((const char*)(gbase) + (voff)[_i]), (PG8_LAS unsigned*)(lds + (bufoff) + ldsw + _i * 8192), 16, 0, 0); } while (0)
; #define PG8_LDA(dst, b, h) do { _Pragma("unroll") for (int m = 0; m < 4; ++m) _Pragma("unroll") for (int k = 0; k < 2; ++k) dst[m][k] = *(const PG8_LAS bf16x8*)(lds + PG8_SA(b, h) + aoff + m * 2048 + k * 1024); } while (0)
; #define PG8_MMA(ai, bj, At, Bt) do { __builtin_amdgcn_s_setprio(1); _Pragma("unroll") for (int m = 0; m < 4; ++m) _Pragma("unroll") for (int n = 0; n < 2; ++n) _Pragma("unroll") for (int k = 0; k < 2; ++k) \
;         acc[ai][bj][m][n] = __builtin_amdgcn_mfma_f32_16x16x32_bf16(Bt[n][k], At[m][k], acc[ai][bj][m][n], 0, 0, 0); __builtin_amdgcn_s_setprio(0); } while (0)
; #define PG8_WAIT_V(n) asm volatile("s_waitcnt vmcnt(" #n ")" ::: "memory")
; #define PG8_WAIT_L(n) asm volatile("s_waitcnt lgkmcnt(" #n ")" ::: "memory")
; #define PG8_BAR __builtin_amdgcn_s_barrier()
; #define PG8_SCHED __builtin_amdgcn_sched_barrier(0)
; template <class Epi, class Sched>
; __device__ __forceinline__ void gemm_phase(int wid_s, PG8_LAS unsigned char* lds, const Gemm g, const Sched& S, const Epi& E) {
;     ...
;             PG8_LDA(At, 1, 1); PG8_STAGE(PG8_SB(1, 0), b3, voffB); PG8_STAGE(PG8_SB(1, 1), b3 + hstepB, voffB); PG8_STAGE(PG8_SA(1, 0), a3, voffA);
;             PG8_WAIT_V(8); PG8_WAIT_L(0); PG8_BAR; PG8_MMA(1, 0, At, B0); PG8_MMA(1, 1, At, B1); PG8_BAR; PG8_SCHED;
;         }
	s_add_i32 s6, s47, s55
	v_lshl_add_u64 v[142:143], v[142:143], 0, s[96:97]
	s_mov_b32 m0, s6
	ds_read_b128 v[210:213], v161 offset:49152
	ds_read_b128 v[214:217], v161 offset:50176
	ds_read_b128 v[218:221], v161 offset:51200
	ds_read_b128 v[222:225], v161 offset:52224
	ds_read_b128 v[226:229], v161 offset:53248
	ds_read_b128 v[230:233], v161 offset:54272
	ds_read_b128 v[234:237], v161 offset:55296
	ds_read_b128 v[238:241], v161 offset:56320
	global_load_lds_dwordx4 v[142:143], off
	v_lshl_add_u64 v[142:143], v[154:155], 0, s[96:97]
	s_add_i32 m0, s6, 0x2000
	s_add_i32 s6, s50, s55
	global_load_lds_dwordx4 v[142:143], off
	v_lshl_add_u64 v[142:143], v[166:167], 0, s[96:97]
	s_mov_b32 m0, s6
	s_nop 0
	global_load_lds_dwordx4 v[142:143], off
	v_lshl_add_u64 v[142:143], v[242:243], 0, s[96:97]
	s_add_i32 m0, s6, 0x2000
	s_nop 0
	global_load_lds_dwordx4 v[142:143], off
	v_lshl_add_u64 v[142:143], v[244:245], 0, s[96:97]
	s_mov_b32 m0, s9
	s_nop 0
	global_load_lds_dwordx4 v[142:143], off
	v_lshl_add_u64 v[142:143], v[246:247], 0, s[96:97]
	s_mov_b32 m0, s0
	s_nop 0
	global_load_lds_dwordx4 v[142:143], off
	s_waitcnt vmcnt(8)
	s_waitcnt lgkmcnt(0)
	s_barrier
	s_waitcnt lgkmcnt(0)
	v_mfma_f32_16x16x32_bf16 v[60:63], v[138:141], v[210:213], v[60:63]
	v_mfma_f32_16x16x32_bf16 v[56:59], v[186:189], v[210:213], v[56:59]
	v_mfma_f32_16x16x32_bf16 v[44:47], v[138:141], v[218:221], v[44:47]
	v_mfma_f32_16x16x32_bf16 v[40:43], v[186:189], v[218:221], v[40:43]
	v_mfma_f32_16x16x32_bf16 v[28:31], v[138:141], v[226:229], v[28:31]
	v_mfma_f32_16x16x32_bf16 v[24:27], v[186:189], v[226:229], v[24:27]
	v_mfma_f32_16x16x32_bf16 v[12:15], v[138:141], v[234:237], v[12:15]
	v_mfma_f32_16x16x32_bf16 v[8:11], v[186:189], v[234:237], v[8:11]
	v_mfma_f32_16x16x32_bf16 v[60:63], v[162:165], v[214:217], v[60:63]
	v_mfma_f32_16x16x32_bf16 v[56:59], v[190:193], v[214:217], v[56:59]
	v_mfma_f32_16x16x32_bf16 v[44:47], v[162:165], v[222:225], v[44:47]
	v_mfma_f32_16x16x32_bf16 v[40:43], v[190:193], v[222:225], v[40:43]
	v_mfma_f32_16x16x32_bf16 v[28:31], v[162:165], v[230:233], v[28:31]
	v_mfma_f32_16x16x32_bf16 v[24:27], v[190:193], v[230:233], v[24:27]
	v_mfma_f32_16x16x32_bf16 v[12:15], v[162:165], v[238:241], v[12:15]
	v_mfma_f32_16x16x32_bf16 v[8:11], v[190:193], v[238:241], v[8:11]
	v_mfma_f32_16x16x32_bf16 v[52:55], v[194:197], v[210:213], v[52:55]
	v_mfma_f32_16x16x32_bf16 v[48:51], v[202:205], v[210:213], v[48:51]
	v_mfma_f32_16x16x32_bf16 v[36:39], v[194:197], v[218:221], v[36:39]
	v_mfma_f32_16x16x32_bf16 v[32:35], v[202:205], v[218:221], v[32:35]
	v_mfma_f32_16x16x32_bf16 v[20:23], v[194:197], v[226:229], v[20:23]
	v_mfma_f32_16x16x32_bf16 v[16:19], v[202:205], v[226:229], v[16:19]
	v_mfma_f32_16x16x32_bf16 v[4:7], v[194:197], v[234:237], v[4:7]
	v_mfma_f32_16x16x32_bf16 v[0:3], v[202:205], v[234:237], v[0:3]
	v_mfma_f32_16x16x32_bf16 v[52:55], v[198:201], v[214:217], v[52:55]
	v_mfma_f32_16x16x32_bf16 v[48:51], v[206:209], v[214:217], v[48:51]
	v_mfma_f32_16x16x32_bf16 v[36:39], v[198:201], v[222:225], v[36:39]
	v_mfma_f32_16x16x32_bf16 v[32:35], v[206:209], v[222:225], v[32:35]
	v_mfma_f32_16x16x32_bf16 v[20:23], v[198:201], v[230:233], v[20:23]
	v_mfma_f32_16x16x32_bf16 v[16:19], v[206:209], v[230:233], v[16:19]
	v_mfma_f32_16x16x32_bf16 v[4:7], v[198:201], v[238:241], v[4:7]
	v_mfma_f32_16x16x32_bf16 v[0:3], v[206:209], v[238:241], v[0:3]
	s_barrier
	s_add_u32 s33, s33, 0x100
	s_addc_u32 s49, s49, 0
	s_add_u32 s4, s4, 0x100
	s_addc_u32 s5, s5, 0
	s_cmp_ge_i32 s46, s22
	s_mov_b32 s6, s46
	s_cbranch_scc0 .LBB0_2965
	s_movk_i32 s51, 0x200
	s_movk_i32 s33, 0x300
